# MFMA issue order within each 8-MFMA group changed to boustrophedon (consecutive MFMAs share one operand fragment); on top of gate re-layout
# baseline (speedup 1.0000x reference)
; #define PG8_STAGEX(rs, bufoff, soff, voff) do { _Pragma("unroll") for (int _i = 0; _i < 2; ++_i) \
;         __builtin_amdgcn_raw_ptr_buffer_load_lds(rs, (LAS unsigned*)(lds + (bufoff) + ldsw + _i * 8192), 16, (voff)[_i], (soff), 0, 0); } while (0)
; #define PG8_LDA(dst, b, h) do { _Pragma("unroll") for (int m = 0; m < 4; ++m) _Pragma("unroll") for (int k = 0; k < 2; ++k) dst[m][k] = *(const LAS bf16x8*)(lds + PG8_SA(b, h) + aoff + m * 2048 + k * 1024); } while (0)
; #define PG8_LDB(dst, b, h) do { _Pragma("unroll") for (int n = 0; n < 2; ++n) _Pragma("unroll") for (int k = 0; k < 2; ++k) dst[n][k] = *(const LAS bf16x8*)(lds + PG8_SB(b, h) + boff + n * 2048 + k * 1024); } while (0)
; #define PG8_WAIT_V(n) asm volatile("s_waitcnt vmcnt(" #n ")" ::: "memory")
; #define PG8_WAIT_L(n) asm volatile("s_waitcnt lgkmcnt(" #n ")" ::: "memory")
; #define PG8_BAR __builtin_amdgcn_s_barrier()
; #define PG8_SCHED __builtin_amdgcn_sched_barrier(0)
;     ...
;             PG8_LDB(B0, 0, 0); PG8_LDB(B1, 0, 1); PG8_SCHED; PG8_LDA(At, 0, 0); PG8_STAGEX(rsA, PG8_SA(1, 1), a1 + hstepA, voffA);
;             PG8_WAIT_V(8); PG8_WAIT_L(0); PG8_BAR; PG8_MMA(0, 0, At, B0); PG8_MMA(0, 1, At, B1); PG8_BAR; PG8_SCHED;
;             PG8_LDA(At, 0, 1); PG8_STAGEX(rsB, PG8_SB(0, 0), b2, voffB); PG8_STAGEX(rsB, PG8_SB(0, 1), b2 + hstepB, voffB); PG8_STAGEX(rsA, PG8_SA(0, 0), a2, voffA);
;             PG8_WAIT_V(8); PG8_WAIT_L(0); PG8_BAR; PG8_MMA(1, 0, At, B0); PG8_MMA(1, 1, At, B1); PG8_BAR; PG8_SCHED;
;             PG8_LDB(B0, 1, 0); PG8_LDB(B1, 1, 1); PG8_SCHED; PG8_LDA(At, 1, 0); PG8_STAGEX(rsA, PG8_SA(0, 1), a2 + hstepA, voffA);
;             PG8_WAIT_V(8); PG8_WAIT_L(0); PG8_BAR; PG8_MMA(0, 0, At, B0); PG8_MMA(0, 1, At, B1); PG8_BAR; PG8_SCHED;
;             PG8_LDA(At, 1, 1); PG8_STAGEX(rsB, PG8_SB(1, 0), b3, voffB); PG8_STAGEX(rsB, PG8_SB(1, 1), b3 + hstepB, voffB); PG8_STAGEX(rsA, PG8_SA(1, 0), a3, voffA);
;             PG8_WAIT_V(8); PG8_WAIT_L(0); PG8_BAR; PG8_MMA(1, 0, At, B0); PG8_MMA(1, 1, At, B1); PG8_BAR; PG8_SCHED;
.LBB0_223:
	v_add_u32_e32 v102, 0x10000, v172
	v_add_u32_e32 v146, 0x14000, v172
	ds_read_b128 v[82:85], v102
	ds_read_b128 v[86:89], v102 offset:1024
	ds_read_b128 v[98:101], v102 offset:2048
	ds_read_b128 v[102:105], v102 offset:3072
	ds_read_b128 v[150:153], v146
	ds_read_b128 v[154:157], v146 offset:1024
	ds_read_b128 v[182:185], v146 offset:2048
	ds_read_b128 v[186:189], v146 offset:3072
	s_add_i32 s42, s50, 0xfff80080
	s_cmp_eq_u32 s52, 28
	s_cselect_b32 s55, s30, s42
	s_cselect_b32 s54, s31, s51
	s_or_b32 s53, s55, 0x80
	s_mov_b32 m0, s22
	ds_read_b128 v[190:193], v173
	ds_read_b128 v[194:197], v173 offset:1024
	ds_read_b128 v[198:201], v173 offset:2048
	ds_read_b128 v[202:205], v173 offset:3072
	ds_read_b128 v[206:209], v173 offset:4096
	ds_read_b128 v[210:213], v173 offset:5120
	ds_read_b128 v[214:217], v173 offset:6144
	ds_read_b128 v[218:221], v173 offset:7168
	buffer_load_dwordx4 v159, s[76:79], s50 offen lds
	s_mov_b32 m0, s23
	s_nop 0
	buffer_load_dwordx4 v163, s[76:79], s50 offen lds
	s_waitcnt vmcnt(8)
	s_waitcnt lgkmcnt(0)
	s_barrier
	s_setprio 1
	s_waitcnt lgkmcnt(7)
	s_waitcnt lgkmcnt(0)
	v_mfma_f32_16x16x32_bf16 v[142:145], v[82:85], v[190:193], v[142:145]
	v_mfma_f32_16x16x32_bf16 v[134:137], v[98:101], v[190:193], v[134:137]
	v_mfma_f32_16x16x32_bf16 v[118:121], v[98:101], v[198:201], v[118:121]
	v_mfma_f32_16x16x32_bf16 v[126:129], v[82:85], v[198:201], v[126:129]
	v_mfma_f32_16x16x32_bf16 v[110:113], v[82:85], v[206:209], v[110:113]
	v_mfma_f32_16x16x32_bf16 v[94:97], v[98:101], v[206:209], v[94:97]
	v_mfma_f32_16x16x32_bf16 v[70:73], v[98:101], v[214:217], v[70:73]
	v_mfma_f32_16x16x32_bf16 v[78:81], v[82:85], v[214:217], v[78:81]
	v_mfma_f32_16x16x32_bf16 v[142:145], v[86:89], v[194:197], v[142:145]
	v_mfma_f32_16x16x32_bf16 v[134:137], v[102:105], v[194:197], v[134:137]
	v_mfma_f32_16x16x32_bf16 v[118:121], v[102:105], v[202:205], v[118:121]
	v_mfma_f32_16x16x32_bf16 v[126:129], v[86:89], v[202:205], v[126:129]
	v_mfma_f32_16x16x32_bf16 v[110:113], v[86:89], v[210:213], v[110:113]
	v_mfma_f32_16x16x32_bf16 v[94:97], v[102:105], v[210:213], v[94:97]
	v_mfma_f32_16x16x32_bf16 v[70:73], v[102:105], v[218:221], v[70:73]
	v_mfma_f32_16x16x32_bf16 v[78:81], v[86:89], v[218:221], v[78:81]
	s_setprio 0
	s_setprio 1
	v_mfma_f32_16x16x32_bf16 v[138:141], v[150:153], v[190:193], v[138:141]
	v_mfma_f32_16x16x32_bf16 v[130:133], v[182:185], v[190:193], v[130:133]
	v_mfma_f32_16x16x32_bf16 v[114:117], v[182:185], v[198:201], v[114:117]
	v_mfma_f32_16x16x32_bf16 v[122:125], v[150:153], v[198:201], v[122:125]
	v_mfma_f32_16x16x32_bf16 v[106:109], v[150:153], v[206:209], v[106:109]
	v_mfma_f32_16x16x32_bf16 v[90:93], v[182:185], v[206:209], v[90:93]
	v_mfma_f32_16x16x32_bf16 v[66:69], v[182:185], v[214:217], v[66:69]
	v_mfma_f32_16x16x32_bf16 v[74:77], v[150:153], v[214:217], v[74:77]
	v_mfma_f32_16x16x32_bf16 v[138:141], v[154:157], v[194:197], v[138:141]
	v_mfma_f32_16x16x32_bf16 v[130:133], v[186:189], v[194:197], v[130:133]
	v_mfma_f32_16x16x32_bf16 v[114:117], v[186:189], v[202:205], v[114:117]
	v_mfma_f32_16x16x32_bf16 v[122:125], v[154:157], v[202:205], v[122:125]
	v_mfma_f32_16x16x32_bf16 v[106:109], v[154:157], v[210:213], v[106:109]
	v_mfma_f32_16x16x32_bf16 v[90:93], v[186:189], v[210:213], v[90:93]
	v_mfma_f32_16x16x32_bf16 v[66:69], v[186:189], v[218:221], v[66:69]
	v_mfma_f32_16x16x32_bf16 v[74:77], v[154:157], v[218:221], v[74:77]
	s_setprio 0
	s_barrier
	s_mov_b32 m0, s9
	s_mov_b32 s42, s78
	s_mov_b32 s43, s79
	ds_read_b128 v[190:193], v173 offset:16384
	ds_read_b128 v[194:197], v173 offset:17408
	ds_read_b128 v[198:201], v173 offset:18432
	ds_read_b128 v[202:205], v173 offset:19456
	ds_read_b128 v[206:209], v173 offset:20480
	ds_read_b128 v[210:213], v173 offset:21504
	ds_read_b128 v[214:217], v173 offset:22528
	ds_read_b128 v[218:221], v173 offset:23552
	buffer_load_dwordx4 v161, s[40:43], s54 offen lds
	s_mov_b32 m0, s10
	s_add_i32 s56, s54, 0x80000
	buffer_load_dwordx4 v165, s[40:43], s54 offen lds
	s_mov_b32 m0, s11
	s_nop 0
	buffer_load_dwordx4 v161, s[40:43], s56 offen lds
	s_mov_b32 m0, s12
	s_nop 0
	buffer_load_dwordx4 v165, s[40:43], s56 offen lds
	s_mov_b32 m0, s8
	s_nop 0
	buffer_load_dwordx4 v159, s[76:79], s55 offen lds
	s_mov_b32 m0, s13
	s_nop 0
	buffer_load_dwordx4 v163, s[76:79], s55 offen lds
	s_waitcnt vmcnt(8)
	s_waitcnt lgkmcnt(0)
	s_barrier
	s_setprio 1
	s_waitcnt lgkmcnt(7)
	s_waitcnt lgkmcnt(0)
	v_mfma_f32_16x16x32_bf16 v[62:65], v[82:85], v[190:193], v[62:65]
	v_mfma_f32_16x16x32_bf16 v[54:57], v[98:101], v[190:193], v[54:57]
	v_mfma_f32_16x16x32_bf16 v[38:41], v[98:101], v[198:201], v[38:41]
	v_mfma_f32_16x16x32_bf16 v[46:49], v[82:85], v[198:201], v[46:49]
	v_mfma_f32_16x16x32_bf16 v[30:33], v[82:85], v[206:209], v[30:33]
	v_mfma_f32_16x16x32_bf16 v[22:25], v[98:101], v[206:209], v[22:25]
	v_mfma_f32_16x16x32_bf16 v[6:9], v[98:101], v[214:217], v[6:9]
	v_mfma_f32_16x16x32_bf16 v[14:17], v[82:85], v[214:217], v[14:17]
	v_mfma_f32_16x16x32_bf16 v[62:65], v[86:89], v[194:197], v[62:65]
	v_mfma_f32_16x16x32_bf16 v[54:57], v[102:105], v[194:197], v[54:57]
	v_mfma_f32_16x16x32_bf16 v[38:41], v[102:105], v[202:205], v[38:41]
	v_mfma_f32_16x16x32_bf16 v[46:49], v[86:89], v[202:205], v[46:49]
	v_mfma_f32_16x16x32_bf16 v[30:33], v[86:89], v[210:213], v[30:33]
	v_mfma_f32_16x16x32_bf16 v[22:25], v[102:105], v[210:213], v[22:25]
	v_mfma_f32_16x16x32_bf16 v[6:9], v[102:105], v[218:221], v[6:9]
	v_mfma_f32_16x16x32_bf16 v[14:17], v[86:89], v[218:221], v[14:17]
	s_setprio 0
	s_setprio 1
	v_mfma_f32_16x16x32_bf16 v[58:61], v[150:153], v[190:193], v[58:61]
	v_mfma_f32_16x16x32_bf16 v[50:53], v[182:185], v[190:193], v[50:53]
	v_mfma_f32_16x16x32_bf16 v[34:37], v[182:185], v[198:201], v[34:37]
	v_mfma_f32_16x16x32_bf16 v[42:45], v[150:153], v[198:201], v[42:45]
	v_mfma_f32_16x16x32_bf16 v[26:29], v[150:153], v[206:209], v[26:29]
	v_mfma_f32_16x16x32_bf16 v[18:21], v[182:185], v[206:209], v[18:21]
	v_mfma_f32_16x16x32_bf16 v[2:5], v[182:185], v[214:217], v[2:5]
	v_mfma_f32_16x16x32_bf16 v[10:13], v[150:153], v[214:217], v[10:13]
	v_mfma_f32_16x16x32_bf16 v[58:61], v[154:157], v[194:197], v[58:61]
	v_mfma_f32_16x16x32_bf16 v[50:53], v[186:189], v[194:197], v[50:53]
	v_mfma_f32_16x16x32_bf16 v[34:37], v[186:189], v[202:205], v[34:37]
	v_mfma_f32_16x16x32_bf16 v[42:45], v[154:157], v[202:205], v[42:45]
	v_mfma_f32_16x16x32_bf16 v[26:29], v[154:157], v[210:213], v[26:29]
	v_mfma_f32_16x16x32_bf16 v[18:21], v[186:189], v[210:213], v[18:21]
	v_mfma_f32_16x16x32_bf16 v[2:5], v[186:189], v[218:221], v[2:5]
	v_mfma_f32_16x16x32_bf16 v[10:13], v[154:157], v[218:221], v[10:13]
	s_setprio 0
	s_barrier
; #define PG8_STAGEX(rs, bufoff, soff, voff) do { _Pragma("unroll") for (int _i = 0; _i < 2; ++_i) \
;         __builtin_amdgcn_raw_ptr_buffer_load_lds(rs, (LAS unsigned*)(lds + (bufoff) + ldsw + _i * 8192), 16, (voff)[_i], (soff), 0, 0); } while (0)
; #define PG8_LDA(dst, b, h) do { _Pragma("unroll") for (int m = 0; m < 4; ++m) _Pragma("unroll") for (int k = 0; k < 2; ++k) dst[m][k] = *(const LAS bf16x8*)(lds + PG8_SA(b, h) + aoff + m * 2048 + k * 1024); } while (0)
; #define PG8_LDB(dst, b, h) do { _Pragma("unroll") for (int n = 0; n < 2; ++n) _Pragma("unroll") for (int k = 0; k < 2; ++k) dst[n][k] = *(const LAS bf16x8*)(lds + PG8_SB(b, h) + boff + n * 2048 + k * 1024); } while (0)
; #define PG8_WAIT_V(n) asm volatile("s_waitcnt vmcnt(" #n ")" ::: "memory")
; #define PG8_WAIT_L(n) asm volatile("s_waitcnt lgkmcnt(" #n ")" ::: "memory")
; #define PG8_BAR __builtin_amdgcn_s_barrier()
; #define PG8_SCHED __builtin_amdgcn_sched_barrier(0)
;     ...
;             PG8_LDB(B0, 0, 0); PG8_LDB(B1, 0, 1); PG8_SCHED; PG8_LDA(At, 0, 0); PG8_STAGEX(rsA, PG8_SA(1, 1), a1 + hstepA, voffA);
;             PG8_WAIT_V(8); PG8_WAIT_L(0); PG8_BAR; PG8_MMA(0, 0, At, B0); PG8_MMA(0, 1, At, B1); PG8_BAR; PG8_SCHED;
;             PG8_LDA(At, 0, 1); PG8_STAGEX(rsB, PG8_SB(0, 0), b2, voffB); PG8_STAGEX(rsB, PG8_SB(0, 1), b2 + hstepB, voffB); PG8_STAGEX(rsA, PG8_SA(0, 0), a2, voffA);
;             PG8_WAIT_V(8); PG8_WAIT_L(0); PG8_BAR; PG8_MMA(1, 0, At, B0); PG8_MMA(1, 1, At, B1); PG8_BAR; PG8_SCHED;
;             PG8_LDB(B0, 1, 0); PG8_LDB(B1, 1, 1); PG8_SCHED; PG8_LDA(At, 1, 0); PG8_STAGEX(rsA, PG8_SA(0, 1), a2 + hstepA, voffA);
;             PG8_WAIT_V(8); PG8_WAIT_L(0); PG8_BAR; PG8_MMA(0, 0, At, B0); PG8_MMA(0, 1, At, B1); PG8_BAR; PG8_SCHED;
;             PG8_LDA(At, 1, 1); PG8_STAGEX(rsB, PG8_SB(1, 0), b3, voffB); PG8_STAGEX(rsB, PG8_SB(1, 1), b3 + hstepB, voffB); PG8_STAGEX(rsA, PG8_SA(1, 0), a3, voffA);
;             PG8_WAIT_V(8); PG8_WAIT_L(0); PG8_BAR; PG8_MMA(1, 0, At, B0); PG8_MMA(1, 1, At, B1); PG8_BAR; PG8_SCHED;
	v_add_u32_e32 v102, 0x18000, v172
	v_add_u32_e32 v146, 0x1c000, v172
	ds_read_b128 v[82:85], v102
	ds_read_b128 v[86:89], v102 offset:1024
	ds_read_b128 v[98:101], v102 offset:2048
	ds_read_b128 v[102:105], v102 offset:3072
	ds_read_b128 v[150:153], v146
	ds_read_b128 v[154:157], v146 offset:1024
	ds_read_b128 v[182:185], v146 offset:2048
	ds_read_b128 v[186:189], v146 offset:3072
	s_add_i32 s55, s55, 0x80000
	s_mov_b32 m0, s14
	ds_read_b128 v[190:193], v173 offset:32768
	ds_read_b128 v[194:197], v173 offset:33792
	ds_read_b128 v[198:201], v173 offset:34816
	ds_read_b128 v[202:205], v173 offset:35840
	ds_read_b128 v[206:209], v173 offset:36864
	ds_read_b128 v[210:213], v173 offset:37888
	ds_read_b128 v[214:217], v173 offset:38912
	ds_read_b128 v[218:221], v173 offset:39936
	buffer_load_dwordx4 v159, s[76:79], s55 offen lds
	s_mov_b32 m0, s15
	s_nop 0
	buffer_load_dwordx4 v163, s[76:79], s55 offen lds
	s_waitcnt vmcnt(8)
	s_waitcnt lgkmcnt(0)
	s_barrier
	s_setprio 1
	s_waitcnt lgkmcnt(7)
	s_waitcnt lgkmcnt(0)
	v_mfma_f32_16x16x32_bf16 v[142:145], v[82:85], v[190:193], v[142:145]
	v_mfma_f32_16x16x32_bf16 v[134:137], v[98:101], v[190:193], v[134:137]
	v_mfma_f32_16x16x32_bf16 v[118:121], v[98:101], v[198:201], v[118:121]
	v_mfma_f32_16x16x32_bf16 v[126:129], v[82:85], v[198:201], v[126:129]
	v_mfma_f32_16x16x32_bf16 v[110:113], v[82:85], v[206:209], v[110:113]
	v_mfma_f32_16x16x32_bf16 v[94:97], v[98:101], v[206:209], v[94:97]
	v_mfma_f32_16x16x32_bf16 v[70:73], v[98:101], v[214:217], v[70:73]
	v_mfma_f32_16x16x32_bf16 v[78:81], v[82:85], v[214:217], v[78:81]
	v_mfma_f32_16x16x32_bf16 v[142:145], v[86:89], v[194:197], v[142:145]
	v_mfma_f32_16x16x32_bf16 v[134:137], v[102:105], v[194:197], v[134:137]
	v_mfma_f32_16x16x32_bf16 v[118:121], v[102:105], v[202:205], v[118:121]
	v_mfma_f32_16x16x32_bf16 v[126:129], v[86:89], v[202:205], v[126:129]
	v_mfma_f32_16x16x32_bf16 v[110:113], v[86:89], v[210:213], v[110:113]
	v_mfma_f32_16x16x32_bf16 v[94:97], v[102:105], v[210:213], v[94:97]
	v_mfma_f32_16x16x32_bf16 v[70:73], v[102:105], v[218:221], v[70:73]
	v_mfma_f32_16x16x32_bf16 v[78:81], v[86:89], v[218:221], v[78:81]
	s_setprio 0
	s_setprio 1
	v_mfma_f32_16x16x32_bf16 v[138:141], v[150:153], v[190:193], v[138:141]
	v_mfma_f32_16x16x32_bf16 v[130:133], v[182:185], v[190:193], v[130:133]
	v_mfma_f32_16x16x32_bf16 v[114:117], v[182:185], v[198:201], v[114:117]
	v_mfma_f32_16x16x32_bf16 v[122:125], v[150:153], v[198:201], v[122:125]
	v_mfma_f32_16x16x32_bf16 v[106:109], v[150:153], v[206:209], v[106:109]
	v_mfma_f32_16x16x32_bf16 v[90:93], v[182:185], v[206:209], v[90:93]
	v_mfma_f32_16x16x32_bf16 v[66:69], v[182:185], v[214:217], v[66:69]
	v_mfma_f32_16x16x32_bf16 v[74:77], v[150:153], v[214:217], v[74:77]
	v_mfma_f32_16x16x32_bf16 v[138:141], v[154:157], v[194:197], v[138:141]
	v_mfma_f32_16x16x32_bf16 v[130:133], v[186:189], v[194:197], v[130:133]
	v_mfma_f32_16x16x32_bf16 v[114:117], v[186:189], v[202:205], v[114:117]
	v_mfma_f32_16x16x32_bf16 v[122:125], v[154:157], v[202:205], v[122:125]
	v_mfma_f32_16x16x32_bf16 v[106:109], v[154:157], v[210:213], v[106:109]
	v_mfma_f32_16x16x32_bf16 v[90:93], v[186:189], v[210:213], v[90:93]
	v_mfma_f32_16x16x32_bf16 v[66:69], v[186:189], v[218:221], v[66:69]
	v_mfma_f32_16x16x32_bf16 v[74:77], v[154:157], v[218:221], v[74:77]
	s_setprio 0
	s_barrier
	s_mov_b32 m0, s16
	s_or_b32 s55, s54, 0x80
	ds_read_b128 v[190:193], v173 offset:49152
	ds_read_b128 v[194:197], v173 offset:50176
	ds_read_b128 v[198:201], v173 offset:51200
	ds_read_b128 v[202:205], v173 offset:52224
	ds_read_b128 v[206:209], v173 offset:53248
	ds_read_b128 v[210:213], v173 offset:54272
	ds_read_b128 v[214:217], v173 offset:55296
	ds_read_b128 v[218:221], v173 offset:56320
	buffer_load_dwordx4 v161, s[40:43], s55 offen lds
	s_mov_b32 m0, s17
	s_add_i32 s54, s54, 0x80080
	buffer_load_dwordx4 v165, s[40:43], s55 offen lds
	s_mov_b32 m0, s20
	s_nop 0
	buffer_load_dwordx4 v161, s[40:43], s54 offen lds
	s_mov_b32 m0, s21
	s_nop 0
	buffer_load_dwordx4 v165, s[40:43], s54 offen lds
	s_mov_b32 m0, s18
	s_nop 0
	buffer_load_dwordx4 v159, s[76:79], s53 offen lds
	s_mov_b32 m0, s19
	s_nop 0
	buffer_load_dwordx4 v163, s[76:79], s53 offen lds
	s_waitcnt vmcnt(8)
	s_waitcnt lgkmcnt(0)
	s_barrier
	s_setprio 1
	s_waitcnt lgkmcnt(7)
	s_waitcnt lgkmcnt(0)
	v_mfma_f32_16x16x32_bf16 v[62:65], v[82:85], v[190:193], v[62:65]
	v_mfma_f32_16x16x32_bf16 v[54:57], v[98:101], v[190:193], v[54:57]
	v_mfma_f32_16x16x32_bf16 v[38:41], v[98:101], v[198:201], v[38:41]
	v_mfma_f32_16x16x32_bf16 v[46:49], v[82:85], v[198:201], v[46:49]
	v_mfma_f32_16x16x32_bf16 v[30:33], v[82:85], v[206:209], v[30:33]
	v_mfma_f32_16x16x32_bf16 v[22:25], v[98:101], v[206:209], v[22:25]
	v_mfma_f32_16x16x32_bf16 v[6:9], v[98:101], v[214:217], v[6:9]
	v_mfma_f32_16x16x32_bf16 v[14:17], v[82:85], v[214:217], v[14:17]
	v_mfma_f32_16x16x32_bf16 v[62:65], v[86:89], v[194:197], v[62:65]
	v_mfma_f32_16x16x32_bf16 v[54:57], v[102:105], v[194:197], v[54:57]
	v_mfma_f32_16x16x32_bf16 v[38:41], v[102:105], v[202:205], v[38:41]
	v_mfma_f32_16x16x32_bf16 v[46:49], v[86:89], v[202:205], v[46:49]
	v_mfma_f32_16x16x32_bf16 v[30:33], v[86:89], v[210:213], v[30:33]
	v_mfma_f32_16x16x32_bf16 v[22:25], v[102:105], v[210:213], v[22:25]
	v_mfma_f32_16x16x32_bf16 v[6:9], v[102:105], v[218:221], v[6:9]
	v_mfma_f32_16x16x32_bf16 v[14:17], v[86:89], v[218:221], v[14:17]
	s_setprio 0
	s_setprio 1
	v_mfma_f32_16x16x32_bf16 v[58:61], v[150:153], v[190:193], v[58:61]
	v_mfma_f32_16x16x32_bf16 v[50:53], v[182:185], v[190:193], v[50:53]
	v_mfma_f32_16x16x32_bf16 v[34:37], v[182:185], v[198:201], v[34:37]
	v_mfma_f32_16x16x32_bf16 v[42:45], v[150:153], v[198:201], v[42:45]
	v_mfma_f32_16x16x32_bf16 v[26:29], v[150:153], v[206:209], v[26:29]
	v_mfma_f32_16x16x32_bf16 v[18:21], v[182:185], v[206:209], v[18:21]
	v_mfma_f32_16x16x32_bf16 v[2:5], v[182:185], v[214:217], v[2:5]
	v_mfma_f32_16x16x32_bf16 v[10:13], v[150:153], v[214:217], v[10:13]
	v_mfma_f32_16x16x32_bf16 v[58:61], v[154:157], v[194:197], v[58:61]
	v_mfma_f32_16x16x32_bf16 v[50:53], v[186:189], v[194:197], v[50:53]
	v_mfma_f32_16x16x32_bf16 v[34:37], v[186:189], v[202:205], v[34:37]
	v_mfma_f32_16x16x32_bf16 v[42:45], v[154:157], v[202:205], v[42:45]
	v_mfma_f32_16x16x32_bf16 v[26:29], v[154:157], v[210:213], v[26:29]
	v_mfma_f32_16x16x32_bf16 v[18:21], v[186:189], v[210:213], v[18:21]
	v_mfma_f32_16x16x32_bf16 v[2:5], v[186:189], v[218:221], v[2:5]
	v_mfma_f32_16x16x32_bf16 v[10:13], v[154:157], v[218:221], v[10:13]
	s_setprio 0
	s_barrier
	s_add_i32 s52, s52, 2
	s_addk_i32 s50, 0x100
	s_addk_i32 s51, 0x100
	s_cmp_gt_u32 s52, 29
	s_cbranch_scc0 .LBB0_223
	s_and_b64 vcc, exec, s[46:47]
	s_cbranch_vccz .LBB0_226
	s_barrier

; #define PG8_STAGEX(rs, bufoff, soff, voff) do { _Pragma("unroll") for (int _i = 0; _i < 2; ++_i) \
;         __builtin_amdgcn_raw_ptr_buffer_load_lds(rs, (LAS unsigned*)(lds + (bufoff) + ldsw + _i * 8192), 16, (voff)[_i], (soff), 0, 0); } while (0)
; #define PG8_LDA(dst, b, h) do { _Pragma("unroll") for (int m = 0; m < 4; ++m) _Pragma("unroll") for (int k = 0; k < 2; ++k) dst[m][k] = *(const LAS bf16x8*)(lds + PG8_SA(b, h) + aoff + m * 2048 + k * 1024); } while (0)
; #define PG8_LDB(dst, b, h) do { _Pragma("unroll") for (int n = 0; n < 2; ++n) _Pragma("unroll") for (int k = 0; k < 2; ++k) dst[n][k] = *(const LAS bf16x8*)(lds + PG8_SB(b, h) + boff + n * 2048 + k * 1024); } while (0)
; #define PG8_WAIT_V(n) asm volatile("s_waitcnt vmcnt(" #n ")" ::: "memory")
; #define PG8_WAIT_L(n) asm volatile("s_waitcnt lgkmcnt(" #n ")" ::: "memory")
; #define PG8_BAR __builtin_amdgcn_s_barrier()
; #define PG8_SCHED __builtin_amdgcn_sched_barrier(0)
;     ...
;                 if (w0) { PG8_LDB(B0, 0, 0); PG8_LDB(B1, 0, 1); PG8_SCHED; PG8_LDA(At, 0, 0); }
;                 PG8_WAIT_L(0); PG8_BAR; if (w0) { PG8_MMA(0, 0, At, B0); PG8_MMA(0, 1, At, B1); } PG8_BAR; PG8_SCHED;
;                 PG8_STAGEX(rsB, PG8_SB(0, 0), b2, voffB); PG8_STAGEX(rsB, PG8_SB(0, 1), b2 + hstepB, voffB); PG8_STAGEX(rsA, PG8_SA(0, 0), a2, voffA);
;                 PG8_WAIT_V(6); PG8_BAR; PG8_BAR; PG8_SCHED;
;                 if (w0) { PG8_LDB(B0, 1, 0); PG8_LDB(B1, 1, 1); PG8_SCHED; PG8_LDA(At, 1, 0); }
;                 PG8_WAIT_L(0); PG8_BAR; if (w0) { PG8_MMA(0, 0, At, B0); PG8_MMA(0, 1, At, B1); } PG8_BAR; PG8_SCHED;
;                 PG8_STAGEX(rsB, PG8_SB(1, 0), b3, voffB); PG8_STAGEX(rsB, PG8_SB(1, 1), b3 + hstepB, voffB); PG8_STAGEX(rsA, PG8_SA(1, 0), a3, voffA);
;                 PG8_WAIT_V(6); PG8_BAR; PG8_BAR; PG8_SCHED;
.LBB0_240:
	v_add_u32_e32 v86, 0x10000, v72
	v_add_u32_e32 v102, 0x14000, v72
	ds_read_b128 v[74:77], v86
	ds_read_b128 v[78:81], v86 offset:1024
	ds_read_b128 v[82:85], v86 offset:2048
	ds_read_b128 v[86:89], v86 offset:3072
	ds_read_b128 v[90:93], v102
	ds_read_b128 v[94:97], v102 offset:1024
	ds_read_b128 v[98:101], v102 offset:2048
	ds_read_b128 v[102:105], v102 offset:3072
	s_cmp_lg_u32 s27, 28
	s_cselect_b32 s28, s26, 0
	s_add_i32 s29, s28, s17
	s_or_b32 s30, s29, 0x80
	s_add_i32 s28, s28, s11
	ds_read_b128 v[106:109], v73
	ds_read_b128 v[110:113], v73 offset:1024
	ds_read_b128 v[114:117], v73 offset:2048
	ds_read_b128 v[118:121], v73 offset:3072
	ds_read_b128 v[122:125], v73 offset:4096
	ds_read_b128 v[126:129], v73 offset:5120
	ds_read_b128 v[130:133], v73 offset:6144
	ds_read_b128 v[134:137], v73 offset:7168
	s_waitcnt lgkmcnt(0)
	s_barrier
	s_setprio 1
	s_waitcnt lgkmcnt(7)
	s_waitcnt lgkmcnt(0)
	v_mfma_f32_16x16x32_bf16 v[62:65], v[74:77], v[106:109], v[62:65]
	v_mfma_f32_16x16x32_bf16 v[58:61], v[82:85], v[106:109], v[58:61]
	v_mfma_f32_16x16x32_bf16 v[38:41], v[82:85], v[114:117], v[38:41]
	v_mfma_f32_16x16x32_bf16 v[54:57], v[74:77], v[114:117], v[54:57]
	v_mfma_f32_16x16x32_bf16 v[30:33], v[74:77], v[122:125], v[30:33]
	v_mfma_f32_16x16x32_bf16 v[22:25], v[82:85], v[122:125], v[22:25]
	v_mfma_f32_16x16x32_bf16 v[6:9], v[82:85], v[130:133], v[6:9]
	v_mfma_f32_16x16x32_bf16 v[14:17], v[74:77], v[130:133], v[14:17]
	v_mfma_f32_16x16x32_bf16 v[62:65], v[78:81], v[110:113], v[62:65]
	v_mfma_f32_16x16x32_bf16 v[58:61], v[86:89], v[110:113], v[58:61]
	v_mfma_f32_16x16x32_bf16 v[38:41], v[86:89], v[118:121], v[38:41]
	v_mfma_f32_16x16x32_bf16 v[54:57], v[78:81], v[118:121], v[54:57]
	v_mfma_f32_16x16x32_bf16 v[30:33], v[78:81], v[126:129], v[30:33]
	v_mfma_f32_16x16x32_bf16 v[22:25], v[86:89], v[126:129], v[22:25]
	v_mfma_f32_16x16x32_bf16 v[6:9], v[86:89], v[134:137], v[6:9]
	v_mfma_f32_16x16x32_bf16 v[14:17], v[78:81], v[134:137], v[14:17]
	s_setprio 0
	s_setprio 1
	v_mfma_f32_16x16x32_bf16 v[50:53], v[90:93], v[106:109], v[50:53]
	v_mfma_f32_16x16x32_bf16 v[46:49], v[98:101], v[106:109], v[46:49]
	v_mfma_f32_16x16x32_bf16 v[34:37], v[98:101], v[114:117], v[34:37]
	v_mfma_f32_16x16x32_bf16 v[42:45], v[90:93], v[114:117], v[42:45]
	v_mfma_f32_16x16x32_bf16 v[26:29], v[90:93], v[122:125], v[26:29]
	v_mfma_f32_16x16x32_bf16 v[18:21], v[98:101], v[122:125], v[18:21]
	v_mfma_f32_16x16x32_bf16 v[2:5], v[98:101], v[130:133], v[2:5]
	v_mfma_f32_16x16x32_bf16 v[10:13], v[90:93], v[130:133], v[10:13]
	v_mfma_f32_16x16x32_bf16 v[50:53], v[94:97], v[110:113], v[50:53]
	v_mfma_f32_16x16x32_bf16 v[46:49], v[102:105], v[110:113], v[46:49]
	v_mfma_f32_16x16x32_bf16 v[34:37], v[102:105], v[118:121], v[34:37]
	v_mfma_f32_16x16x32_bf16 v[42:45], v[94:97], v[118:121], v[42:45]
	v_mfma_f32_16x16x32_bf16 v[26:29], v[94:97], v[126:129], v[26:29]
	v_mfma_f32_16x16x32_bf16 v[18:21], v[102:105], v[126:129], v[18:21]
	v_mfma_f32_16x16x32_bf16 v[2:5], v[102:105], v[134:137], v[2:5]
	v_mfma_f32_16x16x32_bf16 v[10:13], v[94:97], v[134:137], v[10:13]
	s_setprio 0
	s_barrier
	s_mov_b32 m0, s13
	s_mov_b32 s42, s78
	s_mov_b32 s43, s79
	buffer_load_dwordx4 v67, s[40:43], s28 offen lds
	s_mov_b32 m0, s14
	s_add_i32 s31, s28, 0x80000
	buffer_load_dwordx4 v69, s[40:43], s28 offen lds
	s_mov_b32 m0, s15
	s_nop 0
	buffer_load_dwordx4 v67, s[40:43], s31 offen lds
	s_mov_b32 m0, s16
	s_nop 0
	buffer_load_dwordx4 v69, s[40:43], s31 offen lds
	s_mov_b32 m0, s12
	s_nop 0
	buffer_load_dwordx4 v66, s[76:79], s29 offen lds
	s_mov_b32 m0, s18
	s_nop 0
	buffer_load_dwordx4 v68, s[76:79], s29 offen lds
	s_waitcnt vmcnt(6)
	s_barrier
	s_barrier
; #define PG8_STAGEX(rs, bufoff, soff, voff) do { _Pragma("unroll") for (int _i = 0; _i < 2; ++_i) \
;         __builtin_amdgcn_raw_ptr_buffer_load_lds(rs, (LAS unsigned*)(lds + (bufoff) + ldsw + _i * 8192), 16, (voff)[_i], (soff), 0, 0); } while (0)
; #define PG8_LDA(dst, b, h) do { _Pragma("unroll") for (int m = 0; m < 4; ++m) _Pragma("unroll") for (int k = 0; k < 2; ++k) dst[m][k] = *(const LAS bf16x8*)(lds + PG8_SA(b, h) + aoff + m * 2048 + k * 1024); } while (0)
; #define PG8_LDB(dst, b, h) do { _Pragma("unroll") for (int n = 0; n < 2; ++n) _Pragma("unroll") for (int k = 0; k < 2; ++k) dst[n][k] = *(const LAS bf16x8*)(lds + PG8_SB(b, h) + boff + n * 2048 + k * 1024); } while (0)
; #define PG8_WAIT_V(n) asm volatile("s_waitcnt vmcnt(" #n ")" ::: "memory")
; #define PG8_WAIT_L(n) asm volatile("s_waitcnt lgkmcnt(" #n ")" ::: "memory")
; #define PG8_BAR __builtin_amdgcn_s_barrier()
; #define PG8_SCHED __builtin_amdgcn_sched_barrier(0)
;     ...
;                 if (w0) { PG8_LDB(B0, 0, 0); PG8_LDB(B1, 0, 1); PG8_SCHED; PG8_LDA(At, 0, 0); }
;                 PG8_WAIT_L(0); PG8_BAR; if (w0) { PG8_MMA(0, 0, At, B0); PG8_MMA(0, 1, At, B1); } PG8_BAR; PG8_SCHED;
;                 PG8_STAGEX(rsB, PG8_SB(0, 0), b2, voffB); PG8_STAGEX(rsB, PG8_SB(0, 1), b2 + hstepB, voffB); PG8_STAGEX(rsA, PG8_SA(0, 0), a2, voffA);
;                 PG8_WAIT_V(6); PG8_BAR; PG8_BAR; PG8_SCHED;
;                 if (w0) { PG8_LDB(B0, 1, 0); PG8_LDB(B1, 1, 1); PG8_SCHED; PG8_LDA(At, 1, 0); }
;                 PG8_WAIT_L(0); PG8_BAR; if (w0) { PG8_MMA(0, 0, At, B0); PG8_MMA(0, 1, At, B1); } PG8_BAR; PG8_SCHED;
;                 PG8_STAGEX(rsB, PG8_SB(1, 0), b3, voffB); PG8_STAGEX(rsB, PG8_SB(1, 1), b3 + hstepB, voffB); PG8_STAGEX(rsA, PG8_SA(1, 0), a3, voffA);
;                 PG8_WAIT_V(6); PG8_BAR; PG8_BAR; PG8_SCHED;
	v_add_u32_e32 v86, 0x18000, v72
	v_add_u32_e32 v102, 0x1c000, v72
	ds_read_b128 v[74:77], v86
	ds_read_b128 v[78:81], v86 offset:1024
	ds_read_b128 v[82:85], v86 offset:2048
	ds_read_b128 v[86:89], v86 offset:3072
	ds_read_b128 v[90:93], v102
	ds_read_b128 v[94:97], v102 offset:1024
	ds_read_b128 v[98:101], v102 offset:2048
	ds_read_b128 v[102:105], v102 offset:3072
	ds_read_b128 v[106:109], v73 offset:32768
	ds_read_b128 v[110:113], v73 offset:33792
	ds_read_b128 v[114:117], v73 offset:34816
	ds_read_b128 v[118:121], v73 offset:35840
	ds_read_b128 v[122:125], v73 offset:36864
	ds_read_b128 v[126:129], v73 offset:37888
	ds_read_b128 v[130:133], v73 offset:38912
	ds_read_b128 v[134:137], v73 offset:39936
	s_waitcnt lgkmcnt(0)
	s_barrier
	s_setprio 1
	s_waitcnt lgkmcnt(7)
	s_waitcnt lgkmcnt(0)
	v_mfma_f32_16x16x32_bf16 v[62:65], v[74:77], v[106:109], v[62:65]
	v_mfma_f32_16x16x32_bf16 v[58:61], v[82:85], v[106:109], v[58:61]
	v_mfma_f32_16x16x32_bf16 v[38:41], v[82:85], v[114:117], v[38:41]
	v_mfma_f32_16x16x32_bf16 v[54:57], v[74:77], v[114:117], v[54:57]
	v_mfma_f32_16x16x32_bf16 v[30:33], v[74:77], v[122:125], v[30:33]
	v_mfma_f32_16x16x32_bf16 v[22:25], v[82:85], v[122:125], v[22:25]
	v_mfma_f32_16x16x32_bf16 v[6:9], v[82:85], v[130:133], v[6:9]
	v_mfma_f32_16x16x32_bf16 v[14:17], v[74:77], v[130:133], v[14:17]
	v_mfma_f32_16x16x32_bf16 v[62:65], v[78:81], v[110:113], v[62:65]
	v_mfma_f32_16x16x32_bf16 v[58:61], v[86:89], v[110:113], v[58:61]
	v_mfma_f32_16x16x32_bf16 v[38:41], v[86:89], v[118:121], v[38:41]
	v_mfma_f32_16x16x32_bf16 v[54:57], v[78:81], v[118:121], v[54:57]
	v_mfma_f32_16x16x32_bf16 v[30:33], v[78:81], v[126:129], v[30:33]
	v_mfma_f32_16x16x32_bf16 v[22:25], v[86:89], v[126:129], v[22:25]
	v_mfma_f32_16x16x32_bf16 v[6:9], v[86:89], v[134:137], v[6:9]
	v_mfma_f32_16x16x32_bf16 v[14:17], v[78:81], v[134:137], v[14:17]
	s_setprio 0
	s_setprio 1
	v_mfma_f32_16x16x32_bf16 v[50:53], v[90:93], v[106:109], v[50:53]
	s_or_b32 s29, s28, 0x80
	v_mfma_f32_16x16x32_bf16 v[46:49], v[98:101], v[106:109], v[46:49]
	v_mfma_f32_16x16x32_bf16 v[42:45], v[90:93], v[114:117], v[42:45]
	v_mfma_f32_16x16x32_bf16 v[34:37], v[98:101], v[114:117], v[34:37]
	v_mfma_f32_16x16x32_bf16 v[26:29], v[90:93], v[122:125], v[26:29]
	v_mfma_f32_16x16x32_bf16 v[18:21], v[98:101], v[122:125], v[18:21]
	v_mfma_f32_16x16x32_bf16 v[10:13], v[90:93], v[130:133], v[10:13]
	v_mfma_f32_16x16x32_bf16 v[2:5], v[98:101], v[130:133], v[2:5]
	v_mfma_f32_16x16x32_bf16 v[50:53], v[94:97], v[110:113], v[50:53]
	v_mfma_f32_16x16x32_bf16 v[46:49], v[102:105], v[110:113], v[46:49]
	v_mfma_f32_16x16x32_bf16 v[42:45], v[94:97], v[118:121], v[42:45]
	v_mfma_f32_16x16x32_bf16 v[34:37], v[102:105], v[118:121], v[34:37]
	v_mfma_f32_16x16x32_bf16 v[26:29], v[94:97], v[126:129], v[26:29]
	v_mfma_f32_16x16x32_bf16 v[18:21], v[102:105], v[126:129], v[18:21]
	v_mfma_f32_16x16x32_bf16 v[10:13], v[94:97], v[134:137], v[10:13]
	v_mfma_f32_16x16x32_bf16 v[2:5], v[102:105], v[134:137], v[2:5]
	s_setprio 0
	s_barrier
	s_mov_b32 m0, s20
	s_add_i32 s28, s28, 0x80080
	buffer_load_dwordx4 v67, s[40:43], s29 offen lds
	s_mov_b32 m0, s21
	s_nop 0
	buffer_load_dwordx4 v69, s[40:43], s29 offen lds
	s_mov_b32 m0, s24
	s_nop 0
	buffer_load_dwordx4 v67, s[40:43], s28 offen lds
	s_mov_b32 m0, s25
	s_nop 0
	buffer_load_dwordx4 v69, s[40:43], s28 offen lds
	s_mov_b32 m0, s22
	s_nop 0
	buffer_load_dwordx4 v66, s[76:79], s30 offen lds
	s_mov_b32 m0, s23
	s_nop 0
	buffer_load_dwordx4 v68, s[76:79], s30 offen lds
	s_waitcnt vmcnt(6)
	s_barrier
	s_barrier
	s_addk_i32 s26, 0x100
	s_add_i32 s27, s27, 2
	s_cmp_gt_u32 s27, 29
	s_cbranch_scc0 .LBB0_240
	s_cmpk_lt_u32 s8, 0x100
	s_cbranch_scc0 .LBB0_243
	s_barrier

; #define PG8_STAGEX(rs, bufoff, soff, voff) do { _Pragma("unroll") for (int _i = 0; _i < 2; ++_i) \
;         __builtin_amdgcn_raw_ptr_buffer_load_lds(rs, (LAS unsigned*)(lds + (bufoff) + ldsw + _i * 8192), 16, (voff)[_i], (soff), 0, 0); } while (0)
; #define PG8_LDA(dst, b, h) do { _Pragma("unroll") for (int m = 0; m < 4; ++m) _Pragma("unroll") for (int k = 0; k < 2; ++k) dst[m][k] = *(const LAS bf16x8*)(lds + PG8_SA(b, h) + aoff + m * 2048 + k * 1024); } while (0)
; #define PG8_LDB(dst, b, h) do { _Pragma("unroll") for (int n = 0; n < 2; ++n) _Pragma("unroll") for (int k = 0; k < 2; ++k) dst[n][k] = *(const LAS bf16x8*)(lds + PG8_SB(b, h) + boff + n * 2048 + k * 1024); } while (0)
; #define PG8_WAIT_V(n) asm volatile("s_waitcnt vmcnt(" #n ")" ::: "memory")
; #define PG8_WAIT_L(n) asm volatile("s_waitcnt lgkmcnt(" #n ")" ::: "memory")
; #define PG8_BAR __builtin_amdgcn_s_barrier()
; #define PG8_SCHED __builtin_amdgcn_sched_barrier(0)
;     ...
;             PG8_LDB(B0, 0, 0); PG8_LDB(B1, 0, 1); PG8_SCHED; PG8_LDA(At, 0, 0); PG8_STAGEX(rsA, PG8_SA(1, 1), a1 + hstepA, voffA);
;             PG8_WAIT_V(8); PG8_WAIT_L(0); PG8_BAR; PG8_MMA(0, 0, At, B0); PG8_MMA(0, 1, At, B1); PG8_BAR; PG8_SCHED;
;             PG8_LDA(At, 0, 1); PG8_STAGEX(rsB, PG8_SB(0, 0), b2, voffB); PG8_STAGEX(rsB, PG8_SB(0, 1), b2 + hstepB, voffB); PG8_STAGEX(rsA, PG8_SA(0, 0), a2, voffA);
;             PG8_WAIT_V(8); PG8_WAIT_L(0); PG8_BAR; PG8_MMA(1, 0, At, B0); PG8_MMA(1, 1, At, B1); PG8_BAR; PG8_SCHED;
;             PG8_LDB(B0, 1, 0); PG8_LDB(B1, 1, 1); PG8_SCHED; PG8_LDA(At, 1, 0); PG8_STAGEX(rsA, PG8_SA(0, 1), a2 + hstepA, voffA);
;             PG8_WAIT_V(8); PG8_WAIT_L(0); PG8_BAR; PG8_MMA(0, 0, At, B0); PG8_MMA(0, 1, At, B1); PG8_BAR; PG8_SCHED;
;             PG8_LDA(At, 1, 1); PG8_STAGEX(rsB, PG8_SB(1, 0), b3, voffB); PG8_STAGEX(rsB, PG8_SB(1, 1), b3 + hstepB, voffB); PG8_STAGEX(rsA, PG8_SA(1, 0), a3, voffA);
;             PG8_WAIT_V(8); PG8_WAIT_L(0); PG8_BAR; PG8_MMA(1, 0, At, B0); PG8_MMA(1, 1, At, B1); PG8_BAR; PG8_SCHED;
.LBB0_323:
	v_add_u32_e32 v118, 0x10000, v210
	v_add_u32_e32 v160, 0x14000, v210
	ds_read_b128 v[106:109], v118
	ds_read_b128 v[110:113], v118 offset:1024
	ds_read_b128 v[114:117], v118 offset:2048
	ds_read_b128 v[118:121], v118 offset:3072
	ds_read_b128 v[122:125], v160
	ds_read_b128 v[134:137], v160 offset:1024
	ds_read_b128 v[156:159], v160 offset:2048
	ds_read_b128 v[160:163], v160 offset:3072
	s_add_i32 s42, s51, 0xffea8080
	s_cmpk_eq_i32 s58, 0x52
	s_cselect_b32 s61, s30, s42
	s_cselect_b32 s60, s31, s57
	s_or_b32 s59, s61, 0x80
	s_mov_b32 m0, s68
	ds_read_b128 v[164:167], v211
	ds_read_b128 v[168:171], v211 offset:1024
	ds_read_b128 v[182:185], v211 offset:2048
	ds_read_b128 v[186:189], v211 offset:3072
	ds_read_b128 v[190:193], v211 offset:4096
	ds_read_b128 v[194:197], v211 offset:5120
	ds_read_b128 v[198:201], v211 offset:6144
	ds_read_b128 v[202:205], v211 offset:7168
	buffer_load_dwordx4 v178, s[76:79], s51 offen lds
	s_mov_b32 m0, s69
	s_nop 0
	buffer_load_dwordx4 v206, s[76:79], s51 offen lds
	s_waitcnt vmcnt(8)
	s_waitcnt lgkmcnt(0)
	s_barrier
	s_setprio 1
	s_waitcnt lgkmcnt(7)
	s_waitcnt lgkmcnt(0)
	v_mfma_f32_16x16x32_bf16 v[150:153], v[106:109], v[164:167], v[150:153]
	v_mfma_f32_16x16x32_bf16 v[146:149], v[114:117], v[164:167], v[146:149]
	v_mfma_f32_16x16x32_bf16 v[138:141], v[114:117], v[182:185], v[138:141]
	v_mfma_f32_16x16x32_bf16 v[142:145], v[106:109], v[182:185], v[142:145]
	v_mfma_f32_16x16x32_bf16 v[130:133], v[106:109], v[190:193], v[130:133]
	v_mfma_f32_16x16x32_bf16 v[126:129], v[114:117], v[190:193], v[126:129]
	v_mfma_f32_16x16x32_bf16 v[98:101], v[114:117], v[198:201], v[98:101]
	v_mfma_f32_16x16x32_bf16 v[102:105], v[106:109], v[198:201], v[102:105]
	v_mfma_f32_16x16x32_bf16 v[150:153], v[110:113], v[168:171], v[150:153]
	v_mfma_f32_16x16x32_bf16 v[146:149], v[118:121], v[168:171], v[146:149]
	v_mfma_f32_16x16x32_bf16 v[138:141], v[118:121], v[186:189], v[138:141]
	v_mfma_f32_16x16x32_bf16 v[142:145], v[110:113], v[186:189], v[142:145]
	v_mfma_f32_16x16x32_bf16 v[130:133], v[110:113], v[194:197], v[130:133]
	v_mfma_f32_16x16x32_bf16 v[126:129], v[118:121], v[194:197], v[126:129]
	v_mfma_f32_16x16x32_bf16 v[98:101], v[118:121], v[202:205], v[98:101]
	v_mfma_f32_16x16x32_bf16 v[102:105], v[110:113], v[202:205], v[102:105]
	s_setprio 0
	s_setprio 1
	v_mfma_f32_16x16x32_bf16 v[62:65], v[122:125], v[164:167], v[62:65]
	v_mfma_f32_16x16x32_bf16 v[58:61], v[156:159], v[164:167], v[58:61]
	v_mfma_f32_16x16x32_bf16 v[50:53], v[156:159], v[182:185], v[50:53]
	v_mfma_f32_16x16x32_bf16 v[54:57], v[122:125], v[182:185], v[54:57]
	v_mfma_f32_16x16x32_bf16 v[46:49], v[122:125], v[190:193], v[46:49]
	v_mfma_f32_16x16x32_bf16 v[42:45], v[156:159], v[190:193], v[42:45]
	v_mfma_f32_16x16x32_bf16 v[34:37], v[156:159], v[198:201], v[34:37]
	v_mfma_f32_16x16x32_bf16 v[38:41], v[122:125], v[198:201], v[38:41]
	v_mfma_f32_16x16x32_bf16 v[62:65], v[134:137], v[168:171], v[62:65]
	v_mfma_f32_16x16x32_bf16 v[58:61], v[160:163], v[168:171], v[58:61]
	v_mfma_f32_16x16x32_bf16 v[50:53], v[160:163], v[186:189], v[50:53]
	v_mfma_f32_16x16x32_bf16 v[54:57], v[134:137], v[186:189], v[54:57]
	v_mfma_f32_16x16x32_bf16 v[46:49], v[134:137], v[194:197], v[46:49]
	v_mfma_f32_16x16x32_bf16 v[42:45], v[160:163], v[194:197], v[42:45]
	v_mfma_f32_16x16x32_bf16 v[34:37], v[160:163], v[202:205], v[34:37]
	v_mfma_f32_16x16x32_bf16 v[38:41], v[134:137], v[202:205], v[38:41]
	s_setprio 0
	s_barrier
	s_mov_b32 m0, s15
	s_mov_b32 s42, s78
	s_mov_b32 s43, s79
	ds_read_b128 v[164:167], v211 offset:16384
	ds_read_b128 v[168:171], v211 offset:17408
	ds_read_b128 v[182:185], v211 offset:18432
	ds_read_b128 v[186:189], v211 offset:19456
	ds_read_b128 v[190:193], v211 offset:20480
	ds_read_b128 v[194:197], v211 offset:21504
	ds_read_b128 v[198:201], v211 offset:22528
	ds_read_b128 v[202:205], v211 offset:23552
	buffer_load_dwordx4 v179, s[40:43], s60 offen lds
	s_mov_b32 m0, s16
	s_add_i32 s62, s60, 0x158000
	buffer_load_dwordx4 v207, s[40:43], s60 offen lds
	s_mov_b32 m0, s17
	s_nop 0
	buffer_load_dwordx4 v179, s[40:43], s62 offen lds
	s_mov_b32 m0, s18
	s_nop 0
	buffer_load_dwordx4 v207, s[40:43], s62 offen lds
	s_mov_b32 m0, s14
	s_nop 0
	buffer_load_dwordx4 v178, s[76:79], s61 offen lds
	s_mov_b32 m0, s19
	s_nop 0
	buffer_load_dwordx4 v206, s[76:79], s61 offen lds
	s_waitcnt vmcnt(8)
	s_waitcnt lgkmcnt(0)
	s_barrier
	s_setprio 1
	s_waitcnt lgkmcnt(7)
	s_waitcnt lgkmcnt(0)
	v_mfma_f32_16x16x32_bf16 v[94:97], v[106:109], v[164:167], v[94:97]
	v_mfma_f32_16x16x32_bf16 v[90:93], v[114:117], v[164:167], v[90:93]
	v_mfma_f32_16x16x32_bf16 v[82:85], v[114:117], v[182:185], v[82:85]
	v_mfma_f32_16x16x32_bf16 v[86:89], v[106:109], v[182:185], v[86:89]
	v_mfma_f32_16x16x32_bf16 v[78:81], v[106:109], v[190:193], v[78:81]
	v_mfma_f32_16x16x32_bf16 v[74:77], v[114:117], v[190:193], v[74:77]
	v_mfma_f32_16x16x32_bf16 v[66:69], v[114:117], v[198:201], v[66:69]
	v_mfma_f32_16x16x32_bf16 v[70:73], v[106:109], v[198:201], v[70:73]
	v_mfma_f32_16x16x32_bf16 v[94:97], v[110:113], v[168:171], v[94:97]
	v_mfma_f32_16x16x32_bf16 v[90:93], v[118:121], v[168:171], v[90:93]
	v_mfma_f32_16x16x32_bf16 v[82:85], v[118:121], v[186:189], v[82:85]
	v_mfma_f32_16x16x32_bf16 v[86:89], v[110:113], v[186:189], v[86:89]
	v_mfma_f32_16x16x32_bf16 v[78:81], v[110:113], v[194:197], v[78:81]
	v_mfma_f32_16x16x32_bf16 v[74:77], v[118:121], v[194:197], v[74:77]
	v_mfma_f32_16x16x32_bf16 v[66:69], v[118:121], v[202:205], v[66:69]
	v_mfma_f32_16x16x32_bf16 v[70:73], v[110:113], v[202:205], v[70:73]
	s_setprio 0
	s_setprio 1
	v_mfma_f32_16x16x32_bf16 v[30:33], v[122:125], v[164:167], v[30:33]
	v_mfma_f32_16x16x32_bf16 v[26:29], v[156:159], v[164:167], v[26:29]
	v_mfma_f32_16x16x32_bf16 v[18:21], v[156:159], v[182:185], v[18:21]
	v_mfma_f32_16x16x32_bf16 v[22:25], v[122:125], v[182:185], v[22:25]
	v_mfma_f32_16x16x32_bf16 v[14:17], v[122:125], v[190:193], v[14:17]
	v_mfma_f32_16x16x32_bf16 v[10:13], v[156:159], v[190:193], v[10:13]
	v_mfma_f32_16x16x32_bf16 v[2:5], v[156:159], v[198:201], v[2:5]
	v_mfma_f32_16x16x32_bf16 v[6:9], v[122:125], v[198:201], v[6:9]
	v_mfma_f32_16x16x32_bf16 v[30:33], v[134:137], v[168:171], v[30:33]
	v_mfma_f32_16x16x32_bf16 v[26:29], v[160:163], v[168:171], v[26:29]
	v_mfma_f32_16x16x32_bf16 v[18:21], v[160:163], v[186:189], v[18:21]
	v_mfma_f32_16x16x32_bf16 v[22:25], v[134:137], v[186:189], v[22:25]
	v_mfma_f32_16x16x32_bf16 v[14:17], v[134:137], v[194:197], v[14:17]
	v_mfma_f32_16x16x32_bf16 v[10:13], v[160:163], v[194:197], v[10:13]
	v_mfma_f32_16x16x32_bf16 v[2:5], v[160:163], v[202:205], v[2:5]
	v_mfma_f32_16x16x32_bf16 v[6:9], v[134:137], v[202:205], v[6:9]
	s_setprio 0
	s_barrier
; #define PG8_STAGEX(rs, bufoff, soff, voff) do { _Pragma("unroll") for (int _i = 0; _i < 2; ++_i) \
;         __builtin_amdgcn_raw_ptr_buffer_load_lds(rs, (LAS unsigned*)(lds + (bufoff) + ldsw + _i * 8192), 16, (voff)[_i], (soff), 0, 0); } while (0)
; #define PG8_LDA(dst, b, h) do { _Pragma("unroll") for (int m = 0; m < 4; ++m) _Pragma("unroll") for (int k = 0; k < 2; ++k) dst[m][k] = *(const LAS bf16x8*)(lds + PG8_SA(b, h) + aoff + m * 2048 + k * 1024); } while (0)
; #define PG8_LDB(dst, b, h) do { _Pragma("unroll") for (int n = 0; n < 2; ++n) _Pragma("unroll") for (int k = 0; k < 2; ++k) dst[n][k] = *(const LAS bf16x8*)(lds + PG8_SB(b, h) + boff + n * 2048 + k * 1024); } while (0)
; #define PG8_WAIT_V(n) asm volatile("s_waitcnt vmcnt(" #n ")" ::: "memory")
; #define PG8_WAIT_L(n) asm volatile("s_waitcnt lgkmcnt(" #n ")" ::: "memory")
; #define PG8_BAR __builtin_amdgcn_s_barrier()
; #define PG8_SCHED __builtin_amdgcn_sched_barrier(0)
;     ...
;             PG8_LDB(B0, 0, 0); PG8_LDB(B1, 0, 1); PG8_SCHED; PG8_LDA(At, 0, 0); PG8_STAGEX(rsA, PG8_SA(1, 1), a1 + hstepA, voffA);
;             PG8_WAIT_V(8); PG8_WAIT_L(0); PG8_BAR; PG8_MMA(0, 0, At, B0); PG8_MMA(0, 1, At, B1); PG8_BAR; PG8_SCHED;
;             PG8_LDA(At, 0, 1); PG8_STAGEX(rsB, PG8_SB(0, 0), b2, voffB); PG8_STAGEX(rsB, PG8_SB(0, 1), b2 + hstepB, voffB); PG8_STAGEX(rsA, PG8_SA(0, 0), a2, voffA);
;             PG8_WAIT_V(8); PG8_WAIT_L(0); PG8_BAR; PG8_MMA(1, 0, At, B0); PG8_MMA(1, 1, At, B1); PG8_BAR; PG8_SCHED;
;             PG8_LDB(B0, 1, 0); PG8_LDB(B1, 1, 1); PG8_SCHED; PG8_LDA(At, 1, 0); PG8_STAGEX(rsA, PG8_SA(0, 1), a2 + hstepA, voffA);
;             PG8_WAIT_V(8); PG8_WAIT_L(0); PG8_BAR; PG8_MMA(0, 0, At, B0); PG8_MMA(0, 1, At, B1); PG8_BAR; PG8_SCHED;
;             PG8_LDA(At, 1, 1); PG8_STAGEX(rsB, PG8_SB(1, 0), b3, voffB); PG8_STAGEX(rsB, PG8_SB(1, 1), b3 + hstepB, voffB); PG8_STAGEX(rsA, PG8_SA(1, 0), a3, voffA);
;             PG8_WAIT_V(8); PG8_WAIT_L(0); PG8_BAR; PG8_MMA(1, 0, At, B0); PG8_MMA(1, 1, At, B1); PG8_BAR; PG8_SCHED;
	v_add_u32_e32 v118, 0x18000, v210
	v_add_u32_e32 v160, 0x1c000, v210
	ds_read_b128 v[106:109], v118
	ds_read_b128 v[110:113], v118 offset:1024
	ds_read_b128 v[114:117], v118 offset:2048
	ds_read_b128 v[118:121], v118 offset:3072
	ds_read_b128 v[122:125], v160
	ds_read_b128 v[134:137], v160 offset:1024
	ds_read_b128 v[156:159], v160 offset:2048
	ds_read_b128 v[160:163], v160 offset:3072
	s_add_i32 s61, s61, 0x158000
	s_mov_b32 m0, s20
	ds_read_b128 v[164:167], v211 offset:32768
	ds_read_b128 v[168:171], v211 offset:33792
	ds_read_b128 v[182:185], v211 offset:34816
	ds_read_b128 v[186:189], v211 offset:35840
	ds_read_b128 v[190:193], v211 offset:36864
	ds_read_b128 v[194:197], v211 offset:37888
	ds_read_b128 v[198:201], v211 offset:38912
	ds_read_b128 v[202:205], v211 offset:39936
	buffer_load_dwordx4 v178, s[76:79], s61 offen lds
	s_mov_b32 m0, s21
	s_nop 0
	buffer_load_dwordx4 v206, s[76:79], s61 offen lds
	s_waitcnt vmcnt(8)
	s_waitcnt lgkmcnt(0)
	s_barrier
	s_setprio 1
	s_waitcnt lgkmcnt(7)
	s_waitcnt lgkmcnt(0)
	v_mfma_f32_16x16x32_bf16 v[150:153], v[106:109], v[164:167], v[150:153]
	v_mfma_f32_16x16x32_bf16 v[146:149], v[114:117], v[164:167], v[146:149]
	v_mfma_f32_16x16x32_bf16 v[138:141], v[114:117], v[182:185], v[138:141]
	v_mfma_f32_16x16x32_bf16 v[142:145], v[106:109], v[182:185], v[142:145]
	v_mfma_f32_16x16x32_bf16 v[130:133], v[106:109], v[190:193], v[130:133]
	v_mfma_f32_16x16x32_bf16 v[126:129], v[114:117], v[190:193], v[126:129]
	v_mfma_f32_16x16x32_bf16 v[98:101], v[114:117], v[198:201], v[98:101]
	v_mfma_f32_16x16x32_bf16 v[102:105], v[106:109], v[198:201], v[102:105]
	v_mfma_f32_16x16x32_bf16 v[150:153], v[110:113], v[168:171], v[150:153]
	v_mfma_f32_16x16x32_bf16 v[146:149], v[118:121], v[168:171], v[146:149]
	v_mfma_f32_16x16x32_bf16 v[138:141], v[118:121], v[186:189], v[138:141]
	v_mfma_f32_16x16x32_bf16 v[142:145], v[110:113], v[186:189], v[142:145]
	v_mfma_f32_16x16x32_bf16 v[130:133], v[110:113], v[194:197], v[130:133]
	v_mfma_f32_16x16x32_bf16 v[126:129], v[118:121], v[194:197], v[126:129]
	v_mfma_f32_16x16x32_bf16 v[98:101], v[118:121], v[202:205], v[98:101]
	v_mfma_f32_16x16x32_bf16 v[102:105], v[110:113], v[202:205], v[102:105]
	s_setprio 0
	s_setprio 1
	v_mfma_f32_16x16x32_bf16 v[62:65], v[122:125], v[164:167], v[62:65]
	v_mfma_f32_16x16x32_bf16 v[58:61], v[156:159], v[164:167], v[58:61]
	v_mfma_f32_16x16x32_bf16 v[50:53], v[156:159], v[182:185], v[50:53]
	v_mfma_f32_16x16x32_bf16 v[54:57], v[122:125], v[182:185], v[54:57]
	v_mfma_f32_16x16x32_bf16 v[46:49], v[122:125], v[190:193], v[46:49]
	v_mfma_f32_16x16x32_bf16 v[42:45], v[156:159], v[190:193], v[42:45]
	v_mfma_f32_16x16x32_bf16 v[34:37], v[156:159], v[198:201], v[34:37]
	v_mfma_f32_16x16x32_bf16 v[38:41], v[122:125], v[198:201], v[38:41]
	v_mfma_f32_16x16x32_bf16 v[62:65], v[134:137], v[168:171], v[62:65]
	v_mfma_f32_16x16x32_bf16 v[58:61], v[160:163], v[168:171], v[58:61]
	v_mfma_f32_16x16x32_bf16 v[50:53], v[160:163], v[186:189], v[50:53]
	v_mfma_f32_16x16x32_bf16 v[54:57], v[134:137], v[186:189], v[54:57]
	v_mfma_f32_16x16x32_bf16 v[46:49], v[134:137], v[194:197], v[46:49]
	v_mfma_f32_16x16x32_bf16 v[42:45], v[160:163], v[194:197], v[42:45]
	v_mfma_f32_16x16x32_bf16 v[34:37], v[160:163], v[202:205], v[34:37]
	v_mfma_f32_16x16x32_bf16 v[38:41], v[134:137], v[202:205], v[38:41]
	s_setprio 0
	s_barrier
	s_mov_b32 m0, s28
	s_or_b32 s61, s60, 0x80
	ds_read_b128 v[164:167], v211 offset:49152
	ds_read_b128 v[168:171], v211 offset:50176
	ds_read_b128 v[182:185], v211 offset:51200
	ds_read_b128 v[186:189], v211 offset:52224
	ds_read_b128 v[190:193], v211 offset:53248
	ds_read_b128 v[194:197], v211 offset:54272
	ds_read_b128 v[198:201], v211 offset:55296
	ds_read_b128 v[202:205], v211 offset:56320
	buffer_load_dwordx4 v179, s[40:43], s61 offen lds
	s_mov_b32 m0, s29
	s_add_i32 s60, s60, 0x158080
	buffer_load_dwordx4 v207, s[40:43], s61 offen lds
	s_mov_b32 m0, s66
	s_nop 0
	buffer_load_dwordx4 v179, s[40:43], s60 offen lds
	s_mov_b32 m0, s67
	s_nop 0
	buffer_load_dwordx4 v207, s[40:43], s60 offen lds
	s_mov_b32 m0, s54
	s_nop 0
	buffer_load_dwordx4 v178, s[76:79], s59 offen lds
	s_mov_b32 m0, s55
	s_nop 0
	buffer_load_dwordx4 v206, s[76:79], s59 offen lds
	s_waitcnt vmcnt(8)
	s_waitcnt lgkmcnt(0)
	s_barrier
	s_setprio 1
	s_waitcnt lgkmcnt(7)
	s_waitcnt lgkmcnt(0)
	v_mfma_f32_16x16x32_bf16 v[94:97], v[106:109], v[164:167], v[94:97]
	v_mfma_f32_16x16x32_bf16 v[90:93], v[114:117], v[164:167], v[90:93]
	v_mfma_f32_16x16x32_bf16 v[82:85], v[114:117], v[182:185], v[82:85]
	v_mfma_f32_16x16x32_bf16 v[86:89], v[106:109], v[182:185], v[86:89]
	v_mfma_f32_16x16x32_bf16 v[78:81], v[106:109], v[190:193], v[78:81]
	v_mfma_f32_16x16x32_bf16 v[74:77], v[114:117], v[190:193], v[74:77]
	v_mfma_f32_16x16x32_bf16 v[66:69], v[114:117], v[198:201], v[66:69]
	v_mfma_f32_16x16x32_bf16 v[70:73], v[106:109], v[198:201], v[70:73]
	v_mfma_f32_16x16x32_bf16 v[94:97], v[110:113], v[168:171], v[94:97]
	v_mfma_f32_16x16x32_bf16 v[90:93], v[118:121], v[168:171], v[90:93]
	v_mfma_f32_16x16x32_bf16 v[82:85], v[118:121], v[186:189], v[82:85]
	v_mfma_f32_16x16x32_bf16 v[86:89], v[110:113], v[186:189], v[86:89]
	v_mfma_f32_16x16x32_bf16 v[78:81], v[110:113], v[194:197], v[78:81]
	v_mfma_f32_16x16x32_bf16 v[74:77], v[118:121], v[194:197], v[74:77]
	v_mfma_f32_16x16x32_bf16 v[66:69], v[118:121], v[202:205], v[66:69]
	v_mfma_f32_16x16x32_bf16 v[70:73], v[110:113], v[202:205], v[70:73]
	s_setprio 0
	s_setprio 1
	v_mfma_f32_16x16x32_bf16 v[30:33], v[122:125], v[164:167], v[30:33]
	v_mfma_f32_16x16x32_bf16 v[26:29], v[156:159], v[164:167], v[26:29]
	v_mfma_f32_16x16x32_bf16 v[18:21], v[156:159], v[182:185], v[18:21]
	v_mfma_f32_16x16x32_bf16 v[22:25], v[122:125], v[182:185], v[22:25]
	v_mfma_f32_16x16x32_bf16 v[14:17], v[122:125], v[190:193], v[14:17]
	v_mfma_f32_16x16x32_bf16 v[10:13], v[156:159], v[190:193], v[10:13]
	v_mfma_f32_16x16x32_bf16 v[2:5], v[156:159], v[198:201], v[2:5]
	v_mfma_f32_16x16x32_bf16 v[6:9], v[122:125], v[198:201], v[6:9]
	v_mfma_f32_16x16x32_bf16 v[30:33], v[134:137], v[168:171], v[30:33]
	v_mfma_f32_16x16x32_bf16 v[26:29], v[160:163], v[168:171], v[26:29]
	v_mfma_f32_16x16x32_bf16 v[18:21], v[160:163], v[186:189], v[18:21]
	v_mfma_f32_16x16x32_bf16 v[22:25], v[134:137], v[186:189], v[22:25]
	v_mfma_f32_16x16x32_bf16 v[14:17], v[134:137], v[194:197], v[14:17]
	v_mfma_f32_16x16x32_bf16 v[10:13], v[160:163], v[194:197], v[10:13]
	v_mfma_f32_16x16x32_bf16 v[2:5], v[160:163], v[202:205], v[2:5]
	v_mfma_f32_16x16x32_bf16 v[6:9], v[134:137], v[202:205], v[6:9]
	s_setprio 0
	s_barrier
	s_add_i32 s58, s58, 2
	s_addk_i32 s51, 0x100
	s_addk_i32 s57, 0x100
	s_cmpk_gt_u32 s58, 0x53
	s_cbranch_scc0 .LBB0_323
	s_and_b64 vcc, exec, s[48:49]
	s_cbranch_vccz .LBB0_326
	s_barrier

; #define PG8_STAGEX(rs, bufoff, soff, voff) do { _Pragma("unroll") for (int _i = 0; _i < 2; ++_i) \
;         __builtin_amdgcn_raw_ptr_buffer_load_lds(rs, (LAS unsigned*)(lds + (bufoff) + ldsw + _i * 8192), 16, (voff)[_i], (soff), 0, 0); } while (0)
; #define PG8_LDA(dst, b, h) do { _Pragma("unroll") for (int m = 0; m < 4; ++m) _Pragma("unroll") for (int k = 0; k < 2; ++k) dst[m][k] = *(const LAS bf16x8*)(lds + PG8_SA(b, h) + aoff + m * 2048 + k * 1024); } while (0)
; #define PG8_LDB(dst, b, h) do { _Pragma("unroll") for (int n = 0; n < 2; ++n) _Pragma("unroll") for (int k = 0; k < 2; ++k) dst[n][k] = *(const LAS bf16x8*)(lds + PG8_SB(b, h) + boff + n * 2048 + k * 1024); } while (0)
; #define PG8_WAIT_V(n) asm volatile("s_waitcnt vmcnt(" #n ")" ::: "memory")
; #define PG8_WAIT_L(n) asm volatile("s_waitcnt lgkmcnt(" #n ")" ::: "memory")
; #define PG8_BAR __builtin_amdgcn_s_barrier()
; #define PG8_SCHED __builtin_amdgcn_sched_barrier(0)
;     ...
;                 PG8_WAIT_L(0); PG8_BAR; if (w0) { PG8_MMA(0, 0, At, B0); PG8_MMA(0, 1, At, B1); } PG8_BAR; PG8_SCHED;
;                 PG8_STAGEX(rsB, PG8_SB(0, 0), b2, voffB); PG8_STAGEX(rsB, PG8_SB(0, 1), b2 + hstepB, voffB); PG8_STAGEX(rsA, PG8_SA(0, 0), a2, voffA);
;                 PG8_WAIT_V(6); PG8_BAR; PG8_BAR; PG8_SCHED;
;                 if (w0) { PG8_LDB(B0, 1, 0); PG8_LDB(B1, 1, 1); PG8_SCHED; PG8_LDA(At, 1, 0); }
;                 PG8_WAIT_L(0); PG8_BAR; if (w0) { PG8_MMA(0, 0, At, B0); PG8_MMA(0, 1, At, B1); } PG8_BAR; PG8_SCHED;
.LBB0_355:
	s_waitcnt lgkmcnt(0)
	s_and_b64 vcc, exec, s[38:39]
	s_barrier
	s_cbranch_vccnz .LBB0_357
	s_setprio 1
	s_waitcnt lgkmcnt(7)
	s_waitcnt lgkmcnt(0)
	v_mfma_f32_16x16x32_bf16 v[62:65], v[66:69], v[98:101], v[62:65]
	v_mfma_f32_16x16x32_bf16 v[58:61], v[74:77], v[98:101], v[58:61]
	v_mfma_f32_16x16x32_bf16 v[50:53], v[74:77], v[106:109], v[50:53]
	v_mfma_f32_16x16x32_bf16 v[54:57], v[66:69], v[106:109], v[54:57]
	v_mfma_f32_16x16x32_bf16 v[46:49], v[66:69], v[114:117], v[46:49]
	v_mfma_f32_16x16x32_bf16 v[42:45], v[74:77], v[114:117], v[42:45]
	v_mfma_f32_16x16x32_bf16 v[34:37], v[74:77], v[122:125], v[34:37]
	v_mfma_f32_16x16x32_bf16 v[38:41], v[66:69], v[122:125], v[38:41]
	v_mfma_f32_16x16x32_bf16 v[62:65], v[70:73], v[102:105], v[62:65]
	v_mfma_f32_16x16x32_bf16 v[58:61], v[78:81], v[102:105], v[58:61]
	v_mfma_f32_16x16x32_bf16 v[50:53], v[78:81], v[110:113], v[50:53]
	v_mfma_f32_16x16x32_bf16 v[54:57], v[70:73], v[110:113], v[54:57]
	v_mfma_f32_16x16x32_bf16 v[46:49], v[70:73], v[118:121], v[46:49]
	v_mfma_f32_16x16x32_bf16 v[42:45], v[78:81], v[118:121], v[42:45]
	v_mfma_f32_16x16x32_bf16 v[34:37], v[78:81], v[126:129], v[34:37]
	v_mfma_f32_16x16x32_bf16 v[38:41], v[70:73], v[126:129], v[38:41]
	s_setprio 0
	s_setprio 1
	v_mfma_f32_16x16x32_bf16 v[30:33], v[82:85], v[98:101], v[30:33]
	v_mfma_f32_16x16x32_bf16 v[26:29], v[90:93], v[98:101], v[26:29]
	v_mfma_f32_16x16x32_bf16 v[18:21], v[90:93], v[106:109], v[18:21]
	v_mfma_f32_16x16x32_bf16 v[22:25], v[82:85], v[106:109], v[22:25]
	v_mfma_f32_16x16x32_bf16 v[14:17], v[82:85], v[114:117], v[14:17]
	v_mfma_f32_16x16x32_bf16 v[10:13], v[90:93], v[114:117], v[10:13]
	v_mfma_f32_16x16x32_bf16 v[2:5], v[90:93], v[122:125], v[2:5]
	v_mfma_f32_16x16x32_bf16 v[6:9], v[82:85], v[122:125], v[6:9]
	v_mfma_f32_16x16x32_bf16 v[30:33], v[86:89], v[102:105], v[30:33]
	v_mfma_f32_16x16x32_bf16 v[26:29], v[94:97], v[102:105], v[26:29]
	v_mfma_f32_16x16x32_bf16 v[18:21], v[94:97], v[110:113], v[18:21]
	v_mfma_f32_16x16x32_bf16 v[22:25], v[86:89], v[110:113], v[22:25]
	v_mfma_f32_16x16x32_bf16 v[14:17], v[86:89], v[118:121], v[14:17]
	v_mfma_f32_16x16x32_bf16 v[10:13], v[94:97], v[118:121], v[10:13]
	v_mfma_f32_16x16x32_bf16 v[2:5], v[94:97], v[126:129], v[2:5]
	v_mfma_f32_16x16x32_bf16 v[6:9], v[86:89], v[126:129], v[6:9]
	s_setprio 0

; #define PG8_STAGEX(rs, bufoff, soff, voff) do { _Pragma("unroll") for (int _i = 0; _i < 2; ++_i) \
;         __builtin_amdgcn_raw_ptr_buffer_load_lds(rs, (LAS unsigned*)(lds + (bufoff) + ldsw + _i * 8192), 16, (voff)[_i], (soff), 0, 0); } while (0)
; #define PG8_LDA(dst, b, h) do { _Pragma("unroll") for (int m = 0; m < 4; ++m) _Pragma("unroll") for (int k = 0; k < 2; ++k) dst[m][k] = *(const LAS bf16x8*)(lds + PG8_SA(b, h) + aoff + m * 2048 + k * 1024); } while (0)
; #define PG8_LDB(dst, b, h) do { _Pragma("unroll") for (int n = 0; n < 2; ++n) _Pragma("unroll") for (int k = 0; k < 2; ++k) dst[n][k] = *(const LAS bf16x8*)(lds + PG8_SB(b, h) + boff + n * 2048 + k * 1024); } while (0)
; #define PG8_WAIT_V(n) asm volatile("s_waitcnt vmcnt(" #n ")" ::: "memory")
; #define PG8_WAIT_L(n) asm volatile("s_waitcnt lgkmcnt(" #n ")" ::: "memory")
; #define PG8_BAR __builtin_amdgcn_s_barrier()
; #define PG8_SCHED __builtin_amdgcn_sched_barrier(0)
;     ...
;                 PG8_WAIT_L(0); PG8_BAR; if (w0) { PG8_MMA(0, 0, At, B0); PG8_MMA(0, 1, At, B1); } PG8_BAR; PG8_SCHED;
;                 PG8_STAGEX(rsB, PG8_SB(0, 0), b2, voffB); PG8_STAGEX(rsB, PG8_SB(0, 1), b2 + hstepB, voffB); PG8_STAGEX(rsA, PG8_SA(0, 0), a2, voffA);
;                 PG8_WAIT_V(6); PG8_BAR; PG8_BAR; PG8_SCHED;
;                 if (w0) { PG8_LDB(B0, 1, 0); PG8_LDB(B1, 1, 1); PG8_SCHED; PG8_LDA(At, 1, 0); }
;                 PG8_WAIT_L(0); PG8_BAR; if (w0) { PG8_MMA(0, 0, At, B0); PG8_MMA(0, 1, At, B1); } PG8_BAR; PG8_SCHED;
.LBB0_359:
	s_waitcnt lgkmcnt(0)
	s_and_b64 vcc, exec, s[38:39]
	s_barrier
	s_cbranch_vccnz .LBB0_352
	s_setprio 1
	s_waitcnt lgkmcnt(7)
	s_waitcnt lgkmcnt(0)
	v_mfma_f32_16x16x32_bf16 v[62:65], v[66:69], v[98:101], v[62:65]
	v_mfma_f32_16x16x32_bf16 v[58:61], v[74:77], v[98:101], v[58:61]
	v_mfma_f32_16x16x32_bf16 v[50:53], v[74:77], v[106:109], v[50:53]
	v_mfma_f32_16x16x32_bf16 v[54:57], v[66:69], v[106:109], v[54:57]
	v_mfma_f32_16x16x32_bf16 v[46:49], v[66:69], v[114:117], v[46:49]
	v_mfma_f32_16x16x32_bf16 v[42:45], v[74:77], v[114:117], v[42:45]
	v_mfma_f32_16x16x32_bf16 v[34:37], v[74:77], v[122:125], v[34:37]
	v_mfma_f32_16x16x32_bf16 v[38:41], v[66:69], v[122:125], v[38:41]
	v_mfma_f32_16x16x32_bf16 v[62:65], v[70:73], v[102:105], v[62:65]
	v_mfma_f32_16x16x32_bf16 v[58:61], v[78:81], v[102:105], v[58:61]
	v_mfma_f32_16x16x32_bf16 v[50:53], v[78:81], v[110:113], v[50:53]
	v_mfma_f32_16x16x32_bf16 v[54:57], v[70:73], v[110:113], v[54:57]
	v_mfma_f32_16x16x32_bf16 v[46:49], v[70:73], v[118:121], v[46:49]
	v_mfma_f32_16x16x32_bf16 v[42:45], v[78:81], v[118:121], v[42:45]
	v_mfma_f32_16x16x32_bf16 v[34:37], v[78:81], v[126:129], v[34:37]
	v_mfma_f32_16x16x32_bf16 v[38:41], v[70:73], v[126:129], v[38:41]
	s_setprio 0
	s_setprio 1
	v_mfma_f32_16x16x32_bf16 v[30:33], v[82:85], v[98:101], v[30:33]
	v_mfma_f32_16x16x32_bf16 v[26:29], v[90:93], v[98:101], v[26:29]
	v_mfma_f32_16x16x32_bf16 v[18:21], v[90:93], v[106:109], v[18:21]
	v_mfma_f32_16x16x32_bf16 v[22:25], v[82:85], v[106:109], v[22:25]
	v_mfma_f32_16x16x32_bf16 v[14:17], v[82:85], v[114:117], v[14:17]
	v_mfma_f32_16x16x32_bf16 v[10:13], v[90:93], v[114:117], v[10:13]
	v_mfma_f32_16x16x32_bf16 v[2:5], v[90:93], v[122:125], v[2:5]
	v_mfma_f32_16x16x32_bf16 v[6:9], v[82:85], v[122:125], v[6:9]
	v_mfma_f32_16x16x32_bf16 v[30:33], v[86:89], v[102:105], v[30:33]
	v_mfma_f32_16x16x32_bf16 v[26:29], v[94:97], v[102:105], v[26:29]
	v_mfma_f32_16x16x32_bf16 v[18:21], v[94:97], v[110:113], v[18:21]
	v_mfma_f32_16x16x32_bf16 v[22:25], v[86:89], v[110:113], v[22:25]
	v_mfma_f32_16x16x32_bf16 v[14:17], v[86:89], v[118:121], v[14:17]
	v_mfma_f32_16x16x32_bf16 v[10:13], v[94:97], v[118:121], v[10:13]
	v_mfma_f32_16x16x32_bf16 v[2:5], v[94:97], v[126:129], v[2:5]
	v_mfma_f32_16x16x32_bf16 v[6:9], v[86:89], v[126:129], v[6:9]
	s_setprio 0
	s_branch .LBB0_352

; #define PG8_STAGEX(rs, bufoff, soff, voff) do { _Pragma("unroll") for (int _i = 0; _i < 2; ++_i) \
;         __builtin_amdgcn_raw_ptr_buffer_load_lds(rs, (LAS unsigned*)(lds + (bufoff) + ldsw + _i * 8192), 16, (voff)[_i], (soff), 0, 0); } while (0)
; #define PG8_LDA(dst, b, h) do { _Pragma("unroll") for (int m = 0; m < 4; ++m) _Pragma("unroll") for (int k = 0; k < 2; ++k) dst[m][k] = *(const LAS bf16x8*)(lds + PG8_SA(b, h) + aoff + m * 2048 + k * 1024); } while (0)
; #define PG8_LDB(dst, b, h) do { _Pragma("unroll") for (int n = 0; n < 2; ++n) _Pragma("unroll") for (int k = 0; k < 2; ++k) dst[n][k] = *(const LAS bf16x8*)(lds + PG8_SB(b, h) + boff + n * 2048 + k * 1024); } while (0)
; #define PG8_WAIT_V(n) asm volatile("s_waitcnt vmcnt(" #n ")" ::: "memory")
; #define PG8_WAIT_L(n) asm volatile("s_waitcnt lgkmcnt(" #n ")" ::: "memory")
; #define PG8_BAR __builtin_amdgcn_s_barrier()
; #define PG8_SCHED __builtin_amdgcn_sched_barrier(0)
;     ...
;             PG8_LDB(B0, 0, 0); PG8_LDB(B1, 0, 1); PG8_SCHED; PG8_LDA(At, 0, 0); PG8_STAGEX(rsA, PG8_SA(1, 1), a1 + hstepA, voffA);
;             PG8_WAIT_V(8); PG8_WAIT_L(0); PG8_BAR; PG8_MMA(0, 0, At, B0); PG8_MMA(0, 1, At, B1); PG8_BAR; PG8_SCHED;
;             PG8_LDA(At, 0, 1); PG8_STAGEX(rsB, PG8_SB(0, 0), b2, voffB); PG8_STAGEX(rsB, PG8_SB(0, 1), b2 + hstepB, voffB); PG8_STAGEX(rsA, PG8_SA(0, 0), a2, voffA);
;             PG8_WAIT_V(8); PG8_WAIT_L(0); PG8_BAR; PG8_MMA(1, 0, At, B0); PG8_MMA(1, 1, At, B1); PG8_BAR; PG8_SCHED;
;             PG8_LDB(B0, 1, 0); PG8_LDB(B1, 1, 1); PG8_SCHED; PG8_LDA(At, 1, 0); PG8_STAGEX(rsA, PG8_SA(0, 1), a2 + hstepA, voffA);
;             PG8_WAIT_V(8); PG8_WAIT_L(0); PG8_BAR; PG8_MMA(0, 0, At, B0); PG8_MMA(0, 1, At, B1); PG8_BAR; PG8_SCHED;
;             PG8_LDA(At, 1, 1); PG8_STAGEX(rsB, PG8_SB(1, 0), b3, voffB); PG8_STAGEX(rsB, PG8_SB(1, 1), b3 + hstepB, voffB); PG8_STAGEX(rsA, PG8_SA(1, 0), a3, voffA);
;             PG8_WAIT_V(8); PG8_WAIT_L(0); PG8_BAR; PG8_MMA(1, 0, At, B0); PG8_MMA(1, 1, At, B1); PG8_BAR; PG8_SCHED;
.LBB0_437:
	v_add_u32_e32 v142, 0x10000, v220
	v_add_u32_e32 v158, 0x14000, v220
	ds_read_b128 v[130:133], v142
	ds_read_b128 v[134:137], v142 offset:1024
	ds_read_b128 v[138:141], v142 offset:2048
	ds_read_b128 v[142:145], v142 offset:3072
	ds_read_b128 v[146:149], v158
	ds_read_b128 v[150:153], v158 offset:1024
	ds_read_b128 v[154:157], v158 offset:2048
	ds_read_b128 v[158:161], v158 offset:3072
	s_add_i32 s30, s7, 0xfff80080
	s_cmp_eq_u32 s29, 28
	s_cselect_b32 s50, s2, s30
	s_cselect_b32 s31, s5, s28
	s_or_b32 s30, s50, 0x80
	s_mov_b32 m0, s20
	ds_read_b128 v[162:165], v221
	ds_read_b128 v[170:173], v221 offset:1024
	ds_read_b128 v[182:185], v221 offset:2048
	ds_read_b128 v[186:189], v221 offset:3072
	ds_read_b128 v[190:193], v221 offset:4096
	ds_read_b128 v[194:197], v221 offset:5120
	ds_read_b128 v[198:201], v221 offset:6144
	ds_read_b128 v[202:205], v221 offset:7168
	buffer_load_dwordx4 v178, s[76:79], s7 offen lds
	s_mov_b32 m0, s22
	s_nop 0
	buffer_load_dwordx4 v210, s[76:79], s7 offen lds
	s_waitcnt vmcnt(8)
	s_waitcnt lgkmcnt(0)
	s_barrier
	s_setprio 1
	s_waitcnt lgkmcnt(7)
	s_waitcnt lgkmcnt(0)
	v_mfma_f32_16x16x32_bf16 v[126:129], v[130:133], v[162:165], v[126:129]
	v_mfma_f32_16x16x32_bf16 v[110:113], v[138:141], v[162:165], v[110:113]
	v_mfma_f32_16x16x32_bf16 v[102:105], v[138:141], v[182:185], v[102:105]
	v_mfma_f32_16x16x32_bf16 v[118:121], v[130:133], v[182:185], v[118:121]
	v_mfma_f32_16x16x32_bf16 v[114:117], v[130:133], v[190:193], v[114:117]
	v_mfma_f32_16x16x32_bf16 v[98:101], v[138:141], v[190:193], v[98:101]
	v_mfma_f32_16x16x32_bf16 v[106:109], v[138:141], v[198:201], v[106:109]
	v_mfma_f32_16x16x32_bf16 v[122:125], v[130:133], v[198:201], v[122:125]
	v_mfma_f32_16x16x32_bf16 v[126:129], v[134:137], v[170:173], v[126:129]
	v_mfma_f32_16x16x32_bf16 v[110:113], v[142:145], v[170:173], v[110:113]
	v_mfma_f32_16x16x32_bf16 v[102:105], v[142:145], v[186:189], v[102:105]
	v_mfma_f32_16x16x32_bf16 v[118:121], v[134:137], v[186:189], v[118:121]
	v_mfma_f32_16x16x32_bf16 v[114:117], v[134:137], v[194:197], v[114:117]
	v_mfma_f32_16x16x32_bf16 v[98:101], v[142:145], v[194:197], v[98:101]
	v_mfma_f32_16x16x32_bf16 v[106:109], v[142:145], v[202:205], v[106:109]
	v_mfma_f32_16x16x32_bf16 v[122:125], v[134:137], v[202:205], v[122:125]
	s_setprio 0
	s_setprio 1
	v_mfma_f32_16x16x32_bf16 v[62:65], v[146:149], v[162:165], v[62:65]
	v_mfma_f32_16x16x32_bf16 v[46:49], v[154:157], v[162:165], v[46:49]
	v_mfma_f32_16x16x32_bf16 v[38:41], v[154:157], v[182:185], v[38:41]
	v_mfma_f32_16x16x32_bf16 v[54:57], v[146:149], v[182:185], v[54:57]
	v_mfma_f32_16x16x32_bf16 v[50:53], v[146:149], v[190:193], v[50:53]
	v_mfma_f32_16x16x32_bf16 v[34:37], v[154:157], v[190:193], v[34:37]
	v_mfma_f32_16x16x32_bf16 v[42:45], v[154:157], v[198:201], v[42:45]
	v_mfma_f32_16x16x32_bf16 v[58:61], v[146:149], v[198:201], v[58:61]
	v_mfma_f32_16x16x32_bf16 v[62:65], v[150:153], v[170:173], v[62:65]
	v_mfma_f32_16x16x32_bf16 v[46:49], v[158:161], v[170:173], v[46:49]
	v_mfma_f32_16x16x32_bf16 v[38:41], v[158:161], v[186:189], v[38:41]
	v_mfma_f32_16x16x32_bf16 v[54:57], v[150:153], v[186:189], v[54:57]
	v_mfma_f32_16x16x32_bf16 v[50:53], v[150:153], v[194:197], v[50:53]
	v_mfma_f32_16x16x32_bf16 v[34:37], v[158:161], v[194:197], v[34:37]
	v_mfma_f32_16x16x32_bf16 v[42:45], v[158:161], v[202:205], v[42:45]
	v_mfma_f32_16x16x32_bf16 v[58:61], v[150:153], v[202:205], v[58:61]
	s_setprio 0
	s_barrier
	s_mov_b32 m0, s90
	s_mov_b32 s58, s78
	s_mov_b32 s59, s79
	ds_read_b128 v[162:165], v221 offset:16384
	ds_read_b128 v[170:173], v221 offset:17408
	ds_read_b128 v[182:185], v221 offset:18432
	ds_read_b128 v[186:189], v221 offset:19456
	ds_read_b128 v[190:193], v221 offset:20480
	ds_read_b128 v[194:197], v221 offset:21504
	ds_read_b128 v[198:201], v221 offset:22528
	ds_read_b128 v[202:205], v221 offset:23552
	buffer_load_dwordx4 v179, s[56:59], s31 offen lds
	s_mov_b32 m0, s91
	s_add_i32 s51, s31, 0x80000
	buffer_load_dwordx4 v211, s[56:59], s31 offen lds
	s_mov_b32 m0, s9
	s_nop 0
	buffer_load_dwordx4 v179, s[56:59], s51 offen lds
	s_mov_b32 m0, s10
	s_nop 0
	buffer_load_dwordx4 v211, s[56:59], s51 offen lds
	s_mov_b32 m0, s89
	s_nop 0
	buffer_load_dwordx4 v178, s[76:79], s50 offen lds
	s_mov_b32 m0, s11
	s_nop 0
	buffer_load_dwordx4 v210, s[76:79], s50 offen lds
	s_waitcnt vmcnt(8)
	s_waitcnt lgkmcnt(0)
	s_barrier
	s_setprio 1
	s_waitcnt lgkmcnt(7)
	s_waitcnt lgkmcnt(0)
	v_mfma_f32_16x16x32_bf16 v[94:97], v[130:133], v[162:165], v[94:97]
	v_mfma_f32_16x16x32_bf16 v[78:81], v[138:141], v[162:165], v[78:81]
	v_mfma_f32_16x16x32_bf16 v[70:73], v[138:141], v[182:185], v[70:73]
	v_mfma_f32_16x16x32_bf16 v[86:89], v[130:133], v[182:185], v[86:89]
	v_mfma_f32_16x16x32_bf16 v[82:85], v[130:133], v[190:193], v[82:85]
	v_mfma_f32_16x16x32_bf16 v[66:69], v[138:141], v[190:193], v[66:69]
	v_mfma_f32_16x16x32_bf16 v[74:77], v[138:141], v[198:201], v[74:77]
	v_mfma_f32_16x16x32_bf16 v[90:93], v[130:133], v[198:201], v[90:93]
	v_mfma_f32_16x16x32_bf16 v[94:97], v[134:137], v[170:173], v[94:97]
	v_mfma_f32_16x16x32_bf16 v[78:81], v[142:145], v[170:173], v[78:81]
	v_mfma_f32_16x16x32_bf16 v[70:73], v[142:145], v[186:189], v[70:73]
	v_mfma_f32_16x16x32_bf16 v[86:89], v[134:137], v[186:189], v[86:89]
	v_mfma_f32_16x16x32_bf16 v[82:85], v[134:137], v[194:197], v[82:85]
	v_mfma_f32_16x16x32_bf16 v[66:69], v[142:145], v[194:197], v[66:69]
	v_mfma_f32_16x16x32_bf16 v[74:77], v[142:145], v[202:205], v[74:77]
	v_mfma_f32_16x16x32_bf16 v[90:93], v[134:137], v[202:205], v[90:93]
	s_setprio 0
	s_setprio 1
	v_mfma_f32_16x16x32_bf16 v[30:33], v[146:149], v[162:165], v[30:33]
	v_mfma_f32_16x16x32_bf16 v[14:17], v[154:157], v[162:165], v[14:17]
	v_mfma_f32_16x16x32_bf16 v[10:13], v[154:157], v[182:185], v[10:13]
	v_mfma_f32_16x16x32_bf16 v[22:25], v[146:149], v[182:185], v[22:25]
	v_mfma_f32_16x16x32_bf16 v[18:21], v[146:149], v[190:193], v[18:21]
	v_mfma_f32_16x16x32_bf16 v[2:5], v[154:157], v[190:193], v[2:5]
	v_mfma_f32_16x16x32_bf16 v[6:9], v[154:157], v[198:201], v[6:9]
	v_mfma_f32_16x16x32_bf16 v[26:29], v[146:149], v[198:201], v[26:29]
	v_mfma_f32_16x16x32_bf16 v[30:33], v[150:153], v[170:173], v[30:33]
	v_mfma_f32_16x16x32_bf16 v[14:17], v[158:161], v[170:173], v[14:17]
	v_mfma_f32_16x16x32_bf16 v[10:13], v[158:161], v[186:189], v[10:13]
	v_mfma_f32_16x16x32_bf16 v[22:25], v[150:153], v[186:189], v[22:25]
	v_mfma_f32_16x16x32_bf16 v[18:21], v[150:153], v[194:197], v[18:21]
	v_mfma_f32_16x16x32_bf16 v[2:5], v[158:161], v[194:197], v[2:5]
	v_mfma_f32_16x16x32_bf16 v[6:9], v[158:161], v[202:205], v[6:9]
	v_mfma_f32_16x16x32_bf16 v[26:29], v[150:153], v[202:205], v[26:29]
	s_setprio 0
	s_barrier
; #define PG8_STAGEX(rs, bufoff, soff, voff) do { _Pragma("unroll") for (int _i = 0; _i < 2; ++_i) \
;         __builtin_amdgcn_raw_ptr_buffer_load_lds(rs, (LAS unsigned*)(lds + (bufoff) + ldsw + _i * 8192), 16, (voff)[_i], (soff), 0, 0); } while (0)
; #define PG8_LDA(dst, b, h) do { _Pragma("unroll") for (int m = 0; m < 4; ++m) _Pragma("unroll") for (int k = 0; k < 2; ++k) dst[m][k] = *(const LAS bf16x8*)(lds + PG8_SA(b, h) + aoff + m * 2048 + k * 1024); } while (0)
; #define PG8_LDB(dst, b, h) do { _Pragma("unroll") for (int n = 0; n < 2; ++n) _Pragma("unroll") for (int k = 0; k < 2; ++k) dst[n][k] = *(const LAS bf16x8*)(lds + PG8_SB(b, h) + boff + n * 2048 + k * 1024); } while (0)
; #define PG8_WAIT_V(n) asm volatile("s_waitcnt vmcnt(" #n ")" ::: "memory")
; #define PG8_WAIT_L(n) asm volatile("s_waitcnt lgkmcnt(" #n ")" ::: "memory")
; #define PG8_BAR __builtin_amdgcn_s_barrier()
; #define PG8_SCHED __builtin_amdgcn_sched_barrier(0)
;     ...
;             PG8_LDB(B0, 1, 0); PG8_LDB(B1, 1, 1); PG8_SCHED; PG8_LDA(At, 1, 0); PG8_STAGEX(rsA, PG8_SA(0, 1), a2 + hstepA, voffA);
;             PG8_WAIT_V(8); PG8_WAIT_L(0); PG8_BAR; PG8_MMA(0, 0, At, B0); PG8_MMA(0, 1, At, B1); PG8_BAR; PG8_SCHED;
;             PG8_LDA(At, 1, 1); PG8_STAGEX(rsB, PG8_SB(1, 0), b3, voffB); PG8_STAGEX(rsB, PG8_SB(1, 1), b3 + hstepB, voffB); PG8_STAGEX(rsA, PG8_SA(1, 0), a3, voffA);
;             PG8_WAIT_V(8); PG8_WAIT_L(0); PG8_BAR; PG8_MMA(1, 0, At, B0); PG8_MMA(1, 1, At, B1); PG8_BAR; PG8_SCHED;
;         }
	v_add_u32_e32 v142, 0x18000, v220
	v_add_u32_e32 v158, 0x1c000, v220
	ds_read_b128 v[130:133], v142
	ds_read_b128 v[134:137], v142 offset:1024
	ds_read_b128 v[138:141], v142 offset:2048
	ds_read_b128 v[142:145], v142 offset:3072
	ds_read_b128 v[146:149], v158
	ds_read_b128 v[150:153], v158 offset:1024
	ds_read_b128 v[154:157], v158 offset:2048
	ds_read_b128 v[158:161], v158 offset:3072
	s_add_i32 s50, s50, 0x80000
	s_mov_b32 m0, s74
	ds_read_b128 v[162:165], v221 offset:32768
	ds_read_b128 v[170:173], v221 offset:33792
	ds_read_b128 v[182:185], v221 offset:34816
	ds_read_b128 v[186:189], v221 offset:35840
	ds_read_b128 v[190:193], v221 offset:36864
	ds_read_b128 v[194:197], v221 offset:37888
	ds_read_b128 v[198:201], v221 offset:38912
	ds_read_b128 v[202:205], v221 offset:39936
	buffer_load_dwordx4 v178, s[76:79], s50 offen lds
	s_mov_b32 m0, s12
	s_nop 0
	buffer_load_dwordx4 v210, s[76:79], s50 offen lds
	s_waitcnt vmcnt(8)
	s_waitcnt lgkmcnt(0)
	s_barrier
	s_setprio 1
	s_waitcnt lgkmcnt(7)
	s_waitcnt lgkmcnt(0)
	v_mfma_f32_16x16x32_bf16 v[126:129], v[130:133], v[162:165], v[126:129]
	v_mfma_f32_16x16x32_bf16 v[110:113], v[138:141], v[162:165], v[110:113]
	v_mfma_f32_16x16x32_bf16 v[102:105], v[138:141], v[182:185], v[102:105]
	v_mfma_f32_16x16x32_bf16 v[118:121], v[130:133], v[182:185], v[118:121]
	v_mfma_f32_16x16x32_bf16 v[114:117], v[130:133], v[190:193], v[114:117]
	v_mfma_f32_16x16x32_bf16 v[98:101], v[138:141], v[190:193], v[98:101]
	v_mfma_f32_16x16x32_bf16 v[106:109], v[138:141], v[198:201], v[106:109]
	v_mfma_f32_16x16x32_bf16 v[122:125], v[130:133], v[198:201], v[122:125]
	v_mfma_f32_16x16x32_bf16 v[126:129], v[134:137], v[170:173], v[126:129]
	v_mfma_f32_16x16x32_bf16 v[110:113], v[142:145], v[170:173], v[110:113]
	v_mfma_f32_16x16x32_bf16 v[102:105], v[142:145], v[186:189], v[102:105]
	v_mfma_f32_16x16x32_bf16 v[118:121], v[134:137], v[186:189], v[118:121]
	v_mfma_f32_16x16x32_bf16 v[114:117], v[134:137], v[194:197], v[114:117]
	v_mfma_f32_16x16x32_bf16 v[98:101], v[142:145], v[194:197], v[98:101]
	v_mfma_f32_16x16x32_bf16 v[106:109], v[142:145], v[202:205], v[106:109]
	v_mfma_f32_16x16x32_bf16 v[122:125], v[134:137], v[202:205], v[122:125]
	s_setprio 0
	s_setprio 1
	v_mfma_f32_16x16x32_bf16 v[62:65], v[146:149], v[162:165], v[62:65]
	v_mfma_f32_16x16x32_bf16 v[46:49], v[154:157], v[162:165], v[46:49]
	v_mfma_f32_16x16x32_bf16 v[38:41], v[154:157], v[182:185], v[38:41]
	v_mfma_f32_16x16x32_bf16 v[54:57], v[146:149], v[182:185], v[54:57]
	v_mfma_f32_16x16x32_bf16 v[50:53], v[146:149], v[190:193], v[50:53]
	v_mfma_f32_16x16x32_bf16 v[34:37], v[154:157], v[190:193], v[34:37]
	v_mfma_f32_16x16x32_bf16 v[42:45], v[154:157], v[198:201], v[42:45]
	v_mfma_f32_16x16x32_bf16 v[58:61], v[146:149], v[198:201], v[58:61]
	v_mfma_f32_16x16x32_bf16 v[62:65], v[150:153], v[170:173], v[62:65]
	v_mfma_f32_16x16x32_bf16 v[46:49], v[158:161], v[170:173], v[46:49]
	v_mfma_f32_16x16x32_bf16 v[38:41], v[158:161], v[186:189], v[38:41]
	v_mfma_f32_16x16x32_bf16 v[54:57], v[150:153], v[186:189], v[54:57]
	v_mfma_f32_16x16x32_bf16 v[50:53], v[150:153], v[194:197], v[50:53]
	v_mfma_f32_16x16x32_bf16 v[34:37], v[158:161], v[194:197], v[34:37]
	v_mfma_f32_16x16x32_bf16 v[42:45], v[158:161], v[202:205], v[42:45]
	v_mfma_f32_16x16x32_bf16 v[58:61], v[150:153], v[202:205], v[58:61]
	s_setprio 0
	s_barrier
	s_mov_b32 m0, s13
	s_or_b32 s50, s31, 0x80
	ds_read_b128 v[162:165], v221 offset:49152
	ds_read_b128 v[170:173], v221 offset:50176
	ds_read_b128 v[182:185], v221 offset:51200
	ds_read_b128 v[186:189], v221 offset:52224
	ds_read_b128 v[190:193], v221 offset:53248
	ds_read_b128 v[194:197], v221 offset:54272
	ds_read_b128 v[198:201], v221 offset:55296
	ds_read_b128 v[202:205], v221 offset:56320
	buffer_load_dwordx4 v179, s[56:59], s50 offen lds
	s_mov_b32 m0, s14
	s_add_i32 s31, s31, 0x80080
	buffer_load_dwordx4 v211, s[56:59], s50 offen lds
	s_mov_b32 m0, s17
	s_nop 0
	buffer_load_dwordx4 v179, s[56:59], s31 offen lds
	s_mov_b32 m0, s18
	s_nop 0
	buffer_load_dwordx4 v211, s[56:59], s31 offen lds
	s_mov_b32 m0, s15
	s_nop 0
	buffer_load_dwordx4 v178, s[76:79], s30 offen lds
	s_mov_b32 m0, s16
	s_nop 0
	buffer_load_dwordx4 v210, s[76:79], s30 offen lds
	s_waitcnt vmcnt(8)
	s_waitcnt lgkmcnt(0)
	s_barrier
	s_setprio 1
	s_waitcnt lgkmcnt(7)
	s_waitcnt lgkmcnt(0)
	v_mfma_f32_16x16x32_bf16 v[94:97], v[130:133], v[162:165], v[94:97]
	v_mfma_f32_16x16x32_bf16 v[78:81], v[138:141], v[162:165], v[78:81]
	v_mfma_f32_16x16x32_bf16 v[70:73], v[138:141], v[182:185], v[70:73]
	v_mfma_f32_16x16x32_bf16 v[86:89], v[130:133], v[182:185], v[86:89]
	v_mfma_f32_16x16x32_bf16 v[82:85], v[130:133], v[190:193], v[82:85]
	v_mfma_f32_16x16x32_bf16 v[66:69], v[138:141], v[190:193], v[66:69]
	v_mfma_f32_16x16x32_bf16 v[74:77], v[138:141], v[198:201], v[74:77]
	v_mfma_f32_16x16x32_bf16 v[90:93], v[130:133], v[198:201], v[90:93]
	v_mfma_f32_16x16x32_bf16 v[94:97], v[134:137], v[170:173], v[94:97]
	v_mfma_f32_16x16x32_bf16 v[78:81], v[142:145], v[170:173], v[78:81]
	v_mfma_f32_16x16x32_bf16 v[70:73], v[142:145], v[186:189], v[70:73]
	v_mfma_f32_16x16x32_bf16 v[86:89], v[134:137], v[186:189], v[86:89]
	v_mfma_f32_16x16x32_bf16 v[82:85], v[134:137], v[194:197], v[82:85]
	v_mfma_f32_16x16x32_bf16 v[66:69], v[142:145], v[194:197], v[66:69]
	v_mfma_f32_16x16x32_bf16 v[74:77], v[142:145], v[202:205], v[74:77]
	v_mfma_f32_16x16x32_bf16 v[90:93], v[134:137], v[202:205], v[90:93]
	s_setprio 0
	s_setprio 1
	v_mfma_f32_16x16x32_bf16 v[30:33], v[146:149], v[162:165], v[30:33]
	v_mfma_f32_16x16x32_bf16 v[14:17], v[154:157], v[162:165], v[14:17]
	v_mfma_f32_16x16x32_bf16 v[10:13], v[154:157], v[182:185], v[10:13]
	v_mfma_f32_16x16x32_bf16 v[22:25], v[146:149], v[182:185], v[22:25]
	v_mfma_f32_16x16x32_bf16 v[18:21], v[146:149], v[190:193], v[18:21]
	v_mfma_f32_16x16x32_bf16 v[2:5], v[154:157], v[190:193], v[2:5]
	v_mfma_f32_16x16x32_bf16 v[6:9], v[154:157], v[198:201], v[6:9]
	v_mfma_f32_16x16x32_bf16 v[26:29], v[146:149], v[198:201], v[26:29]
	v_mfma_f32_16x16x32_bf16 v[30:33], v[150:153], v[170:173], v[30:33]
	v_mfma_f32_16x16x32_bf16 v[14:17], v[158:161], v[170:173], v[14:17]
	v_mfma_f32_16x16x32_bf16 v[10:13], v[158:161], v[186:189], v[10:13]
	v_mfma_f32_16x16x32_bf16 v[22:25], v[150:153], v[186:189], v[22:25]
	v_mfma_f32_16x16x32_bf16 v[18:21], v[150:153], v[194:197], v[18:21]
	v_mfma_f32_16x16x32_bf16 v[2:5], v[158:161], v[194:197], v[2:5]
	v_mfma_f32_16x16x32_bf16 v[6:9], v[158:161], v[202:205], v[6:9]
	v_mfma_f32_16x16x32_bf16 v[26:29], v[150:153], v[202:205], v[26:29]
	s_setprio 0
	s_barrier
	s_add_i32 s29, s29, 2
	s_addk_i32 s7, 0x100
	s_addk_i32 s28, 0x100
	s_cmp_gt_u32 s29, 29
	s_cbranch_scc0 .LBB0_437
	s_and_b64 vcc, exec, s[84:85]
	s_cbranch_vccz .LBB0_440
	s_barrier

; #define PG8_STAGEX(rs, bufoff, soff, voff) do { _Pragma("unroll") for (int _i = 0; _i < 2; ++_i) \
;         __builtin_amdgcn_raw_ptr_buffer_load_lds(rs, (LAS unsigned*)(lds + (bufoff) + ldsw + _i * 8192), 16, (voff)[_i], (soff), 0, 0); } while (0)
; #define PG8_LDA(dst, b, h) do { _Pragma("unroll") for (int m = 0; m < 4; ++m) _Pragma("unroll") for (int k = 0; k < 2; ++k) dst[m][k] = *(const LAS bf16x8*)(lds + PG8_SA(b, h) + aoff + m * 2048 + k * 1024); } while (0)
; #define PG8_LDB(dst, b, h) do { _Pragma("unroll") for (int n = 0; n < 2; ++n) _Pragma("unroll") for (int k = 0; k < 2; ++k) dst[n][k] = *(const LAS bf16x8*)(lds + PG8_SB(b, h) + boff + n * 2048 + k * 1024); } while (0)
; #define PG8_WAIT_V(n) asm volatile("s_waitcnt vmcnt(" #n ")" ::: "memory")
; #define PG8_WAIT_L(n) asm volatile("s_waitcnt lgkmcnt(" #n ")" ::: "memory")
; #define PG8_BAR __builtin_amdgcn_s_barrier()
; #define PG8_SCHED __builtin_amdgcn_sched_barrier(0)
;     ...
;                 if (w0) { PG8_LDB(B0, 0, 0); PG8_LDB(B1, 0, 1); PG8_SCHED; PG8_LDA(At, 0, 0); }
;                 PG8_WAIT_L(0); PG8_BAR; if (w0) { PG8_MMA(0, 0, At, B0); PG8_MMA(0, 1, At, B1); } PG8_BAR; PG8_SCHED;
;                 PG8_STAGEX(rsB, PG8_SB(0, 0), b2, voffB); PG8_STAGEX(rsB, PG8_SB(0, 1), b2 + hstepB, voffB); PG8_STAGEX(rsA, PG8_SA(0, 0), a2, voffA);
;                 PG8_WAIT_V(6); PG8_BAR; PG8_BAR; PG8_SCHED;
.LBB0_542:
	v_add_u32_e32 v73, 0x10000, v71
	ds_read_b128 v[74:77], v73
	ds_read_b128 v[78:81], v73 offset:1024
	ds_read_b128 v[82:85], v73 offset:2048
	ds_read_b128 v[86:89], v73 offset:3072
	v_add_u32_e32 v73, 0x14000, v71
	ds_read_b128 v[90:93], v73
	ds_read_b128 v[94:97], v73 offset:1024
	ds_read_b128 v[98:101], v73 offset:2048
	ds_read_b128 v[110:113], v73 offset:3072
	s_cmp_lg_u32 s26, 28
	s_cselect_b32 s27, s25, 0
	s_add_i32 s28, s27, s17
	s_or_b32 s29, s28, 0x80
	s_add_i32 s27, s27, s10
	ds_read_b128 v[114:117], v72
	ds_read_b128 v[118:121], v72 offset:1024
	ds_read_b128 v[122:125], v72 offset:2048
	ds_read_b128 v[126:129], v72 offset:3072
	ds_read_b128 v[130:133], v72 offset:4096
	ds_read_b128 v[134:137], v72 offset:5120
	ds_read_b128 v[138:141], v72 offset:6144
	ds_read_b128 v[142:145], v72 offset:7168
	s_waitcnt lgkmcnt(0)
	s_barrier
	s_setprio 1
	s_waitcnt lgkmcnt(7)
	s_waitcnt lgkmcnt(0)
	v_mfma_f32_16x16x32_bf16 v[62:65], v[74:77], v[114:117], v[62:65]
	v_mfma_f32_16x16x32_bf16 v[46:49], v[82:85], v[114:117], v[46:49]
	v_mfma_f32_16x16x32_bf16 v[38:41], v[82:85], v[122:125], v[38:41]
	v_mfma_f32_16x16x32_bf16 v[54:57], v[74:77], v[122:125], v[54:57]
	v_mfma_f32_16x16x32_bf16 v[50:53], v[74:77], v[130:133], v[50:53]
	v_mfma_f32_16x16x32_bf16 v[34:37], v[82:85], v[130:133], v[34:37]
	v_mfma_f32_16x16x32_bf16 v[42:45], v[82:85], v[138:141], v[42:45]
	v_mfma_f32_16x16x32_bf16 v[58:61], v[74:77], v[138:141], v[58:61]
	v_mfma_f32_16x16x32_bf16 v[62:65], v[78:81], v[118:121], v[62:65]
	v_mfma_f32_16x16x32_bf16 v[46:49], v[86:89], v[118:121], v[46:49]
	v_mfma_f32_16x16x32_bf16 v[38:41], v[86:89], v[126:129], v[38:41]
	v_mfma_f32_16x16x32_bf16 v[54:57], v[78:81], v[126:129], v[54:57]
	v_mfma_f32_16x16x32_bf16 v[50:53], v[78:81], v[134:137], v[50:53]
	v_mfma_f32_16x16x32_bf16 v[34:37], v[86:89], v[134:137], v[34:37]
	v_mfma_f32_16x16x32_bf16 v[42:45], v[86:89], v[142:145], v[42:45]
	v_mfma_f32_16x16x32_bf16 v[58:61], v[78:81], v[142:145], v[58:61]
	s_setprio 0
	s_setprio 1
	v_mfma_f32_16x16x32_bf16 v[30:33], v[90:93], v[114:117], v[30:33]
	v_mfma_f32_16x16x32_bf16 v[14:17], v[98:101], v[114:117], v[14:17]
	v_mfma_f32_16x16x32_bf16 v[10:13], v[98:101], v[122:125], v[10:13]
	v_mfma_f32_16x16x32_bf16 v[22:25], v[90:93], v[122:125], v[22:25]
	v_mfma_f32_16x16x32_bf16 v[18:21], v[90:93], v[130:133], v[18:21]
	v_mfma_f32_16x16x32_bf16 v[2:5], v[98:101], v[130:133], v[2:5]
	v_mfma_f32_16x16x32_bf16 v[6:9], v[98:101], v[138:141], v[6:9]
	v_mfma_f32_16x16x32_bf16 v[26:29], v[90:93], v[138:141], v[26:29]
	v_mfma_f32_16x16x32_bf16 v[30:33], v[94:97], v[118:121], v[30:33]
	v_mfma_f32_16x16x32_bf16 v[14:17], v[110:113], v[118:121], v[14:17]
	v_mfma_f32_16x16x32_bf16 v[10:13], v[110:113], v[126:129], v[10:13]
	v_mfma_f32_16x16x32_bf16 v[22:25], v[94:97], v[126:129], v[22:25]
	v_mfma_f32_16x16x32_bf16 v[18:21], v[94:97], v[134:137], v[18:21]
	v_mfma_f32_16x16x32_bf16 v[2:5], v[110:113], v[134:137], v[2:5]
	v_mfma_f32_16x16x32_bf16 v[6:9], v[110:113], v[142:145], v[6:9]
	v_mfma_f32_16x16x32_bf16 v[26:29], v[94:97], v[142:145], v[26:29]
	s_setprio 0
	s_barrier
	s_mov_b32 m0, s12
	s_mov_b32 s58, s78
	s_mov_b32 s59, s79
	buffer_load_dwordx4 v67, s[56:59], s27 offen lds
	s_mov_b32 m0, s13
	s_add_i32 s30, s27, 0x80000
	buffer_load_dwordx4 v69, s[56:59], s27 offen lds
	s_mov_b32 m0, s14
	s_nop 0
	buffer_load_dwordx4 v67, s[56:59], s30 offen lds
	s_mov_b32 m0, s15
	s_nop 0
	buffer_load_dwordx4 v69, s[56:59], s30 offen lds
	s_mov_b32 m0, s11
	s_nop 0
	buffer_load_dwordx4 v66, s[76:79], s28 offen lds
	s_mov_b32 m0, s18
	s_nop 0
	buffer_load_dwordx4 v68, s[76:79], s28 offen lds
	s_waitcnt vmcnt(6)
	s_barrier
	s_barrier
; #define PG8_STAGEX(rs, bufoff, soff, voff) do { _Pragma("unroll") for (int _i = 0; _i < 2; ++_i) \
;         __builtin_amdgcn_raw_ptr_buffer_load_lds(rs, (LAS unsigned*)(lds + (bufoff) + ldsw + _i * 8192), 16, (voff)[_i], (soff), 0, 0); } while (0)
; #define PG8_LDA(dst, b, h) do { _Pragma("unroll") for (int m = 0; m < 4; ++m) _Pragma("unroll") for (int k = 0; k < 2; ++k) dst[m][k] = *(const LAS bf16x8*)(lds + PG8_SA(b, h) + aoff + m * 2048 + k * 1024); } while (0)
; #define PG8_LDB(dst, b, h) do { _Pragma("unroll") for (int n = 0; n < 2; ++n) _Pragma("unroll") for (int k = 0; k < 2; ++k) dst[n][k] = *(const LAS bf16x8*)(lds + PG8_SB(b, h) + boff + n * 2048 + k * 1024); } while (0)
; #define PG8_WAIT_V(n) asm volatile("s_waitcnt vmcnt(" #n ")" ::: "memory")
; #define PG8_WAIT_L(n) asm volatile("s_waitcnt lgkmcnt(" #n ")" ::: "memory")
; #define PG8_BAR __builtin_amdgcn_s_barrier()
; #define PG8_SCHED __builtin_amdgcn_sched_barrier(0)
;     ...
;                 if (w0) { PG8_LDB(B0, 1, 0); PG8_LDB(B1, 1, 1); PG8_SCHED; PG8_LDA(At, 1, 0); }
;                 PG8_WAIT_L(0); PG8_BAR; if (w0) { PG8_MMA(0, 0, At, B0); PG8_MMA(0, 1, At, B1); } PG8_BAR; PG8_SCHED;
;                 PG8_STAGEX(rsB, PG8_SB(1, 0), b3, voffB); PG8_STAGEX(rsB, PG8_SB(1, 1), b3 + hstepB, voffB); PG8_STAGEX(rsA, PG8_SA(1, 0), a3, voffA);
;                 PG8_WAIT_V(6); PG8_BAR; PG8_BAR; PG8_SCHED;
;             }
	v_add_u32_e32 v73, 0x18000, v71
	ds_read_b128 v[74:77], v73
	ds_read_b128 v[78:81], v73 offset:1024
	ds_read_b128 v[82:85], v73 offset:2048
	ds_read_b128 v[86:89], v73 offset:3072
	v_add_u32_e32 v73, 0x1c000, v71
	ds_read_b128 v[90:93], v73
	ds_read_b128 v[94:97], v73 offset:1024
	ds_read_b128 v[98:101], v73 offset:2048
	ds_read_b128 v[110:113], v73 offset:3072
	ds_read_b128 v[114:117], v72 offset:32768
	ds_read_b128 v[118:121], v72 offset:33792
	ds_read_b128 v[122:125], v72 offset:34816
	ds_read_b128 v[126:129], v72 offset:35840
	ds_read_b128 v[130:133], v72 offset:36864
	ds_read_b128 v[134:137], v72 offset:37888
	ds_read_b128 v[138:141], v72 offset:38912
	ds_read_b128 v[142:145], v72 offset:39936
	s_waitcnt lgkmcnt(0)
	s_barrier
	s_setprio 1
	s_waitcnt lgkmcnt(7)
	s_waitcnt lgkmcnt(0)
	v_mfma_f32_16x16x32_bf16 v[62:65], v[74:77], v[114:117], v[62:65]
	v_mfma_f32_16x16x32_bf16 v[46:49], v[82:85], v[114:117], v[46:49]
	v_mfma_f32_16x16x32_bf16 v[38:41], v[82:85], v[122:125], v[38:41]
	v_mfma_f32_16x16x32_bf16 v[54:57], v[74:77], v[122:125], v[54:57]
	v_mfma_f32_16x16x32_bf16 v[50:53], v[74:77], v[130:133], v[50:53]
	v_mfma_f32_16x16x32_bf16 v[34:37], v[82:85], v[130:133], v[34:37]
	v_mfma_f32_16x16x32_bf16 v[42:45], v[82:85], v[138:141], v[42:45]
	v_mfma_f32_16x16x32_bf16 v[58:61], v[74:77], v[138:141], v[58:61]
	v_mfma_f32_16x16x32_bf16 v[62:65], v[78:81], v[118:121], v[62:65]
	v_mfma_f32_16x16x32_bf16 v[46:49], v[86:89], v[118:121], v[46:49]
	v_mfma_f32_16x16x32_bf16 v[38:41], v[86:89], v[126:129], v[38:41]
	v_mfma_f32_16x16x32_bf16 v[54:57], v[78:81], v[126:129], v[54:57]
	v_mfma_f32_16x16x32_bf16 v[50:53], v[78:81], v[134:137], v[50:53]
	v_mfma_f32_16x16x32_bf16 v[34:37], v[86:89], v[134:137], v[34:37]
	v_mfma_f32_16x16x32_bf16 v[42:45], v[86:89], v[142:145], v[42:45]
	v_mfma_f32_16x16x32_bf16 v[58:61], v[78:81], v[142:145], v[58:61]
	s_setprio 0
	s_setprio 1
	v_mfma_f32_16x16x32_bf16 v[30:33], v[90:93], v[114:117], v[30:33]
	s_or_b32 s28, s27, 0x80
	v_mfma_f32_16x16x32_bf16 v[14:17], v[98:101], v[114:117], v[14:17]
	v_mfma_f32_16x16x32_bf16 v[22:25], v[90:93], v[122:125], v[22:25]
	v_mfma_f32_16x16x32_bf16 v[10:13], v[98:101], v[122:125], v[10:13]
	v_mfma_f32_16x16x32_bf16 v[18:21], v[90:93], v[130:133], v[18:21]
	v_mfma_f32_16x16x32_bf16 v[2:5], v[98:101], v[130:133], v[2:5]
	v_mfma_f32_16x16x32_bf16 v[26:29], v[90:93], v[138:141], v[26:29]
	v_mfma_f32_16x16x32_bf16 v[6:9], v[98:101], v[138:141], v[6:9]
	v_mfma_f32_16x16x32_bf16 v[30:33], v[94:97], v[118:121], v[30:33]
	v_mfma_f32_16x16x32_bf16 v[14:17], v[110:113], v[118:121], v[14:17]
	v_mfma_f32_16x16x32_bf16 v[22:25], v[94:97], v[126:129], v[22:25]
	v_mfma_f32_16x16x32_bf16 v[10:13], v[110:113], v[126:129], v[10:13]
	v_mfma_f32_16x16x32_bf16 v[18:21], v[94:97], v[134:137], v[18:21]
	v_mfma_f32_16x16x32_bf16 v[2:5], v[110:113], v[134:137], v[2:5]
	v_mfma_f32_16x16x32_bf16 v[26:29], v[94:97], v[142:145], v[26:29]
	v_mfma_f32_16x16x32_bf16 v[6:9], v[110:113], v[142:145], v[6:9]
	s_setprio 0
	s_barrier
	s_mov_b32 m0, s19
	s_add_i32 s27, s27, 0x80080
	buffer_load_dwordx4 v67, s[56:59], s28 offen lds
	s_mov_b32 m0, s20
	s_nop 0
	buffer_load_dwordx4 v69, s[56:59], s28 offen lds
	s_mov_b32 m0, s23
	s_nop 0
	buffer_load_dwordx4 v67, s[56:59], s27 offen lds
	s_mov_b32 m0, s24
	s_nop 0
	buffer_load_dwordx4 v69, s[56:59], s27 offen lds
	s_mov_b32 m0, s21
	s_nop 0
	buffer_load_dwordx4 v66, s[76:79], s29 offen lds
	s_mov_b32 m0, s22
	s_nop 0
	buffer_load_dwordx4 v68, s[76:79], s29 offen lds
	s_waitcnt vmcnt(6)
	s_barrier
	s_barrier
	s_addk_i32 s25, 0x100
	s_add_i32 s26, s26, 2
	s_cmp_gt_u32 s26, 29
	s_cbranch_scc0 .LBB0_542
	s_cmpk_lt_u32 s1, 0x100
	s_cbranch_scc0 .LBB0_545
	s_barrier

; #define PG8_STAGEX(rs, bufoff, soff, voff) do { _Pragma("unroll") for (int _i = 0; _i < 2; ++_i) \
;         __builtin_amdgcn_raw_ptr_buffer_load_lds(rs, (LAS unsigned*)(lds + (bufoff) + ldsw + _i * 8192), 16, (voff)[_i], (soff), 0, 0); } while (0)
; #define PG8_LDA(dst, b, h) do { _Pragma("unroll") for (int m = 0; m < 4; ++m) _Pragma("unroll") for (int k = 0; k < 2; ++k) dst[m][k] = *(const LAS bf16x8*)(lds + PG8_SA(b, h) + aoff + m * 2048 + k * 1024); } while (0)
; #define PG8_LDB(dst, b, h) do { _Pragma("unroll") for (int n = 0; n < 2; ++n) _Pragma("unroll") for (int k = 0; k < 2; ++k) dst[n][k] = *(const LAS bf16x8*)(lds + PG8_SB(b, h) + boff + n * 2048 + k * 1024); } while (0)
; #define PG8_WAIT_V(n) asm volatile("s_waitcnt vmcnt(" #n ")" ::: "memory")
; #define PG8_WAIT_L(n) asm volatile("s_waitcnt lgkmcnt(" #n ")" ::: "memory")
; #define PG8_BAR __builtin_amdgcn_s_barrier()
; #define PG8_SCHED __builtin_amdgcn_sched_barrier(0)
;     ...
;             PG8_LDB(B0, 0, 0); PG8_LDB(B1, 0, 1); PG8_SCHED; PG8_LDA(At, 0, 0); PG8_STAGEX(rsA, PG8_SA(1, 1), a1 + hstepA, voffA);
;             PG8_WAIT_V(8); PG8_WAIT_L(0); PG8_BAR; PG8_MMA(0, 0, At, B0); PG8_MMA(0, 1, At, B1); PG8_BAR; PG8_SCHED;
;             PG8_LDA(At, 0, 1); PG8_STAGEX(rsB, PG8_SB(0, 0), b2, voffB); PG8_STAGEX(rsB, PG8_SB(0, 1), b2 + hstepB, voffB); PG8_STAGEX(rsA, PG8_SA(0, 0), a2, voffA);
;             PG8_WAIT_V(8); PG8_WAIT_L(0); PG8_BAR; PG8_MMA(1, 0, At, B0); PG8_MMA(1, 1, At, B1); PG8_BAR; PG8_SCHED;
.LBB0_788:
	v_add_u32_e32 v150, 0x10000, v153
	ds_read_b128 v[138:141], v150
	ds_read_b128 v[142:145], v150 offset:1024
	ds_read_b128 v[146:149], v150 offset:2048
	ds_read_b128 v[156:159], v150 offset:3072
	v_add_u32_e32 v150, 0x14000, v153
	ds_read_b128 v[160:163], v150
	ds_read_b128 v[164:167], v150 offset:1024
	ds_read_b128 v[182:185], v150 offset:2048
	ds_read_b128 v[186:189], v150 offset:3072
	s_add_i32 s48, s31, 0xfffc0080
	s_cmp_eq_u32 s55, s47
	s_cselect_b32 s50, s7, s48
	s_cselect_b32 s49, s30, s46
	s_add_i32 s48, s50, 0x80
	s_mov_b32 m0, s35
	ds_read_b128 v[190:193], v154
	ds_read_b128 v[194:197], v154 offset:1024
	ds_read_b128 v[198:201], v154 offset:2048
	ds_read_b128 v[202:205], v154 offset:3072
	ds_read_b128 v[206:209], v154 offset:4096
	ds_read_b128 v[210:213], v154 offset:5120
	ds_read_b128 v[214:217], v154 offset:6144
	ds_read_b128 v[218:221], v154 offset:7168
	buffer_load_dwordx4 v130, s[76:79], s31 offen lds
	s_mov_b32 m0, s82
	s_nop 0
	buffer_load_dwordx4 v134, s[76:79], s31 offen lds
	s_waitcnt vmcnt(8)
	s_waitcnt lgkmcnt(0)
	s_barrier
	s_setprio 1
	s_waitcnt lgkmcnt(7)
	s_waitcnt lgkmcnt(0)
	v_mfma_f32_16x16x32_bf16 v[126:129], v[190:193], v[138:141], v[126:129]
	v_mfma_f32_16x16x32_bf16 v[62:65], v[190:193], v[146:149], v[62:65]
	v_mfma_f32_16x16x32_bf16 v[54:57], v[198:201], v[146:149], v[54:57]
	v_mfma_f32_16x16x32_bf16 v[118:121], v[198:201], v[138:141], v[118:121]
	v_mfma_f32_16x16x32_bf16 v[110:113], v[206:209], v[138:141], v[110:113]
	v_mfma_f32_16x16x32_bf16 v[46:49], v[206:209], v[146:149], v[46:49]
	v_mfma_f32_16x16x32_bf16 v[38:41], v[214:217], v[146:149], v[38:41]
	v_mfma_f32_16x16x32_bf16 v[102:105], v[214:217], v[138:141], v[102:105]
	v_mfma_f32_16x16x32_bf16 v[126:129], v[194:197], v[142:145], v[126:129]
	v_mfma_f32_16x16x32_bf16 v[62:65], v[194:197], v[156:159], v[62:65]
	v_mfma_f32_16x16x32_bf16 v[54:57], v[202:205], v[156:159], v[54:57]
	v_mfma_f32_16x16x32_bf16 v[118:121], v[202:205], v[142:145], v[118:121]
	v_mfma_f32_16x16x32_bf16 v[110:113], v[210:213], v[142:145], v[110:113]
	v_mfma_f32_16x16x32_bf16 v[46:49], v[210:213], v[156:159], v[46:49]
	v_mfma_f32_16x16x32_bf16 v[38:41], v[218:221], v[156:159], v[38:41]
	v_mfma_f32_16x16x32_bf16 v[102:105], v[218:221], v[142:145], v[102:105]
	s_setprio 0
	s_setprio 1
	v_mfma_f32_16x16x32_bf16 v[122:125], v[190:193], v[160:163], v[122:125]
	v_mfma_f32_16x16x32_bf16 v[58:61], v[190:193], v[182:185], v[58:61]
	v_mfma_f32_16x16x32_bf16 v[50:53], v[198:201], v[182:185], v[50:53]
	v_mfma_f32_16x16x32_bf16 v[114:117], v[198:201], v[160:163], v[114:117]
	v_mfma_f32_16x16x32_bf16 v[106:109], v[206:209], v[160:163], v[106:109]
	v_mfma_f32_16x16x32_bf16 v[42:45], v[206:209], v[182:185], v[42:45]
	v_mfma_f32_16x16x32_bf16 v[34:37], v[214:217], v[182:185], v[34:37]
	v_mfma_f32_16x16x32_bf16 v[98:101], v[214:217], v[160:163], v[98:101]
	v_mfma_f32_16x16x32_bf16 v[122:125], v[194:197], v[164:167], v[122:125]
	v_mfma_f32_16x16x32_bf16 v[58:61], v[194:197], v[186:189], v[58:61]
	v_mfma_f32_16x16x32_bf16 v[50:53], v[202:205], v[186:189], v[50:53]
	v_mfma_f32_16x16x32_bf16 v[114:117], v[202:205], v[164:167], v[114:117]
	v_mfma_f32_16x16x32_bf16 v[106:109], v[210:213], v[164:167], v[106:109]
	v_mfma_f32_16x16x32_bf16 v[42:45], v[210:213], v[186:189], v[42:45]
	v_mfma_f32_16x16x32_bf16 v[34:37], v[218:221], v[186:189], v[34:37]
	v_mfma_f32_16x16x32_bf16 v[98:101], v[218:221], v[164:167], v[98:101]
	s_setprio 0
	s_barrier
	s_mov_b32 m0, s15
	s_mov_b32 s86, s78
	s_mov_b32 s87, s79
	ds_read_b128 v[190:193], v154 offset:16384
	ds_read_b128 v[194:197], v154 offset:17408
	ds_read_b128 v[198:201], v154 offset:18432
	ds_read_b128 v[202:205], v154 offset:19456
	ds_read_b128 v[206:209], v154 offset:20480
	ds_read_b128 v[210:213], v154 offset:21504
	ds_read_b128 v[214:217], v154 offset:22528
	ds_read_b128 v[218:221], v154 offset:23552
	buffer_load_dwordx4 v132, s[84:87], s49 offen lds
	s_mov_b32 m0, s16
	s_add_i32 s51, s49, 0x8000
	buffer_load_dwordx4 v136, s[84:87], s49 offen lds
	s_mov_b32 m0, s17
	s_nop 0
	buffer_load_dwordx4 v132, s[84:87], s51 offen lds
	s_mov_b32 m0, s18
	s_nop 0
	buffer_load_dwordx4 v136, s[84:87], s51 offen lds
	s_mov_b32 m0, s14
	s_nop 0
	buffer_load_dwordx4 v130, s[76:79], s50 offen lds
	s_mov_b32 m0, s19
	s_nop 0
	buffer_load_dwordx4 v134, s[76:79], s50 offen lds
	s_waitcnt vmcnt(8)
	s_waitcnt lgkmcnt(0)
	s_barrier
	s_setprio 1
	s_waitcnt lgkmcnt(7)
	s_waitcnt lgkmcnt(0)
	v_mfma_f32_16x16x32_bf16 v[94:97], v[190:193], v[138:141], v[94:97]
	v_mfma_f32_16x16x32_bf16 v[30:33], v[190:193], v[146:149], v[30:33]
	v_mfma_f32_16x16x32_bf16 v[22:25], v[198:201], v[146:149], v[22:25]
	v_mfma_f32_16x16x32_bf16 v[86:89], v[198:201], v[138:141], v[86:89]
	v_mfma_f32_16x16x32_bf16 v[78:81], v[206:209], v[138:141], v[78:81]
	v_mfma_f32_16x16x32_bf16 v[14:17], v[206:209], v[146:149], v[14:17]
	v_mfma_f32_16x16x32_bf16 v[6:9], v[214:217], v[146:149], v[6:9]
	v_mfma_f32_16x16x32_bf16 v[70:73], v[214:217], v[138:141], v[70:73]
	v_mfma_f32_16x16x32_bf16 v[94:97], v[194:197], v[142:145], v[94:97]
	v_mfma_f32_16x16x32_bf16 v[30:33], v[194:197], v[156:159], v[30:33]
	v_mfma_f32_16x16x32_bf16 v[22:25], v[202:205], v[156:159], v[22:25]
	v_mfma_f32_16x16x32_bf16 v[86:89], v[202:205], v[142:145], v[86:89]
	v_mfma_f32_16x16x32_bf16 v[78:81], v[210:213], v[142:145], v[78:81]
	v_mfma_f32_16x16x32_bf16 v[14:17], v[210:213], v[156:159], v[14:17]
	v_mfma_f32_16x16x32_bf16 v[6:9], v[218:221], v[156:159], v[6:9]
	v_mfma_f32_16x16x32_bf16 v[70:73], v[218:221], v[142:145], v[70:73]
	s_setprio 0
	s_setprio 1
	v_mfma_f32_16x16x32_bf16 v[90:93], v[190:193], v[160:163], v[90:93]
	v_mfma_f32_16x16x32_bf16 v[26:29], v[190:193], v[182:185], v[26:29]
	v_mfma_f32_16x16x32_bf16 v[18:21], v[198:201], v[182:185], v[18:21]
	v_mfma_f32_16x16x32_bf16 v[82:85], v[198:201], v[160:163], v[82:85]
	v_mfma_f32_16x16x32_bf16 v[74:77], v[206:209], v[160:163], v[74:77]
	v_mfma_f32_16x16x32_bf16 v[10:13], v[206:209], v[182:185], v[10:13]
	v_mfma_f32_16x16x32_bf16 v[2:5], v[214:217], v[182:185], v[2:5]
	v_mfma_f32_16x16x32_bf16 v[66:69], v[214:217], v[160:163], v[66:69]
	v_mfma_f32_16x16x32_bf16 v[90:93], v[194:197], v[164:167], v[90:93]
	v_mfma_f32_16x16x32_bf16 v[26:29], v[194:197], v[186:189], v[26:29]
	v_mfma_f32_16x16x32_bf16 v[18:21], v[202:205], v[186:189], v[18:21]
	v_mfma_f32_16x16x32_bf16 v[82:85], v[202:205], v[164:167], v[82:85]
	v_mfma_f32_16x16x32_bf16 v[74:77], v[210:213], v[164:167], v[74:77]
	v_mfma_f32_16x16x32_bf16 v[10:13], v[210:213], v[186:189], v[10:13]
	v_mfma_f32_16x16x32_bf16 v[2:5], v[218:221], v[186:189], v[2:5]
	v_mfma_f32_16x16x32_bf16 v[66:69], v[218:221], v[164:167], v[66:69]
	s_setprio 0
	s_barrier
; #define PG8_STAGEX(rs, bufoff, soff, voff) do { _Pragma("unroll") for (int _i = 0; _i < 2; ++_i) \
;         __builtin_amdgcn_raw_ptr_buffer_load_lds(rs, (LAS unsigned*)(lds + (bufoff) + ldsw + _i * 8192), 16, (voff)[_i], (soff), 0, 0); } while (0)
; #define PG8_LDA(dst, b, h) do { _Pragma("unroll") for (int m = 0; m < 4; ++m) _Pragma("unroll") for (int k = 0; k < 2; ++k) dst[m][k] = *(const LAS bf16x8*)(lds + PG8_SA(b, h) + aoff + m * 2048 + k * 1024); } while (0)
; #define PG8_LDB(dst, b, h) do { _Pragma("unroll") for (int n = 0; n < 2; ++n) _Pragma("unroll") for (int k = 0; k < 2; ++k) dst[n][k] = *(const LAS bf16x8*)(lds + PG8_SB(b, h) + boff + n * 2048 + k * 1024); } while (0)
; #define PG8_WAIT_V(n) asm volatile("s_waitcnt vmcnt(" #n ")" ::: "memory")
; #define PG8_WAIT_L(n) asm volatile("s_waitcnt lgkmcnt(" #n ")" ::: "memory")
; #define PG8_BAR __builtin_amdgcn_s_barrier()
; #define PG8_SCHED __builtin_amdgcn_sched_barrier(0)
;     ...
;             PG8_LDB(B0, 1, 0); PG8_LDB(B1, 1, 1); PG8_SCHED; PG8_LDA(At, 1, 0); PG8_STAGEX(rsA, PG8_SA(0, 1), a2 + hstepA, voffA);
;             PG8_WAIT_V(8); PG8_WAIT_L(0); PG8_BAR; PG8_MMA(0, 0, At, B0); PG8_MMA(0, 1, At, B1); PG8_BAR; PG8_SCHED;
;             PG8_LDA(At, 1, 1); PG8_STAGEX(rsB, PG8_SB(1, 0), b3, voffB); PG8_STAGEX(rsB, PG8_SB(1, 1), b3 + hstepB, voffB); PG8_STAGEX(rsA, PG8_SA(1, 0), a3, voffA);
;             PG8_WAIT_V(8); PG8_WAIT_L(0); PG8_BAR; PG8_MMA(1, 0, At, B0); PG8_MMA(1, 1, At, B1); PG8_BAR; PG8_SCHED;
;         }
	v_add_u32_e32 v150, 0x18000, v153
	ds_read_b128 v[138:141], v150
	ds_read_b128 v[142:145], v150 offset:1024
	ds_read_b128 v[146:149], v150 offset:2048
	ds_read_b128 v[156:159], v150 offset:3072
	v_add_u32_e32 v150, 0x1c000, v153
	ds_read_b128 v[160:163], v150
	ds_read_b128 v[164:167], v150 offset:1024
	ds_read_b128 v[182:185], v150 offset:2048
	ds_read_b128 v[186:189], v150 offset:3072
	s_add_i32 s50, s50, 0x40000
	s_mov_b32 m0, s20
	ds_read_b128 v[190:193], v154 offset:32768
	ds_read_b128 v[194:197], v154 offset:33792
	ds_read_b128 v[198:201], v154 offset:34816
	ds_read_b128 v[202:205], v154 offset:35840
	ds_read_b128 v[206:209], v154 offset:36864
	ds_read_b128 v[210:213], v154 offset:37888
	ds_read_b128 v[214:217], v154 offset:38912
	ds_read_b128 v[218:221], v154 offset:39936
	buffer_load_dwordx4 v130, s[76:79], s50 offen lds
	s_mov_b32 m0, s21
	s_nop 0
	buffer_load_dwordx4 v134, s[76:79], s50 offen lds
	s_waitcnt vmcnt(8)
	s_waitcnt lgkmcnt(0)
	s_barrier
	s_setprio 1
	s_waitcnt lgkmcnt(7)
	s_waitcnt lgkmcnt(0)
	v_mfma_f32_16x16x32_bf16 v[126:129], v[190:193], v[138:141], v[126:129]
	v_mfma_f32_16x16x32_bf16 v[62:65], v[190:193], v[146:149], v[62:65]
	v_mfma_f32_16x16x32_bf16 v[54:57], v[198:201], v[146:149], v[54:57]
	v_mfma_f32_16x16x32_bf16 v[118:121], v[198:201], v[138:141], v[118:121]
	v_mfma_f32_16x16x32_bf16 v[110:113], v[206:209], v[138:141], v[110:113]
	v_mfma_f32_16x16x32_bf16 v[46:49], v[206:209], v[146:149], v[46:49]
	v_mfma_f32_16x16x32_bf16 v[38:41], v[214:217], v[146:149], v[38:41]
	v_mfma_f32_16x16x32_bf16 v[102:105], v[214:217], v[138:141], v[102:105]
	v_mfma_f32_16x16x32_bf16 v[126:129], v[194:197], v[142:145], v[126:129]
	v_mfma_f32_16x16x32_bf16 v[62:65], v[194:197], v[156:159], v[62:65]
	v_mfma_f32_16x16x32_bf16 v[54:57], v[202:205], v[156:159], v[54:57]
	v_mfma_f32_16x16x32_bf16 v[118:121], v[202:205], v[142:145], v[118:121]
	v_mfma_f32_16x16x32_bf16 v[110:113], v[210:213], v[142:145], v[110:113]
	v_mfma_f32_16x16x32_bf16 v[46:49], v[210:213], v[156:159], v[46:49]
	v_mfma_f32_16x16x32_bf16 v[38:41], v[218:221], v[156:159], v[38:41]
	v_mfma_f32_16x16x32_bf16 v[102:105], v[218:221], v[142:145], v[102:105]
	s_setprio 0
	s_setprio 1
	v_mfma_f32_16x16x32_bf16 v[122:125], v[190:193], v[160:163], v[122:125]
	v_mfma_f32_16x16x32_bf16 v[58:61], v[190:193], v[182:185], v[58:61]
	v_mfma_f32_16x16x32_bf16 v[50:53], v[198:201], v[182:185], v[50:53]
	v_mfma_f32_16x16x32_bf16 v[114:117], v[198:201], v[160:163], v[114:117]
	v_mfma_f32_16x16x32_bf16 v[106:109], v[206:209], v[160:163], v[106:109]
	v_mfma_f32_16x16x32_bf16 v[42:45], v[206:209], v[182:185], v[42:45]
	v_mfma_f32_16x16x32_bf16 v[34:37], v[214:217], v[182:185], v[34:37]
	v_mfma_f32_16x16x32_bf16 v[98:101], v[214:217], v[160:163], v[98:101]
	v_mfma_f32_16x16x32_bf16 v[122:125], v[194:197], v[164:167], v[122:125]
	v_mfma_f32_16x16x32_bf16 v[58:61], v[194:197], v[186:189], v[58:61]
	v_mfma_f32_16x16x32_bf16 v[50:53], v[202:205], v[186:189], v[50:53]
	v_mfma_f32_16x16x32_bf16 v[114:117], v[202:205], v[164:167], v[114:117]
	v_mfma_f32_16x16x32_bf16 v[106:109], v[210:213], v[164:167], v[106:109]
	v_mfma_f32_16x16x32_bf16 v[42:45], v[210:213], v[186:189], v[42:45]
	v_mfma_f32_16x16x32_bf16 v[34:37], v[218:221], v[186:189], v[34:37]
	v_mfma_f32_16x16x32_bf16 v[98:101], v[218:221], v[164:167], v[98:101]
	s_setprio 0
	s_barrier
	s_mov_b32 m0, s93
	s_or_b32 s50, s49, 0x80
	ds_read_b128 v[190:193], v154 offset:49152
	ds_read_b128 v[194:197], v154 offset:50176
	ds_read_b128 v[198:201], v154 offset:51200
	ds_read_b128 v[202:205], v154 offset:52224
	ds_read_b128 v[206:209], v154 offset:53248
	ds_read_b128 v[210:213], v154 offset:54272
	ds_read_b128 v[214:217], v154 offset:55296
	ds_read_b128 v[218:221], v154 offset:56320
	buffer_load_dwordx4 v132, s[84:87], s50 offen lds
	s_mov_b32 m0, s94
	s_add_i32 s49, s49, 0x8080
	buffer_load_dwordx4 v136, s[84:87], s50 offen lds
	s_mov_b32 m0, s9
	s_nop 0
	buffer_load_dwordx4 v132, s[84:87], s49 offen lds
	s_mov_b32 m0, s54
	s_nop 0
	buffer_load_dwordx4 v136, s[84:87], s49 offen lds
	s_mov_b32 m0, s95
	s_nop 0
	buffer_load_dwordx4 v130, s[76:79], s48 offen lds
	s_mov_b32 m0, s97
	s_nop 0
	buffer_load_dwordx4 v134, s[76:79], s48 offen lds
	s_waitcnt vmcnt(8)
	s_waitcnt lgkmcnt(0)
	s_barrier
	s_setprio 1
	s_waitcnt lgkmcnt(7)
	s_waitcnt lgkmcnt(0)
	v_mfma_f32_16x16x32_bf16 v[94:97], v[190:193], v[138:141], v[94:97]
	v_mfma_f32_16x16x32_bf16 v[30:33], v[190:193], v[146:149], v[30:33]
	v_mfma_f32_16x16x32_bf16 v[22:25], v[198:201], v[146:149], v[22:25]
	v_mfma_f32_16x16x32_bf16 v[86:89], v[198:201], v[138:141], v[86:89]
	v_mfma_f32_16x16x32_bf16 v[78:81], v[206:209], v[138:141], v[78:81]
	v_mfma_f32_16x16x32_bf16 v[14:17], v[206:209], v[146:149], v[14:17]
	v_mfma_f32_16x16x32_bf16 v[6:9], v[214:217], v[146:149], v[6:9]
	v_mfma_f32_16x16x32_bf16 v[70:73], v[214:217], v[138:141], v[70:73]
	v_mfma_f32_16x16x32_bf16 v[94:97], v[194:197], v[142:145], v[94:97]
	v_mfma_f32_16x16x32_bf16 v[30:33], v[194:197], v[156:159], v[30:33]
	v_mfma_f32_16x16x32_bf16 v[22:25], v[202:205], v[156:159], v[22:25]
	v_mfma_f32_16x16x32_bf16 v[86:89], v[202:205], v[142:145], v[86:89]
	v_mfma_f32_16x16x32_bf16 v[78:81], v[210:213], v[142:145], v[78:81]
	v_mfma_f32_16x16x32_bf16 v[14:17], v[210:213], v[156:159], v[14:17]
	v_mfma_f32_16x16x32_bf16 v[6:9], v[218:221], v[156:159], v[6:9]
	v_mfma_f32_16x16x32_bf16 v[70:73], v[218:221], v[142:145], v[70:73]
	s_setprio 0
	s_setprio 1
	v_mfma_f32_16x16x32_bf16 v[90:93], v[190:193], v[160:163], v[90:93]
	v_mfma_f32_16x16x32_bf16 v[26:29], v[190:193], v[182:185], v[26:29]
	v_mfma_f32_16x16x32_bf16 v[18:21], v[198:201], v[182:185], v[18:21]
	v_mfma_f32_16x16x32_bf16 v[82:85], v[198:201], v[160:163], v[82:85]
	v_mfma_f32_16x16x32_bf16 v[74:77], v[206:209], v[160:163], v[74:77]
	v_mfma_f32_16x16x32_bf16 v[10:13], v[206:209], v[182:185], v[10:13]
	v_mfma_f32_16x16x32_bf16 v[2:5], v[214:217], v[182:185], v[2:5]
	v_mfma_f32_16x16x32_bf16 v[66:69], v[214:217], v[160:163], v[66:69]
	v_mfma_f32_16x16x32_bf16 v[90:93], v[194:197], v[164:167], v[90:93]
	v_mfma_f32_16x16x32_bf16 v[26:29], v[194:197], v[186:189], v[26:29]
	v_mfma_f32_16x16x32_bf16 v[18:21], v[202:205], v[186:189], v[18:21]
	v_mfma_f32_16x16x32_bf16 v[82:85], v[202:205], v[164:167], v[82:85]
	v_mfma_f32_16x16x32_bf16 v[74:77], v[210:213], v[164:167], v[74:77]
	v_mfma_f32_16x16x32_bf16 v[10:13], v[210:213], v[186:189], v[10:13]
	v_mfma_f32_16x16x32_bf16 v[2:5], v[218:221], v[186:189], v[2:5]
	v_mfma_f32_16x16x32_bf16 v[66:69], v[218:221], v[164:167], v[66:69]
	s_setprio 0
	s_barrier
	s_add_i32 s47, s47, 2
	s_addk_i32 s31, 0x100
	s_addk_i32 s46, 0x100
	s_cmp_ge_i32 s47, s34
	s_cbranch_scc0 .LBB0_788
	s_mov_b32 s61, s96
	s_and_b64 vcc, exec, s[62:63]
	s_cbranch_vccz .LBB0_791

; #define PG8_STAGEX(rs, bufoff, soff, voff) do { _Pragma("unroll") for (int _i = 0; _i < 2; ++_i) \
;         __builtin_amdgcn_raw_ptr_buffer_load_lds(rs, (LAS unsigned*)(lds + (bufoff) + ldsw + _i * 8192), 16, (voff)[_i], (soff), 0, 0); } while (0)
; #define PG8_LDA(dst, b, h) do { _Pragma("unroll") for (int m = 0; m < 4; ++m) _Pragma("unroll") for (int k = 0; k < 2; ++k) dst[m][k] = *(const LAS bf16x8*)(lds + PG8_SA(b, h) + aoff + m * 2048 + k * 1024); } while (0)
; #define PG8_LDB(dst, b, h) do { _Pragma("unroll") for (int n = 0; n < 2; ++n) _Pragma("unroll") for (int k = 0; k < 2; ++k) dst[n][k] = *(const LAS bf16x8*)(lds + PG8_SB(b, h) + boff + n * 2048 + k * 1024); } while (0)
; #define PG8_WAIT_V(n) asm volatile("s_waitcnt vmcnt(" #n ")" ::: "memory")
; #define PG8_WAIT_L(n) asm volatile("s_waitcnt lgkmcnt(" #n ")" ::: "memory")
; #define PG8_BAR __builtin_amdgcn_s_barrier()
; #define PG8_SCHED __builtin_amdgcn_sched_barrier(0)
;     ...
;             PG8_LDB(B0, 0, 0); PG8_LDB(B1, 0, 1); PG8_SCHED; PG8_LDA(At, 0, 0); PG8_STAGEX(rsA, PG8_SA(1, 1), a1 + hstepA, voffA);
;             PG8_WAIT_V(8); PG8_WAIT_L(0); PG8_BAR; PG8_MMA(0, 0, At, B0); PG8_MMA(0, 1, At, B1); PG8_BAR; PG8_SCHED;
;             PG8_LDA(At, 0, 1); PG8_STAGEX(rsB, PG8_SB(0, 0), b2, voffB); PG8_STAGEX(rsB, PG8_SB(0, 1), b2 + hstepB, voffB); PG8_STAGEX(rsA, PG8_SA(0, 0), a2, voffA);
;             PG8_WAIT_V(8); PG8_WAIT_L(0); PG8_BAR; PG8_MMA(1, 0, At, B0); PG8_MMA(1, 1, At, B1); PG8_BAR; PG8_SCHED;
.LBB0_1274:
	v_add_u32_e32 v142, 0x10000, v157
	v_add_u32_e32 v159, 0x14000, v157
	ds_read_b128 v[130:133], v142
	ds_read_b128 v[134:137], v142 offset:1024
	ds_read_b128 v[138:141], v142 offset:2048
	ds_read_b128 v[142:145], v142 offset:3072
	ds_read_b128 v[146:149], v159
	ds_read_b128 v[164:167], v159 offset:1024
	ds_read_b128 v[168:171], v159 offset:2048
	ds_read_b128 v[182:185], v159 offset:3072
	s_add_i32 s42, s62, 0xfff80080
	s_cmp_eq_u32 s67, 28
	s_cselect_b32 s70, s30, s42
	s_cselect_b32 s69, s31, s63
	s_or_b32 s68, s70, 0x80
	s_mov_b32 m0, s29
	ds_read_b128 v[186:189], v158
	ds_read_b128 v[190:193], v158 offset:1024
	ds_read_b128 v[194:197], v158 offset:2048
	ds_read_b128 v[198:201], v158 offset:3072
	ds_read_b128 v[202:205], v158 offset:4096
	ds_read_b128 v[206:209], v158 offset:5120
	ds_read_b128 v[210:213], v158 offset:6144
	ds_read_b128 v[214:217], v158 offset:7168
	buffer_load_dwordx4 v150, s[76:79], s62 offen lds
	s_mov_b32 m0, s35
	s_nop 0
	buffer_load_dwordx4 v152, s[76:79], s62 offen lds
	s_waitcnt vmcnt(8)
	s_waitcnt lgkmcnt(0)
	s_barrier
	s_setprio 1
	s_waitcnt lgkmcnt(7)
	s_waitcnt lgkmcnt(0)
	v_mfma_f32_16x16x32_bf16 v[126:129], v[130:133], v[186:189], v[126:129]
	v_mfma_f32_16x16x32_bf16 v[122:125], v[138:141], v[186:189], v[122:125]
	v_mfma_f32_16x16x32_bf16 v[114:117], v[138:141], v[194:197], v[114:117]
	v_mfma_f32_16x16x32_bf16 v[118:121], v[130:133], v[194:197], v[118:121]
	v_mfma_f32_16x16x32_bf16 v[110:113], v[130:133], v[202:205], v[110:113]
	v_mfma_f32_16x16x32_bf16 v[106:109], v[138:141], v[202:205], v[106:109]
	v_mfma_f32_16x16x32_bf16 v[98:101], v[138:141], v[210:213], v[98:101]
	v_mfma_f32_16x16x32_bf16 v[102:105], v[130:133], v[210:213], v[102:105]
	v_mfma_f32_16x16x32_bf16 v[126:129], v[134:137], v[190:193], v[126:129]
	v_mfma_f32_16x16x32_bf16 v[122:125], v[142:145], v[190:193], v[122:125]
	v_mfma_f32_16x16x32_bf16 v[114:117], v[142:145], v[198:201], v[114:117]
	v_mfma_f32_16x16x32_bf16 v[118:121], v[134:137], v[198:201], v[118:121]
	v_mfma_f32_16x16x32_bf16 v[110:113], v[134:137], v[206:209], v[110:113]
	v_mfma_f32_16x16x32_bf16 v[106:109], v[142:145], v[206:209], v[106:109]
	v_mfma_f32_16x16x32_bf16 v[98:101], v[142:145], v[214:217], v[98:101]
	v_mfma_f32_16x16x32_bf16 v[102:105], v[134:137], v[214:217], v[102:105]
	s_setprio 0
	s_setprio 1
	v_mfma_f32_16x16x32_bf16 v[62:65], v[146:149], v[186:189], v[62:65]
	v_mfma_f32_16x16x32_bf16 v[58:61], v[168:171], v[186:189], v[58:61]
	v_mfma_f32_16x16x32_bf16 v[50:53], v[168:171], v[194:197], v[50:53]
	v_mfma_f32_16x16x32_bf16 v[54:57], v[146:149], v[194:197], v[54:57]
	v_mfma_f32_16x16x32_bf16 v[46:49], v[146:149], v[202:205], v[46:49]
	v_mfma_f32_16x16x32_bf16 v[42:45], v[168:171], v[202:205], v[42:45]
	v_mfma_f32_16x16x32_bf16 v[34:37], v[168:171], v[210:213], v[34:37]
	v_mfma_f32_16x16x32_bf16 v[38:41], v[146:149], v[210:213], v[38:41]
	v_mfma_f32_16x16x32_bf16 v[62:65], v[164:167], v[190:193], v[62:65]
	v_mfma_f32_16x16x32_bf16 v[58:61], v[182:185], v[190:193], v[58:61]
	v_mfma_f32_16x16x32_bf16 v[50:53], v[182:185], v[198:201], v[50:53]
	v_mfma_f32_16x16x32_bf16 v[54:57], v[164:167], v[198:201], v[54:57]
	v_mfma_f32_16x16x32_bf16 v[46:49], v[164:167], v[206:209], v[46:49]
	v_mfma_f32_16x16x32_bf16 v[42:45], v[182:185], v[206:209], v[42:45]
	v_mfma_f32_16x16x32_bf16 v[34:37], v[182:185], v[214:217], v[34:37]
	v_mfma_f32_16x16x32_bf16 v[38:41], v[164:167], v[214:217], v[38:41]
	s_setprio 0
	s_barrier
	s_mov_b32 m0, s16
	s_mov_b32 s42, s78
	s_mov_b32 s43, s79
	ds_read_b128 v[186:189], v158 offset:16384
	ds_read_b128 v[190:193], v158 offset:17408
	ds_read_b128 v[194:197], v158 offset:18432
	ds_read_b128 v[198:201], v158 offset:19456
	ds_read_b128 v[202:205], v158 offset:20480
	ds_read_b128 v[206:209], v158 offset:21504
	ds_read_b128 v[210:213], v158 offset:22528
	ds_read_b128 v[214:217], v158 offset:23552
	buffer_load_dwordx4 v151, s[40:43], s69 offen lds
	s_mov_b32 m0, s17
	s_add_i32 s71, s69, 0x80000
	buffer_load_dwordx4 v153, s[40:43], s69 offen lds
	s_mov_b32 m0, s18
	s_nop 0
	buffer_load_dwordx4 v151, s[40:43], s71 offen lds
	s_mov_b32 m0, s19
	s_nop 0
	buffer_load_dwordx4 v153, s[40:43], s71 offen lds
	s_mov_b32 m0, s15
	s_nop 0
	buffer_load_dwordx4 v150, s[76:79], s70 offen lds
	s_mov_b32 m0, s20
	s_nop 0
	buffer_load_dwordx4 v152, s[76:79], s70 offen lds
	s_waitcnt vmcnt(8)
	s_waitcnt lgkmcnt(0)
	s_barrier
	s_setprio 1
	s_waitcnt lgkmcnt(7)
	s_waitcnt lgkmcnt(0)
	v_mfma_f32_16x16x32_bf16 v[94:97], v[130:133], v[186:189], v[94:97]
	v_mfma_f32_16x16x32_bf16 v[90:93], v[138:141], v[186:189], v[90:93]
	v_mfma_f32_16x16x32_bf16 v[82:85], v[138:141], v[194:197], v[82:85]
	v_mfma_f32_16x16x32_bf16 v[86:89], v[130:133], v[194:197], v[86:89]
	v_mfma_f32_16x16x32_bf16 v[78:81], v[130:133], v[202:205], v[78:81]
	v_mfma_f32_16x16x32_bf16 v[74:77], v[138:141], v[202:205], v[74:77]
	v_mfma_f32_16x16x32_bf16 v[66:69], v[138:141], v[210:213], v[66:69]
	v_mfma_f32_16x16x32_bf16 v[70:73], v[130:133], v[210:213], v[70:73]
	v_mfma_f32_16x16x32_bf16 v[94:97], v[134:137], v[190:193], v[94:97]
	v_mfma_f32_16x16x32_bf16 v[90:93], v[142:145], v[190:193], v[90:93]
	v_mfma_f32_16x16x32_bf16 v[82:85], v[142:145], v[198:201], v[82:85]
	v_mfma_f32_16x16x32_bf16 v[86:89], v[134:137], v[198:201], v[86:89]
	v_mfma_f32_16x16x32_bf16 v[78:81], v[134:137], v[206:209], v[78:81]
	v_mfma_f32_16x16x32_bf16 v[74:77], v[142:145], v[206:209], v[74:77]
	v_mfma_f32_16x16x32_bf16 v[66:69], v[142:145], v[214:217], v[66:69]
	v_mfma_f32_16x16x32_bf16 v[70:73], v[134:137], v[214:217], v[70:73]
	s_setprio 0
	s_setprio 1
	v_mfma_f32_16x16x32_bf16 v[30:33], v[146:149], v[186:189], v[30:33]
	v_mfma_f32_16x16x32_bf16 v[26:29], v[168:171], v[186:189], v[26:29]
	v_mfma_f32_16x16x32_bf16 v[18:21], v[168:171], v[194:197], v[18:21]
	v_mfma_f32_16x16x32_bf16 v[22:25], v[146:149], v[194:197], v[22:25]
	v_mfma_f32_16x16x32_bf16 v[14:17], v[146:149], v[202:205], v[14:17]
	v_mfma_f32_16x16x32_bf16 v[10:13], v[168:171], v[202:205], v[10:13]
	v_mfma_f32_16x16x32_bf16 v[2:5], v[168:171], v[210:213], v[2:5]
	v_mfma_f32_16x16x32_bf16 v[6:9], v[146:149], v[210:213], v[6:9]
	v_mfma_f32_16x16x32_bf16 v[30:33], v[164:167], v[190:193], v[30:33]
	v_mfma_f32_16x16x32_bf16 v[26:29], v[182:185], v[190:193], v[26:29]
	v_mfma_f32_16x16x32_bf16 v[18:21], v[182:185], v[198:201], v[18:21]
	v_mfma_f32_16x16x32_bf16 v[22:25], v[164:167], v[198:201], v[22:25]
	v_mfma_f32_16x16x32_bf16 v[14:17], v[164:167], v[206:209], v[14:17]
	v_mfma_f32_16x16x32_bf16 v[10:13], v[182:185], v[206:209], v[10:13]
	v_mfma_f32_16x16x32_bf16 v[2:5], v[182:185], v[214:217], v[2:5]
	v_mfma_f32_16x16x32_bf16 v[6:9], v[164:167], v[214:217], v[6:9]
	s_setprio 0
	s_barrier
; #define PG8_STAGEX(rs, bufoff, soff, voff) do { _Pragma("unroll") for (int _i = 0; _i < 2; ++_i) \
;         __builtin_amdgcn_raw_ptr_buffer_load_lds(rs, (LAS unsigned*)(lds + (bufoff) + ldsw + _i * 8192), 16, (voff)[_i], (soff), 0, 0); } while (0)
; #define PG8_LDA(dst, b, h) do { _Pragma("unroll") for (int m = 0; m < 4; ++m) _Pragma("unroll") for (int k = 0; k < 2; ++k) dst[m][k] = *(const LAS bf16x8*)(lds + PG8_SA(b, h) + aoff + m * 2048 + k * 1024); } while (0)
; #define PG8_LDB(dst, b, h) do { _Pragma("unroll") for (int n = 0; n < 2; ++n) _Pragma("unroll") for (int k = 0; k < 2; ++k) dst[n][k] = *(const LAS bf16x8*)(lds + PG8_SB(b, h) + boff + n * 2048 + k * 1024); } while (0)
; #define PG8_WAIT_V(n) asm volatile("s_waitcnt vmcnt(" #n ")" ::: "memory")
; #define PG8_WAIT_L(n) asm volatile("s_waitcnt lgkmcnt(" #n ")" ::: "memory")
; #define PG8_BAR __builtin_amdgcn_s_barrier()
; #define PG8_SCHED __builtin_amdgcn_sched_barrier(0)
;     ...
;             PG8_LDB(B0, 1, 0); PG8_LDB(B1, 1, 1); PG8_SCHED; PG8_LDA(At, 1, 0); PG8_STAGEX(rsA, PG8_SA(0, 1), a2 + hstepA, voffA);
;             PG8_WAIT_V(8); PG8_WAIT_L(0); PG8_BAR; PG8_MMA(0, 0, At, B0); PG8_MMA(0, 1, At, B1); PG8_BAR; PG8_SCHED;
;             PG8_LDA(At, 1, 1); PG8_STAGEX(rsB, PG8_SB(1, 0), b3, voffB); PG8_STAGEX(rsB, PG8_SB(1, 1), b3 + hstepB, voffB); PG8_STAGEX(rsA, PG8_SA(1, 0), a3, voffA);
;             PG8_WAIT_V(8); PG8_WAIT_L(0); PG8_BAR; PG8_MMA(1, 0, At, B0); PG8_MMA(1, 1, At, B1); PG8_BAR; PG8_SCHED;
;         }
	v_add_u32_e32 v142, 0x18000, v157
	v_add_u32_e32 v159, 0x1c000, v157
	ds_read_b128 v[130:133], v142
	ds_read_b128 v[134:137], v142 offset:1024
	ds_read_b128 v[138:141], v142 offset:2048
	ds_read_b128 v[142:145], v142 offset:3072
	ds_read_b128 v[146:149], v159
	ds_read_b128 v[164:167], v159 offset:1024
	ds_read_b128 v[168:171], v159 offset:2048
	ds_read_b128 v[182:185], v159 offset:3072
	s_add_i32 s70, s70, 0x80000
	s_mov_b32 m0, s21
	ds_read_b128 v[186:189], v158 offset:32768
	ds_read_b128 v[190:193], v158 offset:33792
	ds_read_b128 v[194:197], v158 offset:34816
	ds_read_b128 v[198:201], v158 offset:35840
	ds_read_b128 v[202:205], v158 offset:36864
	ds_read_b128 v[206:209], v158 offset:37888
	ds_read_b128 v[210:213], v158 offset:38912
	ds_read_b128 v[214:217], v158 offset:39936
	buffer_load_dwordx4 v150, s[76:79], s70 offen lds
	s_mov_b32 m0, s22
	s_nop 0
	buffer_load_dwordx4 v152, s[76:79], s70 offen lds
	s_waitcnt vmcnt(8)
	s_waitcnt lgkmcnt(0)
	s_barrier
	s_setprio 1
	s_waitcnt lgkmcnt(7)
	s_waitcnt lgkmcnt(0)
	v_mfma_f32_16x16x32_bf16 v[126:129], v[130:133], v[186:189], v[126:129]
	v_mfma_f32_16x16x32_bf16 v[122:125], v[138:141], v[186:189], v[122:125]
	v_mfma_f32_16x16x32_bf16 v[114:117], v[138:141], v[194:197], v[114:117]
	v_mfma_f32_16x16x32_bf16 v[118:121], v[130:133], v[194:197], v[118:121]
	v_mfma_f32_16x16x32_bf16 v[110:113], v[130:133], v[202:205], v[110:113]
	v_mfma_f32_16x16x32_bf16 v[106:109], v[138:141], v[202:205], v[106:109]
	v_mfma_f32_16x16x32_bf16 v[98:101], v[138:141], v[210:213], v[98:101]
	v_mfma_f32_16x16x32_bf16 v[102:105], v[130:133], v[210:213], v[102:105]
	v_mfma_f32_16x16x32_bf16 v[126:129], v[134:137], v[190:193], v[126:129]
	v_mfma_f32_16x16x32_bf16 v[122:125], v[142:145], v[190:193], v[122:125]
	v_mfma_f32_16x16x32_bf16 v[114:117], v[142:145], v[198:201], v[114:117]
	v_mfma_f32_16x16x32_bf16 v[118:121], v[134:137], v[198:201], v[118:121]
	v_mfma_f32_16x16x32_bf16 v[110:113], v[134:137], v[206:209], v[110:113]
	v_mfma_f32_16x16x32_bf16 v[106:109], v[142:145], v[206:209], v[106:109]
	v_mfma_f32_16x16x32_bf16 v[98:101], v[142:145], v[214:217], v[98:101]
	v_mfma_f32_16x16x32_bf16 v[102:105], v[134:137], v[214:217], v[102:105]
	s_setprio 0
	s_setprio 1
	v_mfma_f32_16x16x32_bf16 v[62:65], v[146:149], v[186:189], v[62:65]
	v_mfma_f32_16x16x32_bf16 v[58:61], v[168:171], v[186:189], v[58:61]
	v_mfma_f32_16x16x32_bf16 v[50:53], v[168:171], v[194:197], v[50:53]
	v_mfma_f32_16x16x32_bf16 v[54:57], v[146:149], v[194:197], v[54:57]
	v_mfma_f32_16x16x32_bf16 v[46:49], v[146:149], v[202:205], v[46:49]
	v_mfma_f32_16x16x32_bf16 v[42:45], v[168:171], v[202:205], v[42:45]
	v_mfma_f32_16x16x32_bf16 v[34:37], v[168:171], v[210:213], v[34:37]
	v_mfma_f32_16x16x32_bf16 v[38:41], v[146:149], v[210:213], v[38:41]
	v_mfma_f32_16x16x32_bf16 v[62:65], v[164:167], v[190:193], v[62:65]
	v_mfma_f32_16x16x32_bf16 v[58:61], v[182:185], v[190:193], v[58:61]
	v_mfma_f32_16x16x32_bf16 v[50:53], v[182:185], v[198:201], v[50:53]
	v_mfma_f32_16x16x32_bf16 v[54:57], v[164:167], v[198:201], v[54:57]
	v_mfma_f32_16x16x32_bf16 v[46:49], v[164:167], v[206:209], v[46:49]
	v_mfma_f32_16x16x32_bf16 v[42:45], v[182:185], v[206:209], v[42:45]
	v_mfma_f32_16x16x32_bf16 v[34:37], v[182:185], v[214:217], v[34:37]
	v_mfma_f32_16x16x32_bf16 v[38:41], v[164:167], v[214:217], v[38:41]
	s_setprio 0
	s_barrier
	s_mov_b32 m0, s23
	s_or_b32 s70, s69, 0x80
	ds_read_b128 v[186:189], v158 offset:49152
	ds_read_b128 v[190:193], v158 offset:50176
	ds_read_b128 v[194:197], v158 offset:51200
	ds_read_b128 v[198:201], v158 offset:52224
	ds_read_b128 v[202:205], v158 offset:53248
	ds_read_b128 v[206:209], v158 offset:54272
	ds_read_b128 v[210:213], v158 offset:55296
	ds_read_b128 v[214:217], v158 offset:56320
	buffer_load_dwordx4 v151, s[40:43], s70 offen lds
	s_mov_b32 m0, s24
	s_add_i32 s69, s69, 0x80080
	buffer_load_dwordx4 v153, s[40:43], s70 offen lds
	s_mov_b32 m0, s27
	s_nop 0
	buffer_load_dwordx4 v151, s[40:43], s69 offen lds
	s_mov_b32 m0, s28
	s_nop 0
	buffer_load_dwordx4 v153, s[40:43], s69 offen lds
	s_mov_b32 m0, s25
	s_nop 0
	buffer_load_dwordx4 v150, s[76:79], s68 offen lds
	s_mov_b32 m0, s26
	s_nop 0
	buffer_load_dwordx4 v152, s[76:79], s68 offen lds
	s_waitcnt vmcnt(8)
	s_waitcnt lgkmcnt(0)
	s_barrier
	s_setprio 1
	s_waitcnt lgkmcnt(7)
	s_waitcnt lgkmcnt(0)
	v_mfma_f32_16x16x32_bf16 v[94:97], v[130:133], v[186:189], v[94:97]
	v_mfma_f32_16x16x32_bf16 v[90:93], v[138:141], v[186:189], v[90:93]
	v_mfma_f32_16x16x32_bf16 v[82:85], v[138:141], v[194:197], v[82:85]
	v_mfma_f32_16x16x32_bf16 v[86:89], v[130:133], v[194:197], v[86:89]
	v_mfma_f32_16x16x32_bf16 v[78:81], v[130:133], v[202:205], v[78:81]
	v_mfma_f32_16x16x32_bf16 v[74:77], v[138:141], v[202:205], v[74:77]
	v_mfma_f32_16x16x32_bf16 v[66:69], v[138:141], v[210:213], v[66:69]
	v_mfma_f32_16x16x32_bf16 v[70:73], v[130:133], v[210:213], v[70:73]
	v_mfma_f32_16x16x32_bf16 v[94:97], v[134:137], v[190:193], v[94:97]
	v_mfma_f32_16x16x32_bf16 v[90:93], v[142:145], v[190:193], v[90:93]
	v_mfma_f32_16x16x32_bf16 v[82:85], v[142:145], v[198:201], v[82:85]
	v_mfma_f32_16x16x32_bf16 v[86:89], v[134:137], v[198:201], v[86:89]
	v_mfma_f32_16x16x32_bf16 v[78:81], v[134:137], v[206:209], v[78:81]
	v_mfma_f32_16x16x32_bf16 v[74:77], v[142:145], v[206:209], v[74:77]
	v_mfma_f32_16x16x32_bf16 v[66:69], v[142:145], v[214:217], v[66:69]
	v_mfma_f32_16x16x32_bf16 v[70:73], v[134:137], v[214:217], v[70:73]
	s_setprio 0
	s_setprio 1
	v_mfma_f32_16x16x32_bf16 v[30:33], v[146:149], v[186:189], v[30:33]
	v_mfma_f32_16x16x32_bf16 v[26:29], v[168:171], v[186:189], v[26:29]
	v_mfma_f32_16x16x32_bf16 v[18:21], v[168:171], v[194:197], v[18:21]
	v_mfma_f32_16x16x32_bf16 v[22:25], v[146:149], v[194:197], v[22:25]
	v_mfma_f32_16x16x32_bf16 v[14:17], v[146:149], v[202:205], v[14:17]
	v_mfma_f32_16x16x32_bf16 v[10:13], v[168:171], v[202:205], v[10:13]
	v_mfma_f32_16x16x32_bf16 v[2:5], v[168:171], v[210:213], v[2:5]
	v_mfma_f32_16x16x32_bf16 v[6:9], v[146:149], v[210:213], v[6:9]
	v_mfma_f32_16x16x32_bf16 v[30:33], v[164:167], v[190:193], v[30:33]
	v_mfma_f32_16x16x32_bf16 v[26:29], v[182:185], v[190:193], v[26:29]
	v_mfma_f32_16x16x32_bf16 v[18:21], v[182:185], v[198:201], v[18:21]
	v_mfma_f32_16x16x32_bf16 v[22:25], v[164:167], v[198:201], v[22:25]
	v_mfma_f32_16x16x32_bf16 v[14:17], v[164:167], v[206:209], v[14:17]
	v_mfma_f32_16x16x32_bf16 v[10:13], v[182:185], v[206:209], v[10:13]
	v_mfma_f32_16x16x32_bf16 v[2:5], v[182:185], v[214:217], v[2:5]
	v_mfma_f32_16x16x32_bf16 v[6:9], v[164:167], v[214:217], v[6:9]
	s_setprio 0
	s_barrier
	s_add_i32 s67, s67, 2
	s_addk_i32 s62, 0x100
	s_addk_i32 s63, 0x100
	s_cmp_gt_u32 s67, 29
	s_cbranch_scc0 .LBB0_1274
	s_and_b64 vcc, exec, s[50:51]
	s_cbranch_vccz .LBB0_1277
	s_barrier

; #define PG8_STAGEX(rs, bufoff, soff, voff) do { _Pragma("unroll") for (int _i = 0; _i < 2; ++_i) \
;         __builtin_amdgcn_raw_ptr_buffer_load_lds(rs, (LAS unsigned*)(lds + (bufoff) + ldsw + _i * 8192), 16, (voff)[_i], (soff), 0, 0); } while (0)
; #define PG8_LDA(dst, b, h) do { _Pragma("unroll") for (int m = 0; m < 4; ++m) _Pragma("unroll") for (int k = 0; k < 2; ++k) dst[m][k] = *(const LAS bf16x8*)(lds + PG8_SA(b, h) + aoff + m * 2048 + k * 1024); } while (0)
; #define PG8_LDB(dst, b, h) do { _Pragma("unroll") for (int n = 0; n < 2; ++n) _Pragma("unroll") for (int k = 0; k < 2; ++k) dst[n][k] = *(const LAS bf16x8*)(lds + PG8_SB(b, h) + boff + n * 2048 + k * 1024); } while (0)
; #define PG8_WAIT_V(n) asm volatile("s_waitcnt vmcnt(" #n ")" ::: "memory")
; #define PG8_WAIT_L(n) asm volatile("s_waitcnt lgkmcnt(" #n ")" ::: "memory")
; #define PG8_BAR __builtin_amdgcn_s_barrier()
; #define PG8_SCHED __builtin_amdgcn_sched_barrier(0)
;     ...
;                 if (w0) { PG8_LDB(B0, 0, 0); PG8_LDB(B1, 0, 1); PG8_SCHED; PG8_LDA(At, 0, 0); }
;                 PG8_WAIT_L(0); PG8_BAR; if (w0) { PG8_MMA(0, 0, At, B0); PG8_MMA(0, 1, At, B1); } PG8_BAR; PG8_SCHED;
;                 PG8_STAGEX(rsB, PG8_SB(0, 0), b2, voffB); PG8_STAGEX(rsB, PG8_SB(0, 1), b2 + hstepB, voffB); PG8_STAGEX(rsA, PG8_SA(0, 0), a2, voffA);
;                 PG8_WAIT_V(6); PG8_BAR; PG8_BAR; PG8_SCHED;
.LBB0_1287:
	v_add_u32_e32 v86, 0x10000, v72
	v_add_u32_e32 v102, 0x14000, v72
	ds_read_b128 v[74:77], v86
	ds_read_b128 v[78:81], v86 offset:1024
	ds_read_b128 v[82:85], v86 offset:2048
	ds_read_b128 v[86:89], v86 offset:3072
	ds_read_b128 v[90:93], v102
	ds_read_b128 v[94:97], v102 offset:1024
	ds_read_b128 v[98:101], v102 offset:2048
	ds_read_b128 v[102:105], v102 offset:3072
	s_cmp_lg_u32 s29, 28
	s_cselect_b32 s30, s28, 0
	s_add_i32 s31, s30, s19
	s_or_b32 s35, s31, 0x80
	s_add_i32 s30, s30, s13
	ds_read_b128 v[106:109], v73
	ds_read_b128 v[110:113], v73 offset:1024
	ds_read_b128 v[114:117], v73 offset:2048
	ds_read_b128 v[118:121], v73 offset:3072
	ds_read_b128 v[122:125], v73 offset:4096
	ds_read_b128 v[126:129], v73 offset:5120
	ds_read_b128 v[130:133], v73 offset:6144
	ds_read_b128 v[134:137], v73 offset:7168
	s_waitcnt lgkmcnt(0)
	s_barrier
	s_setprio 1
	s_waitcnt lgkmcnt(7)
	s_waitcnt lgkmcnt(0)
	v_mfma_f32_16x16x32_bf16 v[62:65], v[74:77], v[106:109], v[62:65]
	v_mfma_f32_16x16x32_bf16 v[58:61], v[82:85], v[106:109], v[58:61]
	v_mfma_f32_16x16x32_bf16 v[50:53], v[82:85], v[114:117], v[50:53]
	v_mfma_f32_16x16x32_bf16 v[54:57], v[74:77], v[114:117], v[54:57]
	v_mfma_f32_16x16x32_bf16 v[46:49], v[74:77], v[122:125], v[46:49]
	v_mfma_f32_16x16x32_bf16 v[42:45], v[82:85], v[122:125], v[42:45]
	v_mfma_f32_16x16x32_bf16 v[34:37], v[82:85], v[130:133], v[34:37]
	v_mfma_f32_16x16x32_bf16 v[38:41], v[74:77], v[130:133], v[38:41]
	v_mfma_f32_16x16x32_bf16 v[62:65], v[78:81], v[110:113], v[62:65]
	v_mfma_f32_16x16x32_bf16 v[58:61], v[86:89], v[110:113], v[58:61]
	v_mfma_f32_16x16x32_bf16 v[50:53], v[86:89], v[118:121], v[50:53]
	v_mfma_f32_16x16x32_bf16 v[54:57], v[78:81], v[118:121], v[54:57]
	v_mfma_f32_16x16x32_bf16 v[46:49], v[78:81], v[126:129], v[46:49]
	v_mfma_f32_16x16x32_bf16 v[42:45], v[86:89], v[126:129], v[42:45]
	v_mfma_f32_16x16x32_bf16 v[34:37], v[86:89], v[134:137], v[34:37]
	v_mfma_f32_16x16x32_bf16 v[38:41], v[78:81], v[134:137], v[38:41]
	s_setprio 0
	s_setprio 1
	v_mfma_f32_16x16x32_bf16 v[30:33], v[90:93], v[106:109], v[30:33]
	v_mfma_f32_16x16x32_bf16 v[26:29], v[98:101], v[106:109], v[26:29]
	v_mfma_f32_16x16x32_bf16 v[18:21], v[98:101], v[114:117], v[18:21]
	v_mfma_f32_16x16x32_bf16 v[22:25], v[90:93], v[114:117], v[22:25]
	v_mfma_f32_16x16x32_bf16 v[14:17], v[90:93], v[122:125], v[14:17]
	v_mfma_f32_16x16x32_bf16 v[10:13], v[98:101], v[122:125], v[10:13]
	v_mfma_f32_16x16x32_bf16 v[2:5], v[98:101], v[130:133], v[2:5]
	v_mfma_f32_16x16x32_bf16 v[6:9], v[90:93], v[130:133], v[6:9]
	v_mfma_f32_16x16x32_bf16 v[30:33], v[94:97], v[110:113], v[30:33]
	v_mfma_f32_16x16x32_bf16 v[26:29], v[102:105], v[110:113], v[26:29]
	v_mfma_f32_16x16x32_bf16 v[18:21], v[102:105], v[118:121], v[18:21]
	v_mfma_f32_16x16x32_bf16 v[22:25], v[94:97], v[118:121], v[22:25]
	v_mfma_f32_16x16x32_bf16 v[14:17], v[94:97], v[126:129], v[14:17]
	v_mfma_f32_16x16x32_bf16 v[10:13], v[102:105], v[126:129], v[10:13]
	v_mfma_f32_16x16x32_bf16 v[2:5], v[102:105], v[134:137], v[2:5]
	v_mfma_f32_16x16x32_bf16 v[6:9], v[94:97], v[134:137], v[6:9]
	s_setprio 0
	s_barrier
	s_mov_b32 m0, s15
	s_mov_b32 s42, s78
	s_mov_b32 s43, s79
	buffer_load_dwordx4 v67, s[40:43], s30 offen lds
	s_mov_b32 m0, s16
	s_add_i32 s38, s30, 0x80000
	buffer_load_dwordx4 v69, s[40:43], s30 offen lds
	s_mov_b32 m0, s17
	s_nop 0
	buffer_load_dwordx4 v67, s[40:43], s38 offen lds
	s_mov_b32 m0, s18
	s_nop 0
	buffer_load_dwordx4 v69, s[40:43], s38 offen lds
	s_mov_b32 m0, s14
	s_nop 0
	buffer_load_dwordx4 v66, s[76:79], s31 offen lds
	s_mov_b32 m0, s20
	s_nop 0
	buffer_load_dwordx4 v68, s[76:79], s31 offen lds
	s_waitcnt vmcnt(6)
	s_barrier
	s_barrier
; #define PG8_STAGEX(rs, bufoff, soff, voff) do { _Pragma("unroll") for (int _i = 0; _i < 2; ++_i) \
;         __builtin_amdgcn_raw_ptr_buffer_load_lds(rs, (LAS unsigned*)(lds + (bufoff) + ldsw + _i * 8192), 16, (voff)[_i], (soff), 0, 0); } while (0)
; #define PG8_LDA(dst, b, h) do { _Pragma("unroll") for (int m = 0; m < 4; ++m) _Pragma("unroll") for (int k = 0; k < 2; ++k) dst[m][k] = *(const LAS bf16x8*)(lds + PG8_SA(b, h) + aoff + m * 2048 + k * 1024); } while (0)
; #define PG8_LDB(dst, b, h) do { _Pragma("unroll") for (int n = 0; n < 2; ++n) _Pragma("unroll") for (int k = 0; k < 2; ++k) dst[n][k] = *(const LAS bf16x8*)(lds + PG8_SB(b, h) + boff + n * 2048 + k * 1024); } while (0)
; #define PG8_WAIT_V(n) asm volatile("s_waitcnt vmcnt(" #n ")" ::: "memory")
; #define PG8_WAIT_L(n) asm volatile("s_waitcnt lgkmcnt(" #n ")" ::: "memory")
; #define PG8_BAR __builtin_amdgcn_s_barrier()
; #define PG8_SCHED __builtin_amdgcn_sched_barrier(0)
;     ...
;                 if (w0) { PG8_LDB(B0, 1, 0); PG8_LDB(B1, 1, 1); PG8_SCHED; PG8_LDA(At, 1, 0); }
;                 PG8_WAIT_L(0); PG8_BAR; if (w0) { PG8_MMA(0, 0, At, B0); PG8_MMA(0, 1, At, B1); } PG8_BAR; PG8_SCHED;
;                 PG8_STAGEX(rsB, PG8_SB(1, 0), b3, voffB); PG8_STAGEX(rsB, PG8_SB(1, 1), b3 + hstepB, voffB); PG8_STAGEX(rsA, PG8_SA(1, 0), a3, voffA);
;                 PG8_WAIT_V(6); PG8_BAR; PG8_BAR; PG8_SCHED;
;             }
	v_add_u32_e32 v86, 0x18000, v72
	v_add_u32_e32 v102, 0x1c000, v72
	ds_read_b128 v[74:77], v86
	ds_read_b128 v[78:81], v86 offset:1024
	ds_read_b128 v[82:85], v86 offset:2048
	ds_read_b128 v[86:89], v86 offset:3072
	ds_read_b128 v[90:93], v102
	ds_read_b128 v[94:97], v102 offset:1024
	ds_read_b128 v[98:101], v102 offset:2048
	ds_read_b128 v[102:105], v102 offset:3072
	ds_read_b128 v[106:109], v73 offset:32768
	ds_read_b128 v[110:113], v73 offset:33792
	ds_read_b128 v[114:117], v73 offset:34816
	ds_read_b128 v[118:121], v73 offset:35840
	ds_read_b128 v[122:125], v73 offset:36864
	ds_read_b128 v[126:129], v73 offset:37888
	ds_read_b128 v[130:133], v73 offset:38912
	ds_read_b128 v[134:137], v73 offset:39936
	s_waitcnt lgkmcnt(0)
	s_barrier
	s_setprio 1
	s_waitcnt lgkmcnt(7)
	s_waitcnt lgkmcnt(0)
	v_mfma_f32_16x16x32_bf16 v[62:65], v[74:77], v[106:109], v[62:65]
	v_mfma_f32_16x16x32_bf16 v[58:61], v[82:85], v[106:109], v[58:61]
	v_mfma_f32_16x16x32_bf16 v[50:53], v[82:85], v[114:117], v[50:53]
	v_mfma_f32_16x16x32_bf16 v[54:57], v[74:77], v[114:117], v[54:57]
	v_mfma_f32_16x16x32_bf16 v[46:49], v[74:77], v[122:125], v[46:49]
	v_mfma_f32_16x16x32_bf16 v[42:45], v[82:85], v[122:125], v[42:45]
	v_mfma_f32_16x16x32_bf16 v[34:37], v[82:85], v[130:133], v[34:37]
	v_mfma_f32_16x16x32_bf16 v[38:41], v[74:77], v[130:133], v[38:41]
	v_mfma_f32_16x16x32_bf16 v[62:65], v[78:81], v[110:113], v[62:65]
	v_mfma_f32_16x16x32_bf16 v[58:61], v[86:89], v[110:113], v[58:61]
	v_mfma_f32_16x16x32_bf16 v[50:53], v[86:89], v[118:121], v[50:53]
	v_mfma_f32_16x16x32_bf16 v[54:57], v[78:81], v[118:121], v[54:57]
	v_mfma_f32_16x16x32_bf16 v[46:49], v[78:81], v[126:129], v[46:49]
	v_mfma_f32_16x16x32_bf16 v[42:45], v[86:89], v[126:129], v[42:45]
	v_mfma_f32_16x16x32_bf16 v[34:37], v[86:89], v[134:137], v[34:37]
	v_mfma_f32_16x16x32_bf16 v[38:41], v[78:81], v[134:137], v[38:41]
	s_setprio 0
	s_setprio 1
	v_mfma_f32_16x16x32_bf16 v[30:33], v[90:93], v[106:109], v[30:33]
	s_or_b32 s31, s30, 0x80
	v_mfma_f32_16x16x32_bf16 v[26:29], v[98:101], v[106:109], v[26:29]
	v_mfma_f32_16x16x32_bf16 v[22:25], v[90:93], v[114:117], v[22:25]
	v_mfma_f32_16x16x32_bf16 v[18:21], v[98:101], v[114:117], v[18:21]
	v_mfma_f32_16x16x32_bf16 v[14:17], v[90:93], v[122:125], v[14:17]
	v_mfma_f32_16x16x32_bf16 v[10:13], v[98:101], v[122:125], v[10:13]
	v_mfma_f32_16x16x32_bf16 v[6:9], v[90:93], v[130:133], v[6:9]
	v_mfma_f32_16x16x32_bf16 v[2:5], v[98:101], v[130:133], v[2:5]
	v_mfma_f32_16x16x32_bf16 v[30:33], v[94:97], v[110:113], v[30:33]
	v_mfma_f32_16x16x32_bf16 v[26:29], v[102:105], v[110:113], v[26:29]
	v_mfma_f32_16x16x32_bf16 v[22:25], v[94:97], v[118:121], v[22:25]
	v_mfma_f32_16x16x32_bf16 v[18:21], v[102:105], v[118:121], v[18:21]
	v_mfma_f32_16x16x32_bf16 v[14:17], v[94:97], v[126:129], v[14:17]
	v_mfma_f32_16x16x32_bf16 v[10:13], v[102:105], v[126:129], v[10:13]
	v_mfma_f32_16x16x32_bf16 v[6:9], v[94:97], v[134:137], v[6:9]
	v_mfma_f32_16x16x32_bf16 v[2:5], v[102:105], v[134:137], v[2:5]
	s_setprio 0
	s_barrier
	s_mov_b32 m0, s22
	s_add_i32 s30, s30, 0x80080
	buffer_load_dwordx4 v67, s[40:43], s31 offen lds
	s_mov_b32 m0, s23
	s_nop 0
	buffer_load_dwordx4 v69, s[40:43], s31 offen lds
	s_mov_b32 m0, s26
	s_nop 0
	buffer_load_dwordx4 v67, s[40:43], s30 offen lds
	s_mov_b32 m0, s27
	s_nop 0
	buffer_load_dwordx4 v69, s[40:43], s30 offen lds
	s_mov_b32 m0, s24
	s_nop 0
	buffer_load_dwordx4 v66, s[76:79], s35 offen lds
	s_mov_b32 m0, s25
	s_nop 0
	buffer_load_dwordx4 v68, s[76:79], s35 offen lds
	s_waitcnt vmcnt(6)
	s_barrier
	s_barrier
	s_addk_i32 s28, 0x100
	s_add_i32 s29, s29, 2
	s_cmp_gt_u32 s29, 29
	s_cbranch_scc0 .LBB0_1287
	s_cmpk_lt_u32 s12, 0x100
	s_cbranch_scc0 .LBB0_1290
	s_barrier

; #define PG8_STAGEX(rs, bufoff, soff, voff) do { _Pragma("unroll") for (int _i = 0; _i < 2; ++_i) \
;         __builtin_amdgcn_raw_ptr_buffer_load_lds(rs, (LAS unsigned*)(lds + (bufoff) + ldsw + _i * 8192), 16, (voff)[_i], (soff), 0, 0); } while (0)
; #define PG8_LDA(dst, b, h) do { _Pragma("unroll") for (int m = 0; m < 4; ++m) _Pragma("unroll") for (int k = 0; k < 2; ++k) dst[m][k] = *(const LAS bf16x8*)(lds + PG8_SA(b, h) + aoff + m * 2048 + k * 1024); } while (0)
; #define PG8_LDB(dst, b, h) do { _Pragma("unroll") for (int n = 0; n < 2; ++n) _Pragma("unroll") for (int k = 0; k < 2; ++k) dst[n][k] = *(const LAS bf16x8*)(lds + PG8_SB(b, h) + boff + n * 2048 + k * 1024); } while (0)
; #define PG8_WAIT_V(n) asm volatile("s_waitcnt vmcnt(" #n ")" ::: "memory")
; #define PG8_WAIT_L(n) asm volatile("s_waitcnt lgkmcnt(" #n ")" ::: "memory")
; #define PG8_BAR __builtin_amdgcn_s_barrier()
; #define PG8_SCHED __builtin_amdgcn_sched_barrier(0)
;     ...
;             PG8_LDB(B0, 0, 0); PG8_LDB(B1, 0, 1); PG8_SCHED; PG8_LDA(At, 0, 0); PG8_STAGEX(rsA, PG8_SA(1, 1), a1 + hstepA, voffA);
;             PG8_WAIT_V(8); PG8_WAIT_L(0); PG8_BAR; PG8_MMA(0, 0, At, B0); PG8_MMA(0, 1, At, B1); PG8_BAR; PG8_SCHED;
;             PG8_LDA(At, 0, 1); PG8_STAGEX(rsB, PG8_SB(0, 0), b2, voffB); PG8_STAGEX(rsB, PG8_SB(0, 1), b2 + hstepB, voffB); PG8_STAGEX(rsA, PG8_SA(0, 0), a2, voffA);
;             PG8_WAIT_V(8); PG8_WAIT_L(0); PG8_BAR; PG8_MMA(1, 0, At, B0); PG8_MMA(1, 1, At, B1); PG8_BAR; PG8_SCHED;
.LBB0_1377:
	v_add_u32_e32 v142, 0x10000, v185
	v_add_u32_e32 v158, 0x14000, v185
	ds_read_b128 v[130:133], v142
	ds_read_b128 v[134:137], v142 offset:1024
	ds_read_b128 v[138:141], v142 offset:2048
	ds_read_b128 v[142:145], v142 offset:3072
	ds_read_b128 v[146:149], v158
	ds_read_b128 v[150:153], v158 offset:1024
	ds_read_b128 v[154:157], v158 offset:2048
	ds_read_b128 v[158:161], v158 offset:3072
	s_add_i32 s50, s43, 0xfff40080
	s_cmp_eq_u32 s60, 12
	s_cselect_b32 s63, s30, s50
	s_cselect_b32 s62, s31, s59
	s_add_i32 s61, s63, 0x80
	s_mov_b32 m0, s23
	ds_read_b128 v[162:165], v186
	ds_read_b128 v[166:169], v186 offset:1024
	ds_read_b128 v[190:193], v186 offset:2048
	ds_read_b128 v[194:197], v186 offset:3072
	ds_read_b128 v[198:201], v186 offset:4096
	ds_read_b128 v[202:205], v186 offset:5120
	ds_read_b128 v[206:209], v186 offset:6144
	ds_read_b128 v[210:213], v186 offset:7168
	buffer_load_dwordx4 v173, s[76:79], s43 offen lds
	s_mov_b32 m0, s24
	s_nop 0
	buffer_load_dwordx4 v178, s[76:79], s43 offen lds
	s_waitcnt vmcnt(8)
	s_waitcnt lgkmcnt(0)
	s_barrier
	s_setprio 1
	s_waitcnt lgkmcnt(7)
	s_waitcnt lgkmcnt(0)
	v_mfma_f32_16x16x32_bf16 v[126:129], v[130:133], v[162:165], v[126:129]
	v_mfma_f32_16x16x32_bf16 v[122:125], v[138:141], v[162:165], v[122:125]
	v_mfma_f32_16x16x32_bf16 v[114:117], v[138:141], v[190:193], v[114:117]
	v_mfma_f32_16x16x32_bf16 v[118:121], v[130:133], v[190:193], v[118:121]
	v_mfma_f32_16x16x32_bf16 v[110:113], v[130:133], v[198:201], v[110:113]
	v_mfma_f32_16x16x32_bf16 v[106:109], v[138:141], v[198:201], v[106:109]
	v_mfma_f32_16x16x32_bf16 v[98:101], v[138:141], v[206:209], v[98:101]
	v_mfma_f32_16x16x32_bf16 v[102:105], v[130:133], v[206:209], v[102:105]
	v_mfma_f32_16x16x32_bf16 v[126:129], v[134:137], v[166:169], v[126:129]
	v_mfma_f32_16x16x32_bf16 v[122:125], v[142:145], v[166:169], v[122:125]
	v_mfma_f32_16x16x32_bf16 v[114:117], v[142:145], v[194:197], v[114:117]
	v_mfma_f32_16x16x32_bf16 v[118:121], v[134:137], v[194:197], v[118:121]
	v_mfma_f32_16x16x32_bf16 v[110:113], v[134:137], v[202:205], v[110:113]
	v_mfma_f32_16x16x32_bf16 v[106:109], v[142:145], v[202:205], v[106:109]
	v_mfma_f32_16x16x32_bf16 v[98:101], v[142:145], v[210:213], v[98:101]
	v_mfma_f32_16x16x32_bf16 v[102:105], v[134:137], v[210:213], v[102:105]
	s_setprio 0
	s_setprio 1
	v_mfma_f32_16x16x32_bf16 v[94:97], v[146:149], v[162:165], v[94:97]
	v_mfma_f32_16x16x32_bf16 v[90:93], v[154:157], v[162:165], v[90:93]
	v_mfma_f32_16x16x32_bf16 v[82:85], v[154:157], v[190:193], v[82:85]
	v_mfma_f32_16x16x32_bf16 v[86:89], v[146:149], v[190:193], v[86:89]
	v_mfma_f32_16x16x32_bf16 v[78:81], v[146:149], v[198:201], v[78:81]
	v_mfma_f32_16x16x32_bf16 v[74:77], v[154:157], v[198:201], v[74:77]
	v_mfma_f32_16x16x32_bf16 v[66:69], v[154:157], v[206:209], v[66:69]
	v_mfma_f32_16x16x32_bf16 v[70:73], v[146:149], v[206:209], v[70:73]
	v_mfma_f32_16x16x32_bf16 v[94:97], v[150:153], v[166:169], v[94:97]
	v_mfma_f32_16x16x32_bf16 v[90:93], v[158:161], v[166:169], v[90:93]
	v_mfma_f32_16x16x32_bf16 v[82:85], v[158:161], v[194:197], v[82:85]
	v_mfma_f32_16x16x32_bf16 v[86:89], v[150:153], v[194:197], v[86:89]
	v_mfma_f32_16x16x32_bf16 v[78:81], v[150:153], v[202:205], v[78:81]
	v_mfma_f32_16x16x32_bf16 v[74:77], v[158:161], v[202:205], v[74:77]
	v_mfma_f32_16x16x32_bf16 v[66:69], v[158:161], v[210:213], v[66:69]
	v_mfma_f32_16x16x32_bf16 v[70:73], v[150:153], v[210:213], v[70:73]
	s_setprio 0
	s_barrier
	s_mov_b32 m0, s7
	s_mov_b32 s50, s78
	s_mov_b32 s51, s79
	ds_read_b128 v[162:165], v186 offset:16384
	ds_read_b128 v[166:169], v186 offset:17408
	ds_read_b128 v[190:193], v186 offset:18432
	ds_read_b128 v[194:197], v186 offset:19456
	ds_read_b128 v[198:201], v186 offset:20480
	ds_read_b128 v[202:205], v186 offset:21504
	ds_read_b128 v[206:209], v186 offset:22528
	ds_read_b128 v[210:213], v186 offset:23552
	buffer_load_dwordx4 v177, s[48:51], s62 offen lds
	s_mov_b32 m0, s11
	s_add_i32 s64, s62, 0x40000
	buffer_load_dwordx4 v179, s[48:51], s62 offen lds
	s_mov_b32 m0, s12
	s_nop 0
	buffer_load_dwordx4 v177, s[48:51], s64 offen lds
	s_mov_b32 m0, s13
	s_nop 0
	buffer_load_dwordx4 v179, s[48:51], s64 offen lds
	s_mov_b32 m0, s5
	s_nop 0
	buffer_load_dwordx4 v173, s[76:79], s63 offen lds
	s_mov_b32 m0, s14
	s_nop 0
	buffer_load_dwordx4 v178, s[76:79], s63 offen lds
	s_waitcnt vmcnt(8)
	s_waitcnt lgkmcnt(0)
	s_barrier
	s_setprio 1
	s_waitcnt lgkmcnt(7)
	s_waitcnt lgkmcnt(0)
	v_mfma_f32_16x16x32_bf16 v[62:65], v[130:133], v[162:165], v[62:65]
	v_mfma_f32_16x16x32_bf16 v[58:61], v[138:141], v[162:165], v[58:61]
	v_mfma_f32_16x16x32_bf16 v[50:53], v[138:141], v[190:193], v[50:53]
	v_mfma_f32_16x16x32_bf16 v[54:57], v[130:133], v[190:193], v[54:57]
	v_mfma_f32_16x16x32_bf16 v[46:49], v[130:133], v[198:201], v[46:49]
	v_mfma_f32_16x16x32_bf16 v[42:45], v[138:141], v[198:201], v[42:45]
	v_mfma_f32_16x16x32_bf16 v[34:37], v[138:141], v[206:209], v[34:37]
	v_mfma_f32_16x16x32_bf16 v[38:41], v[130:133], v[206:209], v[38:41]
	v_mfma_f32_16x16x32_bf16 v[62:65], v[134:137], v[166:169], v[62:65]
	v_mfma_f32_16x16x32_bf16 v[58:61], v[142:145], v[166:169], v[58:61]
	v_mfma_f32_16x16x32_bf16 v[50:53], v[142:145], v[194:197], v[50:53]
	v_mfma_f32_16x16x32_bf16 v[54:57], v[134:137], v[194:197], v[54:57]
	v_mfma_f32_16x16x32_bf16 v[46:49], v[134:137], v[202:205], v[46:49]
	v_mfma_f32_16x16x32_bf16 v[42:45], v[142:145], v[202:205], v[42:45]
	v_mfma_f32_16x16x32_bf16 v[34:37], v[142:145], v[210:213], v[34:37]
	v_mfma_f32_16x16x32_bf16 v[38:41], v[134:137], v[210:213], v[38:41]
	s_setprio 0
	s_setprio 1
	v_mfma_f32_16x16x32_bf16 v[30:33], v[146:149], v[162:165], v[30:33]
	v_mfma_f32_16x16x32_bf16 v[26:29], v[154:157], v[162:165], v[26:29]
	v_mfma_f32_16x16x32_bf16 v[18:21], v[154:157], v[190:193], v[18:21]
	v_mfma_f32_16x16x32_bf16 v[22:25], v[146:149], v[190:193], v[22:25]
	v_mfma_f32_16x16x32_bf16 v[14:17], v[146:149], v[198:201], v[14:17]
	v_mfma_f32_16x16x32_bf16 v[10:13], v[154:157], v[198:201], v[10:13]
	v_mfma_f32_16x16x32_bf16 v[2:5], v[154:157], v[206:209], v[2:5]
	v_mfma_f32_16x16x32_bf16 v[6:9], v[146:149], v[206:209], v[6:9]
	v_mfma_f32_16x16x32_bf16 v[30:33], v[150:153], v[166:169], v[30:33]
	v_mfma_f32_16x16x32_bf16 v[26:29], v[158:161], v[166:169], v[26:29]
	v_mfma_f32_16x16x32_bf16 v[18:21], v[158:161], v[194:197], v[18:21]
	v_mfma_f32_16x16x32_bf16 v[22:25], v[150:153], v[194:197], v[22:25]
	v_mfma_f32_16x16x32_bf16 v[14:17], v[150:153], v[202:205], v[14:17]
	v_mfma_f32_16x16x32_bf16 v[10:13], v[158:161], v[202:205], v[10:13]
	v_mfma_f32_16x16x32_bf16 v[2:5], v[158:161], v[210:213], v[2:5]
	v_mfma_f32_16x16x32_bf16 v[6:9], v[150:153], v[210:213], v[6:9]
	s_setprio 0
	s_barrier
; #define PG8_STAGEX(rs, bufoff, soff, voff) do { _Pragma("unroll") for (int _i = 0; _i < 2; ++_i) \
;         __builtin_amdgcn_raw_ptr_buffer_load_lds(rs, (LAS unsigned*)(lds + (bufoff) + ldsw + _i * 8192), 16, (voff)[_i], (soff), 0, 0); } while (0)
; #define PG8_LDA(dst, b, h) do { _Pragma("unroll") for (int m = 0; m < 4; ++m) _Pragma("unroll") for (int k = 0; k < 2; ++k) dst[m][k] = *(const LAS bf16x8*)(lds + PG8_SA(b, h) + aoff + m * 2048 + k * 1024); } while (0)
; #define PG8_LDB(dst, b, h) do { _Pragma("unroll") for (int n = 0; n < 2; ++n) _Pragma("unroll") for (int k = 0; k < 2; ++k) dst[n][k] = *(const LAS bf16x8*)(lds + PG8_SB(b, h) + boff + n * 2048 + k * 1024); } while (0)
; #define PG8_WAIT_V(n) asm volatile("s_waitcnt vmcnt(" #n ")" ::: "memory")
; #define PG8_WAIT_L(n) asm volatile("s_waitcnt lgkmcnt(" #n ")" ::: "memory")
; #define PG8_BAR __builtin_amdgcn_s_barrier()
; #define PG8_SCHED __builtin_amdgcn_sched_barrier(0)
;     ...
;             PG8_LDB(B0, 1, 0); PG8_LDB(B1, 1, 1); PG8_SCHED; PG8_LDA(At, 1, 0); PG8_STAGEX(rsA, PG8_SA(0, 1), a2 + hstepA, voffA);
;             PG8_WAIT_V(8); PG8_WAIT_L(0); PG8_BAR; PG8_MMA(0, 0, At, B0); PG8_MMA(0, 1, At, B1); PG8_BAR; PG8_SCHED;
;             PG8_LDA(At, 1, 1); PG8_STAGEX(rsB, PG8_SB(1, 0), b3, voffB); PG8_STAGEX(rsB, PG8_SB(1, 1), b3 + hstepB, voffB); PG8_STAGEX(rsA, PG8_SA(1, 0), a3, voffA);
;             PG8_WAIT_V(8); PG8_WAIT_L(0); PG8_BAR; PG8_MMA(1, 0, At, B0); PG8_MMA(1, 1, At, B1); PG8_BAR; PG8_SCHED;
;         }
	v_add_u32_e32 v142, 0x18000, v185
	v_add_u32_e32 v158, 0x1c000, v185
	ds_read_b128 v[130:133], v142
	ds_read_b128 v[134:137], v142 offset:1024
	ds_read_b128 v[138:141], v142 offset:2048
	ds_read_b128 v[142:145], v142 offset:3072
	ds_read_b128 v[146:149], v158
	ds_read_b128 v[150:153], v158 offset:1024
	ds_read_b128 v[154:157], v158 offset:2048
	ds_read_b128 v[158:161], v158 offset:3072
	s_add_i32 s63, s63, 0xc0000
	s_mov_b32 m0, s15
	ds_read_b128 v[162:165], v186 offset:32768
	ds_read_b128 v[166:169], v186 offset:33792
	ds_read_b128 v[190:193], v186 offset:34816
	ds_read_b128 v[194:197], v186 offset:35840
	ds_read_b128 v[198:201], v186 offset:36864
	ds_read_b128 v[202:205], v186 offset:37888
	ds_read_b128 v[206:209], v186 offset:38912
	ds_read_b128 v[210:213], v186 offset:39936
	buffer_load_dwordx4 v173, s[76:79], s63 offen lds
	s_mov_b32 m0, s16
	s_nop 0
	buffer_load_dwordx4 v178, s[76:79], s63 offen lds
	s_waitcnt vmcnt(8)
	s_waitcnt lgkmcnt(0)
	s_barrier
	s_setprio 1
	s_waitcnt lgkmcnt(7)
	s_waitcnt lgkmcnt(0)
	v_mfma_f32_16x16x32_bf16 v[126:129], v[130:133], v[162:165], v[126:129]
	v_mfma_f32_16x16x32_bf16 v[122:125], v[138:141], v[162:165], v[122:125]
	v_mfma_f32_16x16x32_bf16 v[114:117], v[138:141], v[190:193], v[114:117]
	v_mfma_f32_16x16x32_bf16 v[118:121], v[130:133], v[190:193], v[118:121]
	v_mfma_f32_16x16x32_bf16 v[110:113], v[130:133], v[198:201], v[110:113]
	v_mfma_f32_16x16x32_bf16 v[106:109], v[138:141], v[198:201], v[106:109]
	v_mfma_f32_16x16x32_bf16 v[98:101], v[138:141], v[206:209], v[98:101]
	v_mfma_f32_16x16x32_bf16 v[102:105], v[130:133], v[206:209], v[102:105]
	v_mfma_f32_16x16x32_bf16 v[126:129], v[134:137], v[166:169], v[126:129]
	v_mfma_f32_16x16x32_bf16 v[122:125], v[142:145], v[166:169], v[122:125]
	v_mfma_f32_16x16x32_bf16 v[114:117], v[142:145], v[194:197], v[114:117]
	v_mfma_f32_16x16x32_bf16 v[118:121], v[134:137], v[194:197], v[118:121]
	v_mfma_f32_16x16x32_bf16 v[110:113], v[134:137], v[202:205], v[110:113]
	v_mfma_f32_16x16x32_bf16 v[106:109], v[142:145], v[202:205], v[106:109]
	v_mfma_f32_16x16x32_bf16 v[98:101], v[142:145], v[210:213], v[98:101]
	v_mfma_f32_16x16x32_bf16 v[102:105], v[134:137], v[210:213], v[102:105]
	s_setprio 0
	s_setprio 1
	v_mfma_f32_16x16x32_bf16 v[94:97], v[146:149], v[162:165], v[94:97]
	v_mfma_f32_16x16x32_bf16 v[90:93], v[154:157], v[162:165], v[90:93]
	v_mfma_f32_16x16x32_bf16 v[82:85], v[154:157], v[190:193], v[82:85]
	v_mfma_f32_16x16x32_bf16 v[86:89], v[146:149], v[190:193], v[86:89]
	v_mfma_f32_16x16x32_bf16 v[78:81], v[146:149], v[198:201], v[78:81]
	v_mfma_f32_16x16x32_bf16 v[74:77], v[154:157], v[198:201], v[74:77]
	v_mfma_f32_16x16x32_bf16 v[66:69], v[154:157], v[206:209], v[66:69]
	v_mfma_f32_16x16x32_bf16 v[70:73], v[146:149], v[206:209], v[70:73]
	v_mfma_f32_16x16x32_bf16 v[94:97], v[150:153], v[166:169], v[94:97]
	v_mfma_f32_16x16x32_bf16 v[90:93], v[158:161], v[166:169], v[90:93]
	v_mfma_f32_16x16x32_bf16 v[82:85], v[158:161], v[194:197], v[82:85]
	v_mfma_f32_16x16x32_bf16 v[86:89], v[150:153], v[194:197], v[86:89]
	v_mfma_f32_16x16x32_bf16 v[78:81], v[150:153], v[202:205], v[78:81]
	v_mfma_f32_16x16x32_bf16 v[74:77], v[158:161], v[202:205], v[74:77]
	v_mfma_f32_16x16x32_bf16 v[66:69], v[158:161], v[210:213], v[66:69]
	v_mfma_f32_16x16x32_bf16 v[70:73], v[150:153], v[210:213], v[70:73]
	s_setprio 0
	s_barrier
	s_mov_b32 m0, s17
	s_add_i32 s63, s62, 0x80
	ds_read_b128 v[162:165], v186 offset:49152
	ds_read_b128 v[166:169], v186 offset:50176
	ds_read_b128 v[190:193], v186 offset:51200
	ds_read_b128 v[194:197], v186 offset:52224
	ds_read_b128 v[198:201], v186 offset:53248
	ds_read_b128 v[202:205], v186 offset:54272
	ds_read_b128 v[206:209], v186 offset:55296
	ds_read_b128 v[210:213], v186 offset:56320
	buffer_load_dwordx4 v177, s[48:51], s63 offen lds
	s_mov_b32 m0, s18
	s_add_i32 s62, s62, 0x40080
	buffer_load_dwordx4 v179, s[48:51], s63 offen lds
	s_mov_b32 m0, s21
	s_nop 0
	buffer_load_dwordx4 v177, s[48:51], s62 offen lds
	s_mov_b32 m0, s22
	s_nop 0
	buffer_load_dwordx4 v179, s[48:51], s62 offen lds
	s_mov_b32 m0, s19
	s_nop 0
	buffer_load_dwordx4 v173, s[76:79], s61 offen lds
	s_mov_b32 m0, s20
	s_nop 0
	buffer_load_dwordx4 v178, s[76:79], s61 offen lds
	s_waitcnt vmcnt(8)
	s_waitcnt lgkmcnt(0)
	s_barrier
	s_setprio 1
	s_waitcnt lgkmcnt(7)
	s_waitcnt lgkmcnt(0)
	v_mfma_f32_16x16x32_bf16 v[62:65], v[130:133], v[162:165], v[62:65]
	v_mfma_f32_16x16x32_bf16 v[58:61], v[138:141], v[162:165], v[58:61]
	v_mfma_f32_16x16x32_bf16 v[50:53], v[138:141], v[190:193], v[50:53]
	v_mfma_f32_16x16x32_bf16 v[54:57], v[130:133], v[190:193], v[54:57]
	v_mfma_f32_16x16x32_bf16 v[46:49], v[130:133], v[198:201], v[46:49]
	v_mfma_f32_16x16x32_bf16 v[42:45], v[138:141], v[198:201], v[42:45]
	v_mfma_f32_16x16x32_bf16 v[34:37], v[138:141], v[206:209], v[34:37]
	v_mfma_f32_16x16x32_bf16 v[38:41], v[130:133], v[206:209], v[38:41]
	v_mfma_f32_16x16x32_bf16 v[62:65], v[134:137], v[166:169], v[62:65]
	v_mfma_f32_16x16x32_bf16 v[58:61], v[142:145], v[166:169], v[58:61]
	v_mfma_f32_16x16x32_bf16 v[50:53], v[142:145], v[194:197], v[50:53]
	v_mfma_f32_16x16x32_bf16 v[54:57], v[134:137], v[194:197], v[54:57]
	v_mfma_f32_16x16x32_bf16 v[46:49], v[134:137], v[202:205], v[46:49]
	v_mfma_f32_16x16x32_bf16 v[42:45], v[142:145], v[202:205], v[42:45]
	v_mfma_f32_16x16x32_bf16 v[34:37], v[142:145], v[210:213], v[34:37]
	v_mfma_f32_16x16x32_bf16 v[38:41], v[134:137], v[210:213], v[38:41]
	s_setprio 0
	s_setprio 1
	v_mfma_f32_16x16x32_bf16 v[30:33], v[146:149], v[162:165], v[30:33]
	v_mfma_f32_16x16x32_bf16 v[26:29], v[154:157], v[162:165], v[26:29]
	v_mfma_f32_16x16x32_bf16 v[18:21], v[154:157], v[190:193], v[18:21]
	v_mfma_f32_16x16x32_bf16 v[22:25], v[146:149], v[190:193], v[22:25]
	v_mfma_f32_16x16x32_bf16 v[14:17], v[146:149], v[198:201], v[14:17]
	v_mfma_f32_16x16x32_bf16 v[10:13], v[154:157], v[198:201], v[10:13]
	v_mfma_f32_16x16x32_bf16 v[2:5], v[154:157], v[206:209], v[2:5]
	v_mfma_f32_16x16x32_bf16 v[6:9], v[146:149], v[206:209], v[6:9]
	v_mfma_f32_16x16x32_bf16 v[30:33], v[150:153], v[166:169], v[30:33]
	v_mfma_f32_16x16x32_bf16 v[26:29], v[158:161], v[166:169], v[26:29]
	v_mfma_f32_16x16x32_bf16 v[18:21], v[158:161], v[194:197], v[18:21]
	v_mfma_f32_16x16x32_bf16 v[22:25], v[150:153], v[194:197], v[22:25]
	v_mfma_f32_16x16x32_bf16 v[14:17], v[150:153], v[202:205], v[14:17]
	v_mfma_f32_16x16x32_bf16 v[10:13], v[158:161], v[202:205], v[10:13]
	v_mfma_f32_16x16x32_bf16 v[2:5], v[158:161], v[210:213], v[2:5]
	v_mfma_f32_16x16x32_bf16 v[6:9], v[150:153], v[210:213], v[6:9]
	s_setprio 0
	s_barrier
	s_add_i32 s60, s60, 2
	s_addk_i32 s43, 0x100
	s_addk_i32 s59, 0x100
	s_cmp_gt_u32 s60, 13
	s_cbranch_scc0 .LBB0_1377
	s_and_b64 vcc, exec, s[52:53]
	s_cbranch_vccz .LBB0_1380
	s_barrier

; #define PG8_STAGEX(rs, bufoff, soff, voff) do { _Pragma("unroll") for (int _i = 0; _i < 2; ++_i) \
;         __builtin_amdgcn_raw_ptr_buffer_load_lds(rs, (LAS unsigned*)(lds + (bufoff) + ldsw + _i * 8192), 16, (voff)[_i], (soff), 0, 0); } while (0)
; #define PG8_LDA(dst, b, h) do { _Pragma("unroll") for (int m = 0; m < 4; ++m) _Pragma("unroll") for (int k = 0; k < 2; ++k) dst[m][k] = *(const LAS bf16x8*)(lds + PG8_SA(b, h) + aoff + m * 2048 + k * 1024); } while (0)
; #define PG8_LDB(dst, b, h) do { _Pragma("unroll") for (int n = 0; n < 2; ++n) _Pragma("unroll") for (int k = 0; k < 2; ++k) dst[n][k] = *(const LAS bf16x8*)(lds + PG8_SB(b, h) + boff + n * 2048 + k * 1024); } while (0)
; #define PG8_WAIT_V(n) asm volatile("s_waitcnt vmcnt(" #n ")" ::: "memory")
; #define PG8_WAIT_L(n) asm volatile("s_waitcnt lgkmcnt(" #n ")" ::: "memory")
; #define PG8_BAR __builtin_amdgcn_s_barrier()
; #define PG8_SCHED __builtin_amdgcn_sched_barrier(0)
;     ...
;                 if (w0) { PG8_LDB(B0, 0, 0); PG8_LDB(B1, 0, 1); PG8_SCHED; PG8_LDA(At, 0, 0); }
;                 PG8_WAIT_L(0); PG8_BAR; if (w0) { PG8_MMA(0, 0, At, B0); PG8_MMA(0, 1, At, B1); } PG8_BAR; PG8_SCHED;
;                 PG8_STAGEX(rsB, PG8_SB(0, 0), b2, voffB); PG8_STAGEX(rsB, PG8_SB(0, 1), b2 + hstepB, voffB); PG8_STAGEX(rsA, PG8_SA(0, 0), a2, voffA);
;                 PG8_WAIT_V(6); PG8_BAR; PG8_BAR; PG8_SCHED;
.LBB0_1429:
	v_add_u32_e32 v78, 0x10000, v95
	v_add_u32_e32 v86, 0x14000, v95
	ds_read_b128 v[66:69], v78
	ds_read_b128 v[70:73], v78 offset:1024
	ds_read_b128 v[74:77], v78 offset:2048
	ds_read_b128 v[78:81], v78 offset:3072
	ds_read_b128 v[82:85], v86
	ds_read_b128 v[100:103], v86 offset:1024
	ds_read_b128 v[104:107], v86 offset:2048
	ds_read_b128 v[108:111], v86 offset:3072
	s_cmp_eq_u32 s40, 12
	s_cselect_b32 s41, s38, s39
	s_cselect_b32 s46, s30, s31
	s_add_i32 s47, s41, 0x80
	ds_read_b128 v[112:115], v96
	ds_read_b128 v[116:119], v96 offset:1024
	ds_read_b128 v[120:123], v96 offset:2048
	ds_read_b128 v[124:127], v96 offset:3072
	ds_read_b128 v[128:131], v96 offset:4096
	ds_read_b128 v[132:135], v96 offset:5120
	ds_read_b128 v[136:139], v96 offset:6144
	ds_read_b128 v[140:143], v96 offset:7168
	s_waitcnt lgkmcnt(0)
	s_barrier
	s_setprio 1
	s_waitcnt lgkmcnt(7)
	s_waitcnt lgkmcnt(0)
	v_mfma_f32_16x16x32_bf16 v[62:65], v[66:69], v[112:115], v[62:65]
	v_mfma_f32_16x16x32_bf16 v[58:61], v[74:77], v[112:115], v[58:61]
	v_mfma_f32_16x16x32_bf16 v[50:53], v[74:77], v[120:123], v[50:53]
	v_mfma_f32_16x16x32_bf16 v[54:57], v[66:69], v[120:123], v[54:57]
	v_mfma_f32_16x16x32_bf16 v[46:49], v[66:69], v[128:131], v[46:49]
	v_mfma_f32_16x16x32_bf16 v[42:45], v[74:77], v[128:131], v[42:45]
	v_mfma_f32_16x16x32_bf16 v[34:37], v[74:77], v[136:139], v[34:37]
	v_mfma_f32_16x16x32_bf16 v[38:41], v[66:69], v[136:139], v[38:41]
	v_mfma_f32_16x16x32_bf16 v[62:65], v[70:73], v[116:119], v[62:65]
	v_mfma_f32_16x16x32_bf16 v[58:61], v[78:81], v[116:119], v[58:61]
	v_mfma_f32_16x16x32_bf16 v[50:53], v[78:81], v[124:127], v[50:53]
	v_mfma_f32_16x16x32_bf16 v[54:57], v[70:73], v[124:127], v[54:57]
	v_mfma_f32_16x16x32_bf16 v[46:49], v[70:73], v[132:135], v[46:49]
	v_mfma_f32_16x16x32_bf16 v[42:45], v[78:81], v[132:135], v[42:45]
	v_mfma_f32_16x16x32_bf16 v[34:37], v[78:81], v[140:143], v[34:37]
	v_mfma_f32_16x16x32_bf16 v[38:41], v[70:73], v[140:143], v[38:41]
	s_setprio 0
	s_setprio 1
	v_mfma_f32_16x16x32_bf16 v[30:33], v[82:85], v[112:115], v[30:33]
	v_mfma_f32_16x16x32_bf16 v[26:29], v[104:107], v[112:115], v[26:29]
	v_mfma_f32_16x16x32_bf16 v[18:21], v[104:107], v[120:123], v[18:21]
	v_mfma_f32_16x16x32_bf16 v[22:25], v[82:85], v[120:123], v[22:25]
	v_mfma_f32_16x16x32_bf16 v[14:17], v[82:85], v[128:131], v[14:17]
	v_mfma_f32_16x16x32_bf16 v[10:13], v[104:107], v[128:131], v[10:13]
	v_mfma_f32_16x16x32_bf16 v[2:5], v[104:107], v[136:139], v[2:5]
	v_mfma_f32_16x16x32_bf16 v[6:9], v[82:85], v[136:139], v[6:9]
	v_mfma_f32_16x16x32_bf16 v[30:33], v[100:103], v[116:119], v[30:33]
	v_mfma_f32_16x16x32_bf16 v[26:29], v[108:111], v[116:119], v[26:29]
	v_mfma_f32_16x16x32_bf16 v[18:21], v[108:111], v[124:127], v[18:21]
	v_mfma_f32_16x16x32_bf16 v[22:25], v[100:103], v[124:127], v[22:25]
	v_mfma_f32_16x16x32_bf16 v[14:17], v[100:103], v[132:135], v[14:17]
	v_mfma_f32_16x16x32_bf16 v[10:13], v[108:111], v[132:135], v[10:13]
	v_mfma_f32_16x16x32_bf16 v[2:5], v[108:111], v[140:143], v[2:5]
	v_mfma_f32_16x16x32_bf16 v[6:9], v[100:103], v[140:143], v[6:9]
	s_setprio 0
	s_barrier
	s_mov_b32 m0, s5
	s_mov_b32 s50, s78
	s_mov_b32 s51, s79
	buffer_load_dwordx4 v89, s[48:51], s46 offen lds
	s_mov_b32 m0, s7
	s_add_i32 s52, s46, 0x40000
	buffer_load_dwordx4 v91, s[48:51], s46 offen lds
	s_mov_b32 m0, s11
	s_nop 0
	buffer_load_dwordx4 v89, s[48:51], s52 offen lds
	s_mov_b32 m0, s12
	s_nop 0
	buffer_load_dwordx4 v91, s[48:51], s52 offen lds
	s_mov_b32 m0, s3
	s_nop 0
	buffer_load_dwordx4 v88, s[76:79], s41 offen lds
	s_mov_b32 m0, s13
	s_nop 0
	buffer_load_dwordx4 v90, s[76:79], s41 offen lds
	s_waitcnt vmcnt(6)
	s_barrier
	s_barrier
; #define PG8_STAGEX(rs, bufoff, soff, voff) do { _Pragma("unroll") for (int _i = 0; _i < 2; ++_i) \
;         __builtin_amdgcn_raw_ptr_buffer_load_lds(rs, (LAS unsigned*)(lds + (bufoff) + ldsw + _i * 8192), 16, (voff)[_i], (soff), 0, 0); } while (0)
; #define PG8_LDA(dst, b, h) do { _Pragma("unroll") for (int m = 0; m < 4; ++m) _Pragma("unroll") for (int k = 0; k < 2; ++k) dst[m][k] = *(const LAS bf16x8*)(lds + PG8_SA(b, h) + aoff + m * 2048 + k * 1024); } while (0)
; #define PG8_LDB(dst, b, h) do { _Pragma("unroll") for (int n = 0; n < 2; ++n) _Pragma("unroll") for (int k = 0; k < 2; ++k) dst[n][k] = *(const LAS bf16x8*)(lds + PG8_SB(b, h) + boff + n * 2048 + k * 1024); } while (0)
; #define PG8_WAIT_V(n) asm volatile("s_waitcnt vmcnt(" #n ")" ::: "memory")
; #define PG8_WAIT_L(n) asm volatile("s_waitcnt lgkmcnt(" #n ")" ::: "memory")
; #define PG8_BAR __builtin_amdgcn_s_barrier()
; #define PG8_SCHED __builtin_amdgcn_sched_barrier(0)
;     ...
;                 if (w0) { PG8_LDB(B0, 1, 0); PG8_LDB(B1, 1, 1); PG8_SCHED; PG8_LDA(At, 1, 0); }
;                 PG8_WAIT_L(0); PG8_BAR; if (w0) { PG8_MMA(0, 0, At, B0); PG8_MMA(0, 1, At, B1); } PG8_BAR; PG8_SCHED;
;                 PG8_STAGEX(rsB, PG8_SB(1, 0), b3, voffB); PG8_STAGEX(rsB, PG8_SB(1, 1), b3 + hstepB, voffB); PG8_STAGEX(rsA, PG8_SA(1, 0), a3, voffA);
;                 PG8_WAIT_V(6); PG8_BAR; PG8_BAR; PG8_SCHED;
;             }
	v_add_u32_e32 v78, 0x18000, v95
	v_add_u32_e32 v86, 0x1c000, v95
	ds_read_b128 v[66:69], v78
	ds_read_b128 v[70:73], v78 offset:1024
	ds_read_b128 v[74:77], v78 offset:2048
	ds_read_b128 v[78:81], v78 offset:3072
	ds_read_b128 v[82:85], v86
	ds_read_b128 v[100:103], v86 offset:1024
	ds_read_b128 v[104:107], v86 offset:2048
	ds_read_b128 v[108:111], v86 offset:3072
	ds_read_b128 v[112:115], v96 offset:32768
	ds_read_b128 v[116:119], v96 offset:33792
	ds_read_b128 v[120:123], v96 offset:34816
	ds_read_b128 v[124:127], v96 offset:35840
	ds_read_b128 v[128:131], v96 offset:36864
	ds_read_b128 v[132:135], v96 offset:37888
	ds_read_b128 v[136:139], v96 offset:38912
	ds_read_b128 v[140:143], v96 offset:39936
	s_waitcnt lgkmcnt(0)
	s_barrier
	s_setprio 1
	s_waitcnt lgkmcnt(7)
	s_waitcnt lgkmcnt(0)
	v_mfma_f32_16x16x32_bf16 v[62:65], v[66:69], v[112:115], v[62:65]
	v_mfma_f32_16x16x32_bf16 v[58:61], v[74:77], v[112:115], v[58:61]
	v_mfma_f32_16x16x32_bf16 v[50:53], v[74:77], v[120:123], v[50:53]
	v_mfma_f32_16x16x32_bf16 v[54:57], v[66:69], v[120:123], v[54:57]
	v_mfma_f32_16x16x32_bf16 v[46:49], v[66:69], v[128:131], v[46:49]
	v_mfma_f32_16x16x32_bf16 v[42:45], v[74:77], v[128:131], v[42:45]
	v_mfma_f32_16x16x32_bf16 v[34:37], v[74:77], v[136:139], v[34:37]
	v_mfma_f32_16x16x32_bf16 v[38:41], v[66:69], v[136:139], v[38:41]
	v_mfma_f32_16x16x32_bf16 v[62:65], v[70:73], v[116:119], v[62:65]
	v_mfma_f32_16x16x32_bf16 v[58:61], v[78:81], v[116:119], v[58:61]
	v_mfma_f32_16x16x32_bf16 v[50:53], v[78:81], v[124:127], v[50:53]
	v_mfma_f32_16x16x32_bf16 v[54:57], v[70:73], v[124:127], v[54:57]
	v_mfma_f32_16x16x32_bf16 v[46:49], v[70:73], v[132:135], v[46:49]
	v_mfma_f32_16x16x32_bf16 v[42:45], v[78:81], v[132:135], v[42:45]
	v_mfma_f32_16x16x32_bf16 v[34:37], v[78:81], v[140:143], v[34:37]
	v_mfma_f32_16x16x32_bf16 v[38:41], v[70:73], v[140:143], v[38:41]
	s_setprio 0
	s_setprio 1
	v_mfma_f32_16x16x32_bf16 v[30:33], v[82:85], v[112:115], v[30:33]
	s_add_i32 s41, s46, 0x80
	v_mfma_f32_16x16x32_bf16 v[26:29], v[104:107], v[112:115], v[26:29]
	v_mfma_f32_16x16x32_bf16 v[22:25], v[82:85], v[120:123], v[22:25]
	v_mfma_f32_16x16x32_bf16 v[18:21], v[104:107], v[120:123], v[18:21]
	v_mfma_f32_16x16x32_bf16 v[14:17], v[82:85], v[128:131], v[14:17]
	v_mfma_f32_16x16x32_bf16 v[10:13], v[104:107], v[128:131], v[10:13]
	v_mfma_f32_16x16x32_bf16 v[6:9], v[82:85], v[136:139], v[6:9]
	v_mfma_f32_16x16x32_bf16 v[2:5], v[104:107], v[136:139], v[2:5]
	v_mfma_f32_16x16x32_bf16 v[30:33], v[100:103], v[116:119], v[30:33]
	v_mfma_f32_16x16x32_bf16 v[26:29], v[108:111], v[116:119], v[26:29]
	v_mfma_f32_16x16x32_bf16 v[22:25], v[100:103], v[124:127], v[22:25]
	v_mfma_f32_16x16x32_bf16 v[18:21], v[108:111], v[124:127], v[18:21]
	v_mfma_f32_16x16x32_bf16 v[14:17], v[100:103], v[132:135], v[14:17]
	v_mfma_f32_16x16x32_bf16 v[10:13], v[108:111], v[132:135], v[10:13]
	v_mfma_f32_16x16x32_bf16 v[6:9], v[100:103], v[140:143], v[6:9]
	v_mfma_f32_16x16x32_bf16 v[2:5], v[108:111], v[140:143], v[2:5]
	s_setprio 0
	s_barrier
	s_mov_b32 m0, s14
	s_add_i32 s46, s46, 0x40080
	buffer_load_dwordx4 v89, s[48:51], s41 offen lds
	s_mov_b32 m0, s15
	s_nop 0
	buffer_load_dwordx4 v91, s[48:51], s41 offen lds
	s_mov_b32 m0, s18
	s_nop 0
	buffer_load_dwordx4 v89, s[48:51], s46 offen lds
	s_mov_b32 m0, s19
	s_nop 0
	buffer_load_dwordx4 v91, s[48:51], s46 offen lds
	s_mov_b32 m0, s16
	s_nop 0
	buffer_load_dwordx4 v88, s[76:79], s47 offen lds
	s_mov_b32 m0, s17
	s_nop 0
	buffer_load_dwordx4 v90, s[76:79], s47 offen lds
	s_waitcnt vmcnt(6)
	s_barrier
	s_barrier
	s_add_i32 s40, s40, 2
	s_addk_i32 s31, 0x100
	s_addk_i32 s39, 0x100
	s_cmp_gt_u32 s40, 13
	s_cbranch_scc0 .LBB0_1429
	s_and_b64 vcc, exec, s[42:43]
	s_cbranch_vccz .LBB0_1432
	s_barrier

; #define PG8_STAGEX(rs, bufoff, soff, voff) do { _Pragma("unroll") for (int _i = 0; _i < 2; ++_i) \
;         __builtin_amdgcn_raw_ptr_buffer_load_lds(rs, (LAS unsigned*)(lds + (bufoff) + ldsw + _i * 8192), 16, (voff)[_i], (soff), 0, 0); } while (0)
; #define PG8_LDA(dst, b, h) do { _Pragma("unroll") for (int m = 0; m < 4; ++m) _Pragma("unroll") for (int k = 0; k < 2; ++k) dst[m][k] = *(const LAS bf16x8*)(lds + PG8_SA(b, h) + aoff + m * 2048 + k * 1024); } while (0)
; #define PG8_LDB(dst, b, h) do { _Pragma("unroll") for (int n = 0; n < 2; ++n) _Pragma("unroll") for (int k = 0; k < 2; ++k) dst[n][k] = *(const LAS bf16x8*)(lds + PG8_SB(b, h) + boff + n * 2048 + k * 1024); } while (0)
; #define PG8_WAIT_V(n) asm volatile("s_waitcnt vmcnt(" #n ")" ::: "memory")
; #define PG8_WAIT_L(n) asm volatile("s_waitcnt lgkmcnt(" #n ")" ::: "memory")
; #define PG8_BAR __builtin_amdgcn_s_barrier()
; #define PG8_SCHED __builtin_amdgcn_sched_barrier(0)
;     ...
;             PG8_LDB(B0, 0, 0); PG8_LDB(B1, 0, 1); PG8_SCHED; PG8_LDA(At, 0, 0); PG8_STAGEX(rsA, PG8_SA(1, 1), a1 + hstepA, voffA);
;             PG8_WAIT_V(8); PG8_WAIT_L(0); PG8_BAR; PG8_MMA(0, 0, At, B0); PG8_MMA(0, 1, At, B1); PG8_BAR; PG8_SCHED;
;             PG8_LDA(At, 0, 1); PG8_STAGEX(rsB, PG8_SB(0, 0), b2, voffB); PG8_STAGEX(rsB, PG8_SB(0, 1), b2 + hstepB, voffB); PG8_STAGEX(rsA, PG8_SA(0, 0), a2, voffA);
;             PG8_WAIT_V(8); PG8_WAIT_L(0); PG8_BAR; PG8_MMA(1, 0, At, B0); PG8_MMA(1, 1, At, B1); PG8_BAR; PG8_SCHED;
.LBB0_1529:
	v_add_u32_e32 v118, 0x10000, v210
	v_add_u32_e32 v142, 0x14000, v210
	ds_read_b128 v[106:109], v118
	ds_read_b128 v[110:113], v118 offset:1024
	ds_read_b128 v[114:117], v118 offset:2048
	ds_read_b128 v[118:121], v118 offset:3072
	ds_read_b128 v[122:125], v142
	ds_read_b128 v[126:129], v142 offset:1024
	ds_read_b128 v[130:133], v142 offset:2048
	ds_read_b128 v[142:145], v142 offset:3072
	s_add_i32 s46, s59, 0xfff80080
	s_cmp_eq_u32 s64, 28
	s_cselect_b32 s67, s30, s46
	s_cselect_b32 s66, s31, s63
	s_or_b32 s65, s67, 0x80
	s_mov_b32 m0, s76
	ds_read_b128 v[164:167], v211
	ds_read_b128 v[168:171], v211 offset:1024
	ds_read_b128 v[182:185], v211 offset:2048
	ds_read_b128 v[186:189], v211 offset:3072
	ds_read_b128 v[190:193], v211 offset:4096
	ds_read_b128 v[194:197], v211 offset:5120
	ds_read_b128 v[198:201], v211 offset:6144
	ds_read_b128 v[202:205], v211 offset:7168
	buffer_load_dwordx4 v178, s[40:43], s59 offen lds
	s_mov_b32 m0, s77
	s_nop 0
	buffer_load_dwordx4 v206, s[40:43], s59 offen lds
	s_waitcnt vmcnt(8)
	s_waitcnt lgkmcnt(0)
	s_barrier
	s_setprio 1
	s_waitcnt lgkmcnt(7)
	s_waitcnt lgkmcnt(0)
	v_mfma_f32_16x16x32_bf16 v[158:161], v[106:109], v[164:167], v[158:161]
	v_mfma_f32_16x16x32_bf16 v[154:157], v[114:117], v[164:167], v[154:157]
	v_mfma_f32_16x16x32_bf16 v[146:149], v[114:117], v[182:185], v[146:149]
	v_mfma_f32_16x16x32_bf16 v[150:153], v[106:109], v[182:185], v[150:153]
	v_mfma_f32_16x16x32_bf16 v[138:141], v[106:109], v[190:193], v[138:141]
	v_mfma_f32_16x16x32_bf16 v[134:137], v[114:117], v[190:193], v[134:137]
	v_mfma_f32_16x16x32_bf16 v[98:101], v[114:117], v[198:201], v[98:101]
	v_mfma_f32_16x16x32_bf16 v[102:105], v[106:109], v[198:201], v[102:105]
	v_mfma_f32_16x16x32_bf16 v[158:161], v[110:113], v[168:171], v[158:161]
	v_mfma_f32_16x16x32_bf16 v[154:157], v[118:121], v[168:171], v[154:157]
	v_mfma_f32_16x16x32_bf16 v[146:149], v[118:121], v[186:189], v[146:149]
	v_mfma_f32_16x16x32_bf16 v[150:153], v[110:113], v[186:189], v[150:153]
	v_mfma_f32_16x16x32_bf16 v[138:141], v[110:113], v[194:197], v[138:141]
	v_mfma_f32_16x16x32_bf16 v[134:137], v[118:121], v[194:197], v[134:137]
	v_mfma_f32_16x16x32_bf16 v[98:101], v[118:121], v[202:205], v[98:101]
	v_mfma_f32_16x16x32_bf16 v[102:105], v[110:113], v[202:205], v[102:105]
	s_setprio 0
	s_setprio 1
	v_mfma_f32_16x16x32_bf16 v[62:65], v[122:125], v[164:167], v[62:65]
	v_mfma_f32_16x16x32_bf16 v[58:61], v[130:133], v[164:167], v[58:61]
	v_mfma_f32_16x16x32_bf16 v[50:53], v[130:133], v[182:185], v[50:53]
	v_mfma_f32_16x16x32_bf16 v[54:57], v[122:125], v[182:185], v[54:57]
	v_mfma_f32_16x16x32_bf16 v[46:49], v[122:125], v[190:193], v[46:49]
	v_mfma_f32_16x16x32_bf16 v[42:45], v[130:133], v[190:193], v[42:45]
	v_mfma_f32_16x16x32_bf16 v[34:37], v[130:133], v[198:201], v[34:37]
	v_mfma_f32_16x16x32_bf16 v[38:41], v[122:125], v[198:201], v[38:41]
	v_mfma_f32_16x16x32_bf16 v[62:65], v[126:129], v[168:171], v[62:65]
	v_mfma_f32_16x16x32_bf16 v[58:61], v[142:145], v[168:171], v[58:61]
	v_mfma_f32_16x16x32_bf16 v[50:53], v[142:145], v[186:189], v[50:53]
	v_mfma_f32_16x16x32_bf16 v[54:57], v[126:129], v[186:189], v[54:57]
	v_mfma_f32_16x16x32_bf16 v[46:49], v[126:129], v[194:197], v[46:49]
	v_mfma_f32_16x16x32_bf16 v[42:45], v[142:145], v[194:197], v[42:45]
	v_mfma_f32_16x16x32_bf16 v[34:37], v[142:145], v[202:205], v[34:37]
	v_mfma_f32_16x16x32_bf16 v[38:41], v[126:129], v[202:205], v[38:41]
	s_setprio 0
	s_barrier
	s_mov_b32 m0, s17
	s_mov_b32 s46, s42
	s_mov_b32 s47, s43
	ds_read_b128 v[164:167], v211 offset:16384
	ds_read_b128 v[168:171], v211 offset:17408
	ds_read_b128 v[182:185], v211 offset:18432
	ds_read_b128 v[186:189], v211 offset:19456
	ds_read_b128 v[190:193], v211 offset:20480
	ds_read_b128 v[194:197], v211 offset:21504
	ds_read_b128 v[198:201], v211 offset:22528
	ds_read_b128 v[202:205], v211 offset:23552
	buffer_load_dwordx4 v179, s[44:47], s66 offen lds
	s_mov_b32 m0, s18
	s_add_i32 s68, s66, 0x80000
	buffer_load_dwordx4 v207, s[44:47], s66 offen lds
	s_mov_b32 m0, s19
	s_nop 0
	buffer_load_dwordx4 v179, s[44:47], s68 offen lds
	s_mov_b32 m0, s20
	s_nop 0
	buffer_load_dwordx4 v207, s[44:47], s68 offen lds
	s_mov_b32 m0, s16
	s_nop 0
	buffer_load_dwordx4 v178, s[40:43], s67 offen lds
	s_mov_b32 m0, s21
	s_nop 0
	buffer_load_dwordx4 v206, s[40:43], s67 offen lds
	s_waitcnt vmcnt(8)
	s_waitcnt lgkmcnt(0)
	s_barrier
	s_setprio 1
	s_waitcnt lgkmcnt(7)
	s_waitcnt lgkmcnt(0)
	v_mfma_f32_16x16x32_bf16 v[94:97], v[106:109], v[164:167], v[94:97]
	v_mfma_f32_16x16x32_bf16 v[90:93], v[114:117], v[164:167], v[90:93]
	v_mfma_f32_16x16x32_bf16 v[82:85], v[114:117], v[182:185], v[82:85]
	v_mfma_f32_16x16x32_bf16 v[86:89], v[106:109], v[182:185], v[86:89]
	v_mfma_f32_16x16x32_bf16 v[78:81], v[106:109], v[190:193], v[78:81]
	v_mfma_f32_16x16x32_bf16 v[74:77], v[114:117], v[190:193], v[74:77]
	v_mfma_f32_16x16x32_bf16 v[66:69], v[114:117], v[198:201], v[66:69]
	v_mfma_f32_16x16x32_bf16 v[70:73], v[106:109], v[198:201], v[70:73]
	v_mfma_f32_16x16x32_bf16 v[94:97], v[110:113], v[168:171], v[94:97]
	v_mfma_f32_16x16x32_bf16 v[90:93], v[118:121], v[168:171], v[90:93]
	v_mfma_f32_16x16x32_bf16 v[82:85], v[118:121], v[186:189], v[82:85]
	v_mfma_f32_16x16x32_bf16 v[86:89], v[110:113], v[186:189], v[86:89]
	v_mfma_f32_16x16x32_bf16 v[78:81], v[110:113], v[194:197], v[78:81]
	v_mfma_f32_16x16x32_bf16 v[74:77], v[118:121], v[194:197], v[74:77]
	v_mfma_f32_16x16x32_bf16 v[66:69], v[118:121], v[202:205], v[66:69]
	v_mfma_f32_16x16x32_bf16 v[70:73], v[110:113], v[202:205], v[70:73]
	s_setprio 0
	s_setprio 1
	v_mfma_f32_16x16x32_bf16 v[30:33], v[122:125], v[164:167], v[30:33]
	v_mfma_f32_16x16x32_bf16 v[26:29], v[130:133], v[164:167], v[26:29]
	v_mfma_f32_16x16x32_bf16 v[18:21], v[130:133], v[182:185], v[18:21]
	v_mfma_f32_16x16x32_bf16 v[22:25], v[122:125], v[182:185], v[22:25]
	v_mfma_f32_16x16x32_bf16 v[14:17], v[122:125], v[190:193], v[14:17]
	v_mfma_f32_16x16x32_bf16 v[10:13], v[130:133], v[190:193], v[10:13]
	v_mfma_f32_16x16x32_bf16 v[2:5], v[130:133], v[198:201], v[2:5]
	v_mfma_f32_16x16x32_bf16 v[6:9], v[122:125], v[198:201], v[6:9]
	v_mfma_f32_16x16x32_bf16 v[30:33], v[126:129], v[168:171], v[30:33]
	v_mfma_f32_16x16x32_bf16 v[26:29], v[142:145], v[168:171], v[26:29]
	v_mfma_f32_16x16x32_bf16 v[18:21], v[142:145], v[186:189], v[18:21]
	v_mfma_f32_16x16x32_bf16 v[22:25], v[126:129], v[186:189], v[22:25]
	v_mfma_f32_16x16x32_bf16 v[14:17], v[126:129], v[194:197], v[14:17]
	v_mfma_f32_16x16x32_bf16 v[10:13], v[142:145], v[194:197], v[10:13]
	v_mfma_f32_16x16x32_bf16 v[2:5], v[142:145], v[202:205], v[2:5]
	v_mfma_f32_16x16x32_bf16 v[6:9], v[126:129], v[202:205], v[6:9]
	s_setprio 0
	s_barrier
; #define PG8_STAGEX(rs, bufoff, soff, voff) do { _Pragma("unroll") for (int _i = 0; _i < 2; ++_i) \
;         __builtin_amdgcn_raw_ptr_buffer_load_lds(rs, (LAS unsigned*)(lds + (bufoff) + ldsw + _i * 8192), 16, (voff)[_i], (soff), 0, 0); } while (0)
; #define PG8_LDA(dst, b, h) do { _Pragma("unroll") for (int m = 0; m < 4; ++m) _Pragma("unroll") for (int k = 0; k < 2; ++k) dst[m][k] = *(const LAS bf16x8*)(lds + PG8_SA(b, h) + aoff + m * 2048 + k * 1024); } while (0)
; #define PG8_LDB(dst, b, h) do { _Pragma("unroll") for (int n = 0; n < 2; ++n) _Pragma("unroll") for (int k = 0; k < 2; ++k) dst[n][k] = *(const LAS bf16x8*)(lds + PG8_SB(b, h) + boff + n * 2048 + k * 1024); } while (0)
; #define PG8_WAIT_V(n) asm volatile("s_waitcnt vmcnt(" #n ")" ::: "memory")
; #define PG8_WAIT_L(n) asm volatile("s_waitcnt lgkmcnt(" #n ")" ::: "memory")
; #define PG8_BAR __builtin_amdgcn_s_barrier()
; #define PG8_SCHED __builtin_amdgcn_sched_barrier(0)
;     ...
;             PG8_LDB(B0, 1, 0); PG8_LDB(B1, 1, 1); PG8_SCHED; PG8_LDA(At, 1, 0); PG8_STAGEX(rsA, PG8_SA(0, 1), a2 + hstepA, voffA);
;             PG8_WAIT_V(8); PG8_WAIT_L(0); PG8_BAR; PG8_MMA(0, 0, At, B0); PG8_MMA(0, 1, At, B1); PG8_BAR; PG8_SCHED;
;             PG8_LDA(At, 1, 1); PG8_STAGEX(rsB, PG8_SB(1, 0), b3, voffB); PG8_STAGEX(rsB, PG8_SB(1, 1), b3 + hstepB, voffB); PG8_STAGEX(rsA, PG8_SA(1, 0), a3, voffA);
;             PG8_WAIT_V(8); PG8_WAIT_L(0); PG8_BAR; PG8_MMA(1, 0, At, B0); PG8_MMA(1, 1, At, B1); PG8_BAR; PG8_SCHED;
;         }
	v_add_u32_e32 v118, 0x18000, v210
	v_add_u32_e32 v142, 0x1c000, v210
	ds_read_b128 v[106:109], v118
	ds_read_b128 v[110:113], v118 offset:1024
	ds_read_b128 v[114:117], v118 offset:2048
	ds_read_b128 v[118:121], v118 offset:3072
	ds_read_b128 v[122:125], v142
	ds_read_b128 v[126:129], v142 offset:1024
	ds_read_b128 v[130:133], v142 offset:2048
	ds_read_b128 v[142:145], v142 offset:3072
	s_add_i32 s67, s67, 0x80000
	s_mov_b32 m0, s22
	ds_read_b128 v[164:167], v211 offset:32768
	ds_read_b128 v[168:171], v211 offset:33792
	ds_read_b128 v[182:185], v211 offset:34816
	ds_read_b128 v[186:189], v211 offset:35840
	ds_read_b128 v[190:193], v211 offset:36864
	ds_read_b128 v[194:197], v211 offset:37888
	ds_read_b128 v[198:201], v211 offset:38912
	ds_read_b128 v[202:205], v211 offset:39936
	buffer_load_dwordx4 v178, s[40:43], s67 offen lds
	s_mov_b32 m0, s23
	s_nop 0
	buffer_load_dwordx4 v206, s[40:43], s67 offen lds
	s_waitcnt vmcnt(8)
	s_waitcnt lgkmcnt(0)
	s_barrier
	s_setprio 1
	s_waitcnt lgkmcnt(7)
	s_waitcnt lgkmcnt(0)
	v_mfma_f32_16x16x32_bf16 v[158:161], v[106:109], v[164:167], v[158:161]
	v_mfma_f32_16x16x32_bf16 v[154:157], v[114:117], v[164:167], v[154:157]
	v_mfma_f32_16x16x32_bf16 v[146:149], v[114:117], v[182:185], v[146:149]
	v_mfma_f32_16x16x32_bf16 v[150:153], v[106:109], v[182:185], v[150:153]
	v_mfma_f32_16x16x32_bf16 v[138:141], v[106:109], v[190:193], v[138:141]
	v_mfma_f32_16x16x32_bf16 v[134:137], v[114:117], v[190:193], v[134:137]
	v_mfma_f32_16x16x32_bf16 v[98:101], v[114:117], v[198:201], v[98:101]
	v_mfma_f32_16x16x32_bf16 v[102:105], v[106:109], v[198:201], v[102:105]
	v_mfma_f32_16x16x32_bf16 v[158:161], v[110:113], v[168:171], v[158:161]
	v_mfma_f32_16x16x32_bf16 v[154:157], v[118:121], v[168:171], v[154:157]
	v_mfma_f32_16x16x32_bf16 v[146:149], v[118:121], v[186:189], v[146:149]
	v_mfma_f32_16x16x32_bf16 v[150:153], v[110:113], v[186:189], v[150:153]
	v_mfma_f32_16x16x32_bf16 v[138:141], v[110:113], v[194:197], v[138:141]
	v_mfma_f32_16x16x32_bf16 v[134:137], v[118:121], v[194:197], v[134:137]
	v_mfma_f32_16x16x32_bf16 v[98:101], v[118:121], v[202:205], v[98:101]
	v_mfma_f32_16x16x32_bf16 v[102:105], v[110:113], v[202:205], v[102:105]
	s_setprio 0
	s_setprio 1
	v_mfma_f32_16x16x32_bf16 v[62:65], v[122:125], v[164:167], v[62:65]
	v_mfma_f32_16x16x32_bf16 v[58:61], v[130:133], v[164:167], v[58:61]
	v_mfma_f32_16x16x32_bf16 v[50:53], v[130:133], v[182:185], v[50:53]
	v_mfma_f32_16x16x32_bf16 v[54:57], v[122:125], v[182:185], v[54:57]
	v_mfma_f32_16x16x32_bf16 v[46:49], v[122:125], v[190:193], v[46:49]
	v_mfma_f32_16x16x32_bf16 v[42:45], v[130:133], v[190:193], v[42:45]
	v_mfma_f32_16x16x32_bf16 v[34:37], v[130:133], v[198:201], v[34:37]
	v_mfma_f32_16x16x32_bf16 v[38:41], v[122:125], v[198:201], v[38:41]
	v_mfma_f32_16x16x32_bf16 v[62:65], v[126:129], v[168:171], v[62:65]
	v_mfma_f32_16x16x32_bf16 v[58:61], v[142:145], v[168:171], v[58:61]
	v_mfma_f32_16x16x32_bf16 v[50:53], v[142:145], v[186:189], v[50:53]
	v_mfma_f32_16x16x32_bf16 v[54:57], v[126:129], v[186:189], v[54:57]
	v_mfma_f32_16x16x32_bf16 v[46:49], v[126:129], v[194:197], v[46:49]
	v_mfma_f32_16x16x32_bf16 v[42:45], v[142:145], v[194:197], v[42:45]
	v_mfma_f32_16x16x32_bf16 v[34:37], v[142:145], v[202:205], v[34:37]
	v_mfma_f32_16x16x32_bf16 v[38:41], v[126:129], v[202:205], v[38:41]
	s_setprio 0
	s_barrier
	s_mov_b32 m0, s54
	s_or_b32 s67, s66, 0x80
	ds_read_b128 v[164:167], v211 offset:49152
	ds_read_b128 v[168:171], v211 offset:50176
	ds_read_b128 v[182:185], v211 offset:51200
	ds_read_b128 v[186:189], v211 offset:52224
	ds_read_b128 v[190:193], v211 offset:53248
	ds_read_b128 v[194:197], v211 offset:54272
	ds_read_b128 v[198:201], v211 offset:55296
	ds_read_b128 v[202:205], v211 offset:56320
	buffer_load_dwordx4 v179, s[44:47], s67 offen lds
	s_mov_b32 m0, s55
	s_add_i32 s66, s66, 0x80080
	buffer_load_dwordx4 v207, s[44:47], s67 offen lds
	s_mov_b32 m0, s74
	s_nop 0
	buffer_load_dwordx4 v179, s[44:47], s66 offen lds
	s_mov_b32 m0, s75
	s_nop 0
	buffer_load_dwordx4 v207, s[44:47], s66 offen lds
	s_mov_b32 m0, s72
	s_nop 0
	buffer_load_dwordx4 v178, s[40:43], s65 offen lds
	s_mov_b32 m0, s73
	s_nop 0
	buffer_load_dwordx4 v206, s[40:43], s65 offen lds
	s_waitcnt vmcnt(8)
	s_waitcnt lgkmcnt(0)
	s_barrier
	s_setprio 1
	s_waitcnt lgkmcnt(7)
	s_waitcnt lgkmcnt(0)
	v_mfma_f32_16x16x32_bf16 v[94:97], v[106:109], v[164:167], v[94:97]
	v_mfma_f32_16x16x32_bf16 v[90:93], v[114:117], v[164:167], v[90:93]
	v_mfma_f32_16x16x32_bf16 v[82:85], v[114:117], v[182:185], v[82:85]
	v_mfma_f32_16x16x32_bf16 v[86:89], v[106:109], v[182:185], v[86:89]
	v_mfma_f32_16x16x32_bf16 v[78:81], v[106:109], v[190:193], v[78:81]
	v_mfma_f32_16x16x32_bf16 v[74:77], v[114:117], v[190:193], v[74:77]
	v_mfma_f32_16x16x32_bf16 v[66:69], v[114:117], v[198:201], v[66:69]
	v_mfma_f32_16x16x32_bf16 v[70:73], v[106:109], v[198:201], v[70:73]
	v_mfma_f32_16x16x32_bf16 v[94:97], v[110:113], v[168:171], v[94:97]
	v_mfma_f32_16x16x32_bf16 v[90:93], v[118:121], v[168:171], v[90:93]
	v_mfma_f32_16x16x32_bf16 v[82:85], v[118:121], v[186:189], v[82:85]
	v_mfma_f32_16x16x32_bf16 v[86:89], v[110:113], v[186:189], v[86:89]
	v_mfma_f32_16x16x32_bf16 v[78:81], v[110:113], v[194:197], v[78:81]
	v_mfma_f32_16x16x32_bf16 v[74:77], v[118:121], v[194:197], v[74:77]
	v_mfma_f32_16x16x32_bf16 v[66:69], v[118:121], v[202:205], v[66:69]
	v_mfma_f32_16x16x32_bf16 v[70:73], v[110:113], v[202:205], v[70:73]
	s_setprio 0
	s_setprio 1
	v_mfma_f32_16x16x32_bf16 v[30:33], v[122:125], v[164:167], v[30:33]
	v_mfma_f32_16x16x32_bf16 v[26:29], v[130:133], v[164:167], v[26:29]
	v_mfma_f32_16x16x32_bf16 v[18:21], v[130:133], v[182:185], v[18:21]
	v_mfma_f32_16x16x32_bf16 v[22:25], v[122:125], v[182:185], v[22:25]
	v_mfma_f32_16x16x32_bf16 v[14:17], v[122:125], v[190:193], v[14:17]
	v_mfma_f32_16x16x32_bf16 v[10:13], v[130:133], v[190:193], v[10:13]
	v_mfma_f32_16x16x32_bf16 v[2:5], v[130:133], v[198:201], v[2:5]
	v_mfma_f32_16x16x32_bf16 v[6:9], v[122:125], v[198:201], v[6:9]
	v_mfma_f32_16x16x32_bf16 v[30:33], v[126:129], v[168:171], v[30:33]
	v_mfma_f32_16x16x32_bf16 v[26:29], v[142:145], v[168:171], v[26:29]
	v_mfma_f32_16x16x32_bf16 v[18:21], v[142:145], v[186:189], v[18:21]
	v_mfma_f32_16x16x32_bf16 v[22:25], v[126:129], v[186:189], v[22:25]
	v_mfma_f32_16x16x32_bf16 v[14:17], v[126:129], v[194:197], v[14:17]
	v_mfma_f32_16x16x32_bf16 v[10:13], v[142:145], v[194:197], v[10:13]
	v_mfma_f32_16x16x32_bf16 v[2:5], v[142:145], v[202:205], v[2:5]
	v_mfma_f32_16x16x32_bf16 v[6:9], v[126:129], v[202:205], v[6:9]
	s_setprio 0
	s_barrier
	s_add_i32 s64, s64, 2
	s_addk_i32 s59, 0x100
	s_addk_i32 s63, 0x100
	s_cmp_gt_u32 s64, 29
	s_cbranch_scc0 .LBB0_1529
	s_and_b64 vcc, exec, s[52:53]
	s_cbranch_vccz .LBB0_1532
	s_barrier

; #define PG8_STAGEX(rs, bufoff, soff, voff) do { _Pragma("unroll") for (int _i = 0; _i < 2; ++_i) \
;         __builtin_amdgcn_raw_ptr_buffer_load_lds(rs, (LAS unsigned*)(lds + (bufoff) + ldsw + _i * 8192), 16, (voff)[_i], (soff), 0, 0); } while (0)
; #define PG8_LDA(dst, b, h) do { _Pragma("unroll") for (int m = 0; m < 4; ++m) _Pragma("unroll") for (int k = 0; k < 2; ++k) dst[m][k] = *(const LAS bf16x8*)(lds + PG8_SA(b, h) + aoff + m * 2048 + k * 1024); } while (0)
; #define PG8_LDB(dst, b, h) do { _Pragma("unroll") for (int n = 0; n < 2; ++n) _Pragma("unroll") for (int k = 0; k < 2; ++k) dst[n][k] = *(const LAS bf16x8*)(lds + PG8_SB(b, h) + boff + n * 2048 + k * 1024); } while (0)
; #define PG8_WAIT_V(n) asm volatile("s_waitcnt vmcnt(" #n ")" ::: "memory")
; #define PG8_WAIT_L(n) asm volatile("s_waitcnt lgkmcnt(" #n ")" ::: "memory")
; #define PG8_BAR __builtin_amdgcn_s_barrier()
; #define PG8_SCHED __builtin_amdgcn_sched_barrier(0)
;     ...
;             PG8_LDB(B0, 0, 0); PG8_LDB(B1, 0, 1); PG8_SCHED; PG8_LDA(At, 0, 0); PG8_STAGEX(rsA, PG8_SA(1, 1), a1 + hstepA, voffA);
;             PG8_WAIT_V(8); PG8_WAIT_L(0); PG8_BAR; PG8_MMA(0, 0, At, B0); PG8_MMA(0, 1, At, B1); PG8_BAR; PG8_SCHED;
;             PG8_LDA(At, 0, 1); PG8_STAGEX(rsB, PG8_SB(0, 0), b2, voffB); PG8_STAGEX(rsB, PG8_SB(0, 1), b2 + hstepB, voffB); PG8_STAGEX(rsA, PG8_SA(0, 0), a2, voffA);
;             PG8_WAIT_V(8); PG8_WAIT_L(0); PG8_BAR; PG8_MMA(1, 0, At, B0); PG8_MMA(1, 1, At, B1); PG8_BAR; PG8_SCHED;
.LBB0_1651:
	v_add_u32_e32 v102, 0x10000, v172
	v_add_u32_e32 v146, 0x14000, v172
	ds_read_b128 v[82:85], v102
	ds_read_b128 v[86:89], v102 offset:1024
	ds_read_b128 v[98:101], v102 offset:2048
	ds_read_b128 v[102:105], v102 offset:3072
	ds_read_b128 v[150:153], v146
	ds_read_b128 v[154:157], v146 offset:1024
	ds_read_b128 v[182:185], v146 offset:2048
	ds_read_b128 v[186:189], v146 offset:3072
	s_add_i32 s42, s61, 0xfff80080
	s_cmp_eq_u32 s63, 28
	s_cselect_b32 s66, s30, s42
	s_cselect_b32 s65, s31, s62
	s_or_b32 s64, s66, 0x80
	s_mov_b32 m0, s29
	ds_read_b128 v[190:193], v173
	ds_read_b128 v[194:197], v173 offset:1024
	ds_read_b128 v[198:201], v173 offset:2048
	ds_read_b128 v[202:205], v173 offset:3072
	ds_read_b128 v[206:209], v173 offset:4096
	ds_read_b128 v[210:213], v173 offset:5120
	ds_read_b128 v[214:217], v173 offset:6144
	ds_read_b128 v[218:221], v173 offset:7168
	buffer_load_dwordx4 v159, s[76:79], s61 offen lds
	s_mov_b32 m0, s50
	s_nop 0
	buffer_load_dwordx4 v163, s[76:79], s61 offen lds
	s_waitcnt vmcnt(8)
	s_waitcnt lgkmcnt(0)
	s_barrier
	s_setprio 1
	s_waitcnt lgkmcnt(7)
	s_waitcnt lgkmcnt(0)
	v_mfma_f32_16x16x32_bf16 v[142:145], v[82:85], v[190:193], v[142:145]
	v_mfma_f32_16x16x32_bf16 v[134:137], v[98:101], v[190:193], v[134:137]
	v_mfma_f32_16x16x32_bf16 v[118:121], v[98:101], v[198:201], v[118:121]
	v_mfma_f32_16x16x32_bf16 v[126:129], v[82:85], v[198:201], v[126:129]
	v_mfma_f32_16x16x32_bf16 v[110:113], v[82:85], v[206:209], v[110:113]
	v_mfma_f32_16x16x32_bf16 v[94:97], v[98:101], v[206:209], v[94:97]
	v_mfma_f32_16x16x32_bf16 v[70:73], v[98:101], v[214:217], v[70:73]
	v_mfma_f32_16x16x32_bf16 v[78:81], v[82:85], v[214:217], v[78:81]
	v_mfma_f32_16x16x32_bf16 v[142:145], v[86:89], v[194:197], v[142:145]
	v_mfma_f32_16x16x32_bf16 v[134:137], v[102:105], v[194:197], v[134:137]
	v_mfma_f32_16x16x32_bf16 v[118:121], v[102:105], v[202:205], v[118:121]
	v_mfma_f32_16x16x32_bf16 v[126:129], v[86:89], v[202:205], v[126:129]
	v_mfma_f32_16x16x32_bf16 v[110:113], v[86:89], v[210:213], v[110:113]
	v_mfma_f32_16x16x32_bf16 v[94:97], v[102:105], v[210:213], v[94:97]
	v_mfma_f32_16x16x32_bf16 v[70:73], v[102:105], v[218:221], v[70:73]
	v_mfma_f32_16x16x32_bf16 v[78:81], v[86:89], v[218:221], v[78:81]
	s_setprio 0
	s_setprio 1
	v_mfma_f32_16x16x32_bf16 v[138:141], v[150:153], v[190:193], v[138:141]
	v_mfma_f32_16x16x32_bf16 v[130:133], v[182:185], v[190:193], v[130:133]
	v_mfma_f32_16x16x32_bf16 v[114:117], v[182:185], v[198:201], v[114:117]
	v_mfma_f32_16x16x32_bf16 v[122:125], v[150:153], v[198:201], v[122:125]
	v_mfma_f32_16x16x32_bf16 v[106:109], v[150:153], v[206:209], v[106:109]
	v_mfma_f32_16x16x32_bf16 v[90:93], v[182:185], v[206:209], v[90:93]
	v_mfma_f32_16x16x32_bf16 v[66:69], v[182:185], v[214:217], v[66:69]
	v_mfma_f32_16x16x32_bf16 v[74:77], v[150:153], v[214:217], v[74:77]
	v_mfma_f32_16x16x32_bf16 v[138:141], v[154:157], v[194:197], v[138:141]
	v_mfma_f32_16x16x32_bf16 v[130:133], v[186:189], v[194:197], v[130:133]
	v_mfma_f32_16x16x32_bf16 v[114:117], v[186:189], v[202:205], v[114:117]
	v_mfma_f32_16x16x32_bf16 v[122:125], v[154:157], v[202:205], v[122:125]
	v_mfma_f32_16x16x32_bf16 v[106:109], v[154:157], v[210:213], v[106:109]
	v_mfma_f32_16x16x32_bf16 v[90:93], v[186:189], v[210:213], v[90:93]
	v_mfma_f32_16x16x32_bf16 v[66:69], v[186:189], v[218:221], v[66:69]
	v_mfma_f32_16x16x32_bf16 v[74:77], v[154:157], v[218:221], v[74:77]
	s_setprio 0
	s_barrier
	s_mov_b32 m0, s16
	s_mov_b32 s42, s78
	s_mov_b32 s43, s79
	ds_read_b128 v[190:193], v173 offset:16384
	ds_read_b128 v[194:197], v173 offset:17408
	ds_read_b128 v[198:201], v173 offset:18432
	ds_read_b128 v[202:205], v173 offset:19456
	ds_read_b128 v[206:209], v173 offset:20480
	ds_read_b128 v[210:213], v173 offset:21504
	ds_read_b128 v[214:217], v173 offset:22528
	ds_read_b128 v[218:221], v173 offset:23552
	buffer_load_dwordx4 v161, s[40:43], s65 offen lds
	s_mov_b32 m0, s17
	s_add_i32 s67, s65, 0x80000
	buffer_load_dwordx4 v165, s[40:43], s65 offen lds
	s_mov_b32 m0, s18
	s_nop 0
	buffer_load_dwordx4 v161, s[40:43], s67 offen lds
	s_mov_b32 m0, s19
	s_nop 0
	buffer_load_dwordx4 v165, s[40:43], s67 offen lds
	s_mov_b32 m0, s15
	s_nop 0
	buffer_load_dwordx4 v159, s[76:79], s66 offen lds
	s_mov_b32 m0, s20
	s_nop 0
	buffer_load_dwordx4 v163, s[76:79], s66 offen lds
	s_waitcnt vmcnt(8)
	s_waitcnt lgkmcnt(0)
	s_barrier
	s_setprio 1
	s_waitcnt lgkmcnt(7)
	s_waitcnt lgkmcnt(0)
	v_mfma_f32_16x16x32_bf16 v[62:65], v[82:85], v[190:193], v[62:65]
	v_mfma_f32_16x16x32_bf16 v[54:57], v[98:101], v[190:193], v[54:57]
	v_mfma_f32_16x16x32_bf16 v[38:41], v[98:101], v[198:201], v[38:41]
	v_mfma_f32_16x16x32_bf16 v[46:49], v[82:85], v[198:201], v[46:49]
	v_mfma_f32_16x16x32_bf16 v[30:33], v[82:85], v[206:209], v[30:33]
	v_mfma_f32_16x16x32_bf16 v[22:25], v[98:101], v[206:209], v[22:25]
	v_mfma_f32_16x16x32_bf16 v[6:9], v[98:101], v[214:217], v[6:9]
	v_mfma_f32_16x16x32_bf16 v[14:17], v[82:85], v[214:217], v[14:17]
	v_mfma_f32_16x16x32_bf16 v[62:65], v[86:89], v[194:197], v[62:65]
	v_mfma_f32_16x16x32_bf16 v[54:57], v[102:105], v[194:197], v[54:57]
	v_mfma_f32_16x16x32_bf16 v[38:41], v[102:105], v[202:205], v[38:41]
	v_mfma_f32_16x16x32_bf16 v[46:49], v[86:89], v[202:205], v[46:49]
	v_mfma_f32_16x16x32_bf16 v[30:33], v[86:89], v[210:213], v[30:33]
	v_mfma_f32_16x16x32_bf16 v[22:25], v[102:105], v[210:213], v[22:25]
	v_mfma_f32_16x16x32_bf16 v[6:9], v[102:105], v[218:221], v[6:9]
	v_mfma_f32_16x16x32_bf16 v[14:17], v[86:89], v[218:221], v[14:17]
	s_setprio 0
	s_setprio 1
	v_mfma_f32_16x16x32_bf16 v[58:61], v[150:153], v[190:193], v[58:61]
	v_mfma_f32_16x16x32_bf16 v[50:53], v[182:185], v[190:193], v[50:53]
	v_mfma_f32_16x16x32_bf16 v[34:37], v[182:185], v[198:201], v[34:37]
	v_mfma_f32_16x16x32_bf16 v[42:45], v[150:153], v[198:201], v[42:45]
	v_mfma_f32_16x16x32_bf16 v[26:29], v[150:153], v[206:209], v[26:29]
	v_mfma_f32_16x16x32_bf16 v[18:21], v[182:185], v[206:209], v[18:21]
	v_mfma_f32_16x16x32_bf16 v[2:5], v[182:185], v[214:217], v[2:5]
	v_mfma_f32_16x16x32_bf16 v[10:13], v[150:153], v[214:217], v[10:13]
	v_mfma_f32_16x16x32_bf16 v[58:61], v[154:157], v[194:197], v[58:61]
	v_mfma_f32_16x16x32_bf16 v[50:53], v[186:189], v[194:197], v[50:53]
	v_mfma_f32_16x16x32_bf16 v[34:37], v[186:189], v[202:205], v[34:37]
	v_mfma_f32_16x16x32_bf16 v[42:45], v[154:157], v[202:205], v[42:45]
	v_mfma_f32_16x16x32_bf16 v[26:29], v[154:157], v[210:213], v[26:29]
	v_mfma_f32_16x16x32_bf16 v[18:21], v[186:189], v[210:213], v[18:21]
	v_mfma_f32_16x16x32_bf16 v[2:5], v[186:189], v[218:221], v[2:5]
	v_mfma_f32_16x16x32_bf16 v[10:13], v[154:157], v[218:221], v[10:13]
	s_setprio 0
	s_barrier
; #define PG8_STAGEX(rs, bufoff, soff, voff) do { _Pragma("unroll") for (int _i = 0; _i < 2; ++_i) \
;         __builtin_amdgcn_raw_ptr_buffer_load_lds(rs, (LAS unsigned*)(lds + (bufoff) + ldsw + _i * 8192), 16, (voff)[_i], (soff), 0, 0); } while (0)
; #define PG8_LDA(dst, b, h) do { _Pragma("unroll") for (int m = 0; m < 4; ++m) _Pragma("unroll") for (int k = 0; k < 2; ++k) dst[m][k] = *(const LAS bf16x8*)(lds + PG8_SA(b, h) + aoff + m * 2048 + k * 1024); } while (0)
; #define PG8_LDB(dst, b, h) do { _Pragma("unroll") for (int n = 0; n < 2; ++n) _Pragma("unroll") for (int k = 0; k < 2; ++k) dst[n][k] = *(const LAS bf16x8*)(lds + PG8_SB(b, h) + boff + n * 2048 + k * 1024); } while (0)
; #define PG8_WAIT_V(n) asm volatile("s_waitcnt vmcnt(" #n ")" ::: "memory")
; #define PG8_WAIT_L(n) asm volatile("s_waitcnt lgkmcnt(" #n ")" ::: "memory")
; #define PG8_BAR __builtin_amdgcn_s_barrier()
; #define PG8_SCHED __builtin_amdgcn_sched_barrier(0)
;     ...
;             PG8_LDB(B0, 1, 0); PG8_LDB(B1, 1, 1); PG8_SCHED; PG8_LDA(At, 1, 0); PG8_STAGEX(rsA, PG8_SA(0, 1), a2 + hstepA, voffA);
;             PG8_WAIT_V(8); PG8_WAIT_L(0); PG8_BAR; PG8_MMA(0, 0, At, B0); PG8_MMA(0, 1, At, B1); PG8_BAR; PG8_SCHED;
;             PG8_LDA(At, 1, 1); PG8_STAGEX(rsB, PG8_SB(1, 0), b3, voffB); PG8_STAGEX(rsB, PG8_SB(1, 1), b3 + hstepB, voffB); PG8_STAGEX(rsA, PG8_SA(1, 0), a3, voffA);
;             PG8_WAIT_V(8); PG8_WAIT_L(0); PG8_BAR; PG8_MMA(1, 0, At, B0); PG8_MMA(1, 1, At, B1); PG8_BAR; PG8_SCHED;
;         }
	v_add_u32_e32 v102, 0x18000, v172
	v_add_u32_e32 v146, 0x1c000, v172
	ds_read_b128 v[82:85], v102
	ds_read_b128 v[86:89], v102 offset:1024
	ds_read_b128 v[98:101], v102 offset:2048
	ds_read_b128 v[102:105], v102 offset:3072
	ds_read_b128 v[150:153], v146
	ds_read_b128 v[154:157], v146 offset:1024
	ds_read_b128 v[182:185], v146 offset:2048
	ds_read_b128 v[186:189], v146 offset:3072
	s_add_i32 s66, s66, 0x80000
	s_mov_b32 m0, s21
	ds_read_b128 v[190:193], v173 offset:32768
	ds_read_b128 v[194:197], v173 offset:33792
	ds_read_b128 v[198:201], v173 offset:34816
	ds_read_b128 v[202:205], v173 offset:35840
	ds_read_b128 v[206:209], v173 offset:36864
	ds_read_b128 v[210:213], v173 offset:37888
	ds_read_b128 v[214:217], v173 offset:38912
	ds_read_b128 v[218:221], v173 offset:39936
	buffer_load_dwordx4 v159, s[76:79], s66 offen lds
	s_mov_b32 m0, s22
	s_nop 0
	buffer_load_dwordx4 v163, s[76:79], s66 offen lds
	s_waitcnt vmcnt(8)
	s_waitcnt lgkmcnt(0)
	s_barrier
	s_setprio 1
	s_waitcnt lgkmcnt(7)
	s_waitcnt lgkmcnt(0)
	v_mfma_f32_16x16x32_bf16 v[142:145], v[82:85], v[190:193], v[142:145]
	v_mfma_f32_16x16x32_bf16 v[134:137], v[98:101], v[190:193], v[134:137]
	v_mfma_f32_16x16x32_bf16 v[118:121], v[98:101], v[198:201], v[118:121]
	v_mfma_f32_16x16x32_bf16 v[126:129], v[82:85], v[198:201], v[126:129]
	v_mfma_f32_16x16x32_bf16 v[110:113], v[82:85], v[206:209], v[110:113]
	v_mfma_f32_16x16x32_bf16 v[94:97], v[98:101], v[206:209], v[94:97]
	v_mfma_f32_16x16x32_bf16 v[70:73], v[98:101], v[214:217], v[70:73]
	v_mfma_f32_16x16x32_bf16 v[78:81], v[82:85], v[214:217], v[78:81]
	v_mfma_f32_16x16x32_bf16 v[142:145], v[86:89], v[194:197], v[142:145]
	v_mfma_f32_16x16x32_bf16 v[134:137], v[102:105], v[194:197], v[134:137]
	v_mfma_f32_16x16x32_bf16 v[118:121], v[102:105], v[202:205], v[118:121]
	v_mfma_f32_16x16x32_bf16 v[126:129], v[86:89], v[202:205], v[126:129]
	v_mfma_f32_16x16x32_bf16 v[110:113], v[86:89], v[210:213], v[110:113]
	v_mfma_f32_16x16x32_bf16 v[94:97], v[102:105], v[210:213], v[94:97]
	v_mfma_f32_16x16x32_bf16 v[70:73], v[102:105], v[218:221], v[70:73]
	v_mfma_f32_16x16x32_bf16 v[78:81], v[86:89], v[218:221], v[78:81]
	s_setprio 0
	s_setprio 1
	v_mfma_f32_16x16x32_bf16 v[138:141], v[150:153], v[190:193], v[138:141]
	v_mfma_f32_16x16x32_bf16 v[130:133], v[182:185], v[190:193], v[130:133]
	v_mfma_f32_16x16x32_bf16 v[114:117], v[182:185], v[198:201], v[114:117]
	v_mfma_f32_16x16x32_bf16 v[122:125], v[150:153], v[198:201], v[122:125]
	v_mfma_f32_16x16x32_bf16 v[106:109], v[150:153], v[206:209], v[106:109]
	v_mfma_f32_16x16x32_bf16 v[90:93], v[182:185], v[206:209], v[90:93]
	v_mfma_f32_16x16x32_bf16 v[66:69], v[182:185], v[214:217], v[66:69]
	v_mfma_f32_16x16x32_bf16 v[74:77], v[150:153], v[214:217], v[74:77]
	v_mfma_f32_16x16x32_bf16 v[138:141], v[154:157], v[194:197], v[138:141]
	v_mfma_f32_16x16x32_bf16 v[130:133], v[186:189], v[194:197], v[130:133]
	v_mfma_f32_16x16x32_bf16 v[114:117], v[186:189], v[202:205], v[114:117]
	v_mfma_f32_16x16x32_bf16 v[122:125], v[154:157], v[202:205], v[122:125]
	v_mfma_f32_16x16x32_bf16 v[106:109], v[154:157], v[210:213], v[106:109]
	v_mfma_f32_16x16x32_bf16 v[90:93], v[186:189], v[210:213], v[90:93]
	v_mfma_f32_16x16x32_bf16 v[66:69], v[186:189], v[218:221], v[66:69]
	v_mfma_f32_16x16x32_bf16 v[74:77], v[154:157], v[218:221], v[74:77]
	s_setprio 0
	s_barrier
	s_mov_b32 m0, s23
	s_or_b32 s66, s65, 0x80
	ds_read_b128 v[190:193], v173 offset:49152
	ds_read_b128 v[194:197], v173 offset:50176
	ds_read_b128 v[198:201], v173 offset:51200
	ds_read_b128 v[202:205], v173 offset:52224
	ds_read_b128 v[206:209], v173 offset:53248
	ds_read_b128 v[210:213], v173 offset:54272
	ds_read_b128 v[214:217], v173 offset:55296
	ds_read_b128 v[218:221], v173 offset:56320
	buffer_load_dwordx4 v161, s[40:43], s66 offen lds
	s_mov_b32 m0, s24
	s_add_i32 s65, s65, 0x80080
	buffer_load_dwordx4 v165, s[40:43], s66 offen lds
	s_mov_b32 m0, s27
	s_nop 0
	buffer_load_dwordx4 v161, s[40:43], s65 offen lds
	s_mov_b32 m0, s28
	s_nop 0
	buffer_load_dwordx4 v165, s[40:43], s65 offen lds
	s_mov_b32 m0, s25
	s_nop 0
	buffer_load_dwordx4 v159, s[76:79], s64 offen lds
	s_mov_b32 m0, s26
	s_nop 0
	buffer_load_dwordx4 v163, s[76:79], s64 offen lds
	s_waitcnt vmcnt(8)
	s_waitcnt lgkmcnt(0)
	s_barrier
	s_setprio 1
	s_waitcnt lgkmcnt(7)
	s_waitcnt lgkmcnt(0)
	v_mfma_f32_16x16x32_bf16 v[62:65], v[82:85], v[190:193], v[62:65]
	v_mfma_f32_16x16x32_bf16 v[54:57], v[98:101], v[190:193], v[54:57]
	v_mfma_f32_16x16x32_bf16 v[38:41], v[98:101], v[198:201], v[38:41]
	v_mfma_f32_16x16x32_bf16 v[46:49], v[82:85], v[198:201], v[46:49]
	v_mfma_f32_16x16x32_bf16 v[30:33], v[82:85], v[206:209], v[30:33]
	v_mfma_f32_16x16x32_bf16 v[22:25], v[98:101], v[206:209], v[22:25]
	v_mfma_f32_16x16x32_bf16 v[6:9], v[98:101], v[214:217], v[6:9]
	v_mfma_f32_16x16x32_bf16 v[14:17], v[82:85], v[214:217], v[14:17]
	v_mfma_f32_16x16x32_bf16 v[62:65], v[86:89], v[194:197], v[62:65]
	v_mfma_f32_16x16x32_bf16 v[54:57], v[102:105], v[194:197], v[54:57]
	v_mfma_f32_16x16x32_bf16 v[38:41], v[102:105], v[202:205], v[38:41]
	v_mfma_f32_16x16x32_bf16 v[46:49], v[86:89], v[202:205], v[46:49]
	v_mfma_f32_16x16x32_bf16 v[30:33], v[86:89], v[210:213], v[30:33]
	v_mfma_f32_16x16x32_bf16 v[22:25], v[102:105], v[210:213], v[22:25]
	v_mfma_f32_16x16x32_bf16 v[6:9], v[102:105], v[218:221], v[6:9]
	v_mfma_f32_16x16x32_bf16 v[14:17], v[86:89], v[218:221], v[14:17]
	s_setprio 0
	s_setprio 1
	v_mfma_f32_16x16x32_bf16 v[58:61], v[150:153], v[190:193], v[58:61]
	v_mfma_f32_16x16x32_bf16 v[50:53], v[182:185], v[190:193], v[50:53]
	v_mfma_f32_16x16x32_bf16 v[34:37], v[182:185], v[198:201], v[34:37]
	v_mfma_f32_16x16x32_bf16 v[42:45], v[150:153], v[198:201], v[42:45]
	v_mfma_f32_16x16x32_bf16 v[26:29], v[150:153], v[206:209], v[26:29]
	v_mfma_f32_16x16x32_bf16 v[18:21], v[182:185], v[206:209], v[18:21]
	v_mfma_f32_16x16x32_bf16 v[2:5], v[182:185], v[214:217], v[2:5]
	v_mfma_f32_16x16x32_bf16 v[10:13], v[150:153], v[214:217], v[10:13]
	v_mfma_f32_16x16x32_bf16 v[58:61], v[154:157], v[194:197], v[58:61]
	v_mfma_f32_16x16x32_bf16 v[50:53], v[186:189], v[194:197], v[50:53]
	v_mfma_f32_16x16x32_bf16 v[34:37], v[186:189], v[202:205], v[34:37]
	v_mfma_f32_16x16x32_bf16 v[42:45], v[154:157], v[202:205], v[42:45]
	v_mfma_f32_16x16x32_bf16 v[26:29], v[154:157], v[210:213], v[26:29]
	v_mfma_f32_16x16x32_bf16 v[18:21], v[186:189], v[210:213], v[18:21]
	v_mfma_f32_16x16x32_bf16 v[2:5], v[186:189], v[218:221], v[2:5]
	v_mfma_f32_16x16x32_bf16 v[10:13], v[154:157], v[218:221], v[10:13]
	s_setprio 0
	s_barrier
	s_add_i32 s63, s63, 2
	s_addk_i32 s61, 0x100
	s_addk_i32 s62, 0x100
	s_cmp_gt_u32 s63, 29
	s_cbranch_scc0 .LBB0_1651
	s_and_b64 vcc, exec, s[48:49]
	s_cbranch_vccz .LBB0_1654
	s_barrier

; #define PG8_STAGEX(rs, bufoff, soff, voff) do { _Pragma("unroll") for (int _i = 0; _i < 2; ++_i) \
;         __builtin_amdgcn_raw_ptr_buffer_load_lds(rs, (LAS unsigned*)(lds + (bufoff) + ldsw + _i * 8192), 16, (voff)[_i], (soff), 0, 0); } while (0)
; #define PG8_LDA(dst, b, h) do { _Pragma("unroll") for (int m = 0; m < 4; ++m) _Pragma("unroll") for (int k = 0; k < 2; ++k) dst[m][k] = *(const LAS bf16x8*)(lds + PG8_SA(b, h) + aoff + m * 2048 + k * 1024); } while (0)
; #define PG8_LDB(dst, b, h) do { _Pragma("unroll") for (int n = 0; n < 2; ++n) _Pragma("unroll") for (int k = 0; k < 2; ++k) dst[n][k] = *(const LAS bf16x8*)(lds + PG8_SB(b, h) + boff + n * 2048 + k * 1024); } while (0)
; #define PG8_WAIT_V(n) asm volatile("s_waitcnt vmcnt(" #n ")" ::: "memory")
; #define PG8_WAIT_L(n) asm volatile("s_waitcnt lgkmcnt(" #n ")" ::: "memory")
; #define PG8_BAR __builtin_amdgcn_s_barrier()
; #define PG8_SCHED __builtin_amdgcn_sched_barrier(0)
;     ...
;                 if (w0) { PG8_LDB(B0, 0, 0); PG8_LDB(B1, 0, 1); PG8_SCHED; PG8_LDA(At, 0, 0); }
;                 PG8_WAIT_L(0); PG8_BAR; if (w0) { PG8_MMA(0, 0, At, B0); PG8_MMA(0, 1, At, B1); } PG8_BAR; PG8_SCHED;
;                 PG8_STAGEX(rsB, PG8_SB(0, 0), b2, voffB); PG8_STAGEX(rsB, PG8_SB(0, 1), b2 + hstepB, voffB); PG8_STAGEX(rsA, PG8_SA(0, 0), a2, voffA);
;                 PG8_WAIT_V(6); PG8_BAR; PG8_BAR; PG8_SCHED;
.LBB0_1668:
	v_add_u32_e32 v86, 0x10000, v72
	v_add_u32_e32 v102, 0x14000, v72
	ds_read_b128 v[74:77], v86
	ds_read_b128 v[78:81], v86 offset:1024
	ds_read_b128 v[82:85], v86 offset:2048
	ds_read_b128 v[86:89], v86 offset:3072
	ds_read_b128 v[90:93], v102
	ds_read_b128 v[94:97], v102 offset:1024
	ds_read_b128 v[98:101], v102 offset:2048
	ds_read_b128 v[102:105], v102 offset:3072
	s_cmp_lg_u32 s27, 28
	s_cselect_b32 s28, s26, 0
	s_add_i32 s29, s28, s17
	s_or_b32 s30, s29, 0x80
	s_add_i32 s28, s28, s10
	ds_read_b128 v[106:109], v73
	ds_read_b128 v[110:113], v73 offset:1024
	ds_read_b128 v[114:117], v73 offset:2048
	ds_read_b128 v[118:121], v73 offset:3072
	ds_read_b128 v[122:125], v73 offset:4096
	ds_read_b128 v[126:129], v73 offset:5120
	ds_read_b128 v[130:133], v73 offset:6144
	ds_read_b128 v[134:137], v73 offset:7168
	s_waitcnt lgkmcnt(0)
	s_barrier
	s_setprio 1
	s_waitcnt lgkmcnt(7)
	s_waitcnt lgkmcnt(0)
	v_mfma_f32_16x16x32_bf16 v[62:65], v[74:77], v[106:109], v[62:65]
	v_mfma_f32_16x16x32_bf16 v[58:61], v[82:85], v[106:109], v[58:61]
	v_mfma_f32_16x16x32_bf16 v[38:41], v[82:85], v[114:117], v[38:41]
	v_mfma_f32_16x16x32_bf16 v[54:57], v[74:77], v[114:117], v[54:57]
	v_mfma_f32_16x16x32_bf16 v[30:33], v[74:77], v[122:125], v[30:33]
	v_mfma_f32_16x16x32_bf16 v[22:25], v[82:85], v[122:125], v[22:25]
	v_mfma_f32_16x16x32_bf16 v[6:9], v[82:85], v[130:133], v[6:9]
	v_mfma_f32_16x16x32_bf16 v[14:17], v[74:77], v[130:133], v[14:17]
	v_mfma_f32_16x16x32_bf16 v[62:65], v[78:81], v[110:113], v[62:65]
	v_mfma_f32_16x16x32_bf16 v[58:61], v[86:89], v[110:113], v[58:61]
	v_mfma_f32_16x16x32_bf16 v[38:41], v[86:89], v[118:121], v[38:41]
	v_mfma_f32_16x16x32_bf16 v[54:57], v[78:81], v[118:121], v[54:57]
	v_mfma_f32_16x16x32_bf16 v[30:33], v[78:81], v[126:129], v[30:33]
	v_mfma_f32_16x16x32_bf16 v[22:25], v[86:89], v[126:129], v[22:25]
	v_mfma_f32_16x16x32_bf16 v[6:9], v[86:89], v[134:137], v[6:9]
	v_mfma_f32_16x16x32_bf16 v[14:17], v[78:81], v[134:137], v[14:17]
	s_setprio 0
	s_setprio 1
	v_mfma_f32_16x16x32_bf16 v[50:53], v[90:93], v[106:109], v[50:53]
	v_mfma_f32_16x16x32_bf16 v[46:49], v[98:101], v[106:109], v[46:49]
	v_mfma_f32_16x16x32_bf16 v[34:37], v[98:101], v[114:117], v[34:37]
	v_mfma_f32_16x16x32_bf16 v[42:45], v[90:93], v[114:117], v[42:45]
	v_mfma_f32_16x16x32_bf16 v[26:29], v[90:93], v[122:125], v[26:29]
	v_mfma_f32_16x16x32_bf16 v[18:21], v[98:101], v[122:125], v[18:21]
	v_mfma_f32_16x16x32_bf16 v[2:5], v[98:101], v[130:133], v[2:5]
	v_mfma_f32_16x16x32_bf16 v[10:13], v[90:93], v[130:133], v[10:13]
	v_mfma_f32_16x16x32_bf16 v[50:53], v[94:97], v[110:113], v[50:53]
	v_mfma_f32_16x16x32_bf16 v[46:49], v[102:105], v[110:113], v[46:49]
	v_mfma_f32_16x16x32_bf16 v[34:37], v[102:105], v[118:121], v[34:37]
	v_mfma_f32_16x16x32_bf16 v[42:45], v[94:97], v[118:121], v[42:45]
	v_mfma_f32_16x16x32_bf16 v[26:29], v[94:97], v[126:129], v[26:29]
	v_mfma_f32_16x16x32_bf16 v[18:21], v[102:105], v[126:129], v[18:21]
	v_mfma_f32_16x16x32_bf16 v[2:5], v[102:105], v[134:137], v[2:5]
	v_mfma_f32_16x16x32_bf16 v[10:13], v[94:97], v[134:137], v[10:13]
	s_setprio 0
	s_barrier
	s_mov_b32 m0, s13
	s_mov_b32 s42, s78
	s_mov_b32 s43, s79
	buffer_load_dwordx4 v67, s[40:43], s28 offen lds
	s_mov_b32 m0, s14
	s_add_i32 s31, s28, 0x80000
	buffer_load_dwordx4 v69, s[40:43], s28 offen lds
	s_mov_b32 m0, s15
	s_nop 0
	buffer_load_dwordx4 v67, s[40:43], s31 offen lds
	s_mov_b32 m0, s16
	s_nop 0
	buffer_load_dwordx4 v69, s[40:43], s31 offen lds
	s_mov_b32 m0, s12
	s_nop 0
	buffer_load_dwordx4 v66, s[76:79], s29 offen lds
	s_mov_b32 m0, s18
	s_nop 0
	buffer_load_dwordx4 v68, s[76:79], s29 offen lds
	s_waitcnt vmcnt(6)
	s_barrier
	s_barrier
; #define PG8_STAGEX(rs, bufoff, soff, voff) do { _Pragma("unroll") for (int _i = 0; _i < 2; ++_i) \
;         __builtin_amdgcn_raw_ptr_buffer_load_lds(rs, (LAS unsigned*)(lds + (bufoff) + ldsw + _i * 8192), 16, (voff)[_i], (soff), 0, 0); } while (0)
; #define PG8_LDA(dst, b, h) do { _Pragma("unroll") for (int m = 0; m < 4; ++m) _Pragma("unroll") for (int k = 0; k < 2; ++k) dst[m][k] = *(const LAS bf16x8*)(lds + PG8_SA(b, h) + aoff + m * 2048 + k * 1024); } while (0)
; #define PG8_LDB(dst, b, h) do { _Pragma("unroll") for (int n = 0; n < 2; ++n) _Pragma("unroll") for (int k = 0; k < 2; ++k) dst[n][k] = *(const LAS bf16x8*)(lds + PG8_SB(b, h) + boff + n * 2048 + k * 1024); } while (0)
; #define PG8_WAIT_V(n) asm volatile("s_waitcnt vmcnt(" #n ")" ::: "memory")
; #define PG8_WAIT_L(n) asm volatile("s_waitcnt lgkmcnt(" #n ")" ::: "memory")
; #define PG8_BAR __builtin_amdgcn_s_barrier()
; #define PG8_SCHED __builtin_amdgcn_sched_barrier(0)
;     ...
;                 if (w0) { PG8_LDB(B0, 1, 0); PG8_LDB(B1, 1, 1); PG8_SCHED; PG8_LDA(At, 1, 0); }
;                 PG8_WAIT_L(0); PG8_BAR; if (w0) { PG8_MMA(0, 0, At, B0); PG8_MMA(0, 1, At, B1); } PG8_BAR; PG8_SCHED;
;                 PG8_STAGEX(rsB, PG8_SB(1, 0), b3, voffB); PG8_STAGEX(rsB, PG8_SB(1, 1), b3 + hstepB, voffB); PG8_STAGEX(rsA, PG8_SA(1, 0), a3, voffA);
;                 PG8_WAIT_V(6); PG8_BAR; PG8_BAR; PG8_SCHED;
;             }
	v_add_u32_e32 v86, 0x18000, v72
	v_add_u32_e32 v102, 0x1c000, v72
	ds_read_b128 v[74:77], v86
	ds_read_b128 v[78:81], v86 offset:1024
	ds_read_b128 v[82:85], v86 offset:2048
	ds_read_b128 v[86:89], v86 offset:3072
	ds_read_b128 v[90:93], v102
	ds_read_b128 v[94:97], v102 offset:1024
	ds_read_b128 v[98:101], v102 offset:2048
	ds_read_b128 v[102:105], v102 offset:3072
	ds_read_b128 v[106:109], v73 offset:32768
	ds_read_b128 v[110:113], v73 offset:33792
	ds_read_b128 v[114:117], v73 offset:34816
	ds_read_b128 v[118:121], v73 offset:35840
	ds_read_b128 v[122:125], v73 offset:36864
	ds_read_b128 v[126:129], v73 offset:37888
	ds_read_b128 v[130:133], v73 offset:38912
	ds_read_b128 v[134:137], v73 offset:39936
	s_waitcnt lgkmcnt(0)
	s_barrier
	s_setprio 1
	s_waitcnt lgkmcnt(7)
	s_waitcnt lgkmcnt(0)
	v_mfma_f32_16x16x32_bf16 v[62:65], v[74:77], v[106:109], v[62:65]
	v_mfma_f32_16x16x32_bf16 v[58:61], v[82:85], v[106:109], v[58:61]
	v_mfma_f32_16x16x32_bf16 v[38:41], v[82:85], v[114:117], v[38:41]
	v_mfma_f32_16x16x32_bf16 v[54:57], v[74:77], v[114:117], v[54:57]
	v_mfma_f32_16x16x32_bf16 v[30:33], v[74:77], v[122:125], v[30:33]
	v_mfma_f32_16x16x32_bf16 v[22:25], v[82:85], v[122:125], v[22:25]
	v_mfma_f32_16x16x32_bf16 v[6:9], v[82:85], v[130:133], v[6:9]
	v_mfma_f32_16x16x32_bf16 v[14:17], v[74:77], v[130:133], v[14:17]
	v_mfma_f32_16x16x32_bf16 v[62:65], v[78:81], v[110:113], v[62:65]
	v_mfma_f32_16x16x32_bf16 v[58:61], v[86:89], v[110:113], v[58:61]
	v_mfma_f32_16x16x32_bf16 v[38:41], v[86:89], v[118:121], v[38:41]
	v_mfma_f32_16x16x32_bf16 v[54:57], v[78:81], v[118:121], v[54:57]
	v_mfma_f32_16x16x32_bf16 v[30:33], v[78:81], v[126:129], v[30:33]
	v_mfma_f32_16x16x32_bf16 v[22:25], v[86:89], v[126:129], v[22:25]
	v_mfma_f32_16x16x32_bf16 v[6:9], v[86:89], v[134:137], v[6:9]
	v_mfma_f32_16x16x32_bf16 v[14:17], v[78:81], v[134:137], v[14:17]
	s_setprio 0
	s_setprio 1
	v_mfma_f32_16x16x32_bf16 v[50:53], v[90:93], v[106:109], v[50:53]
	s_or_b32 s29, s28, 0x80
	v_mfma_f32_16x16x32_bf16 v[46:49], v[98:101], v[106:109], v[46:49]
	v_mfma_f32_16x16x32_bf16 v[42:45], v[90:93], v[114:117], v[42:45]
	v_mfma_f32_16x16x32_bf16 v[34:37], v[98:101], v[114:117], v[34:37]
	v_mfma_f32_16x16x32_bf16 v[26:29], v[90:93], v[122:125], v[26:29]
	v_mfma_f32_16x16x32_bf16 v[18:21], v[98:101], v[122:125], v[18:21]
	v_mfma_f32_16x16x32_bf16 v[10:13], v[90:93], v[130:133], v[10:13]
	v_mfma_f32_16x16x32_bf16 v[2:5], v[98:101], v[130:133], v[2:5]
	v_mfma_f32_16x16x32_bf16 v[50:53], v[94:97], v[110:113], v[50:53]
	v_mfma_f32_16x16x32_bf16 v[46:49], v[102:105], v[110:113], v[46:49]
	v_mfma_f32_16x16x32_bf16 v[42:45], v[94:97], v[118:121], v[42:45]
	v_mfma_f32_16x16x32_bf16 v[34:37], v[102:105], v[118:121], v[34:37]
	v_mfma_f32_16x16x32_bf16 v[26:29], v[94:97], v[126:129], v[26:29]
	v_mfma_f32_16x16x32_bf16 v[18:21], v[102:105], v[126:129], v[18:21]
	v_mfma_f32_16x16x32_bf16 v[10:13], v[94:97], v[134:137], v[10:13]
	v_mfma_f32_16x16x32_bf16 v[2:5], v[102:105], v[134:137], v[2:5]
	s_setprio 0
	s_barrier
	s_mov_b32 m0, s20
	s_add_i32 s28, s28, 0x80080
	buffer_load_dwordx4 v67, s[40:43], s29 offen lds
	s_mov_b32 m0, s21
	s_nop 0
	buffer_load_dwordx4 v69, s[40:43], s29 offen lds
	s_mov_b32 m0, s24
	s_nop 0
	buffer_load_dwordx4 v67, s[40:43], s28 offen lds
	s_mov_b32 m0, s25
	s_nop 0
	buffer_load_dwordx4 v69, s[40:43], s28 offen lds
	s_mov_b32 m0, s22
	s_nop 0
	buffer_load_dwordx4 v66, s[76:79], s30 offen lds
	s_mov_b32 m0, s23
	s_nop 0
	buffer_load_dwordx4 v68, s[76:79], s30 offen lds
	s_waitcnt vmcnt(6)
	s_barrier
	s_barrier
	s_addk_i32 s26, 0x100
	s_add_i32 s27, s27, 2
	s_cmp_gt_u32 s27, 29
	s_cbranch_scc0 .LBB0_1668
	s_cmpk_lt_u32 s11, 0x100
	s_cbranch_scc0 .LBB0_1671
	s_barrier

; #define PG8_STAGEX(rs, bufoff, soff, voff) do { _Pragma("unroll") for (int _i = 0; _i < 2; ++_i) \
;         __builtin_amdgcn_raw_ptr_buffer_load_lds(rs, (LAS unsigned*)(lds + (bufoff) + ldsw + _i * 8192), 16, (voff)[_i], (soff), 0, 0); } while (0)
; #define PG8_LDA(dst, b, h) do { _Pragma("unroll") for (int m = 0; m < 4; ++m) _Pragma("unroll") for (int k = 0; k < 2; ++k) dst[m][k] = *(const LAS bf16x8*)(lds + PG8_SA(b, h) + aoff + m * 2048 + k * 1024); } while (0)
; #define PG8_LDB(dst, b, h) do { _Pragma("unroll") for (int n = 0; n < 2; ++n) _Pragma("unroll") for (int k = 0; k < 2; ++k) dst[n][k] = *(const LAS bf16x8*)(lds + PG8_SB(b, h) + boff + n * 2048 + k * 1024); } while (0)
; #define PG8_WAIT_V(n) asm volatile("s_waitcnt vmcnt(" #n ")" ::: "memory")
; #define PG8_WAIT_L(n) asm volatile("s_waitcnt lgkmcnt(" #n ")" ::: "memory")
; #define PG8_BAR __builtin_amdgcn_s_barrier()
; #define PG8_SCHED __builtin_amdgcn_sched_barrier(0)
;     ...
;             PG8_LDB(B0, 0, 0); PG8_LDB(B1, 0, 1); PG8_SCHED; PG8_LDA(At, 0, 0); PG8_STAGEX(rsA, PG8_SA(1, 1), a1 + hstepA, voffA);
;             PG8_WAIT_V(8); PG8_WAIT_L(0); PG8_BAR; PG8_MMA(0, 0, At, B0); PG8_MMA(0, 1, At, B1); PG8_BAR; PG8_SCHED;
;             PG8_LDA(At, 0, 1); PG8_STAGEX(rsB, PG8_SB(0, 0), b2, voffB); PG8_STAGEX(rsB, PG8_SB(0, 1), b2 + hstepB, voffB); PG8_STAGEX(rsA, PG8_SA(0, 0), a2, voffA);
;             PG8_WAIT_V(8); PG8_WAIT_L(0); PG8_BAR; PG8_MMA(1, 0, At, B0); PG8_MMA(1, 1, At, B1); PG8_BAR; PG8_SCHED;
.LBB0_1750:
	v_add_u32_e32 v70, 0x10000, v241
	ds_read_b128 v[134:137], v70
	ds_read_b128 v[138:141], v70 offset:1024
	ds_read_b128 v[142:145], v70 offset:2048
	ds_read_b128 v[146:149], v70 offset:3072
	v_add_u32_e32 v70, 0x14000, v241
	ds_read_b128 v[150:153], v70
	ds_read_b128 v[154:157], v70 offset:1024
	ds_read_b128 v[158:161], v70 offset:2048
	ds_read_b128 v[162:165], v70 offset:3072
	s_add_i32 s46, s40, 0xffea8080
	s_cmpk_eq_i32 s60, 0x52
	s_cselect_b32 s63, s30, s46
	s_cselect_b32 s62, s31, s41
	s_or_b32 s61, s63, 0x80
	s_mov_b32 m0, s72
	ds_read_b128 v[166:169], v242
	ds_read_b128 v[170:173], v242 offset:1024
	ds_read_b128 v[184:187], v242 offset:2048
	ds_read_b128 v[188:191], v242 offset:3072
	ds_read_b128 v[192:195], v242 offset:4096
	ds_read_b128 v[196:199], v242 offset:5120
	ds_read_b128 v[200:203], v242 offset:6144
	ds_read_b128 v[204:207], v242 offset:7168
	buffer_load_dwordx4 v178, s[76:79], s40 offen lds
	s_mov_b32 m0, s73
	s_nop 0
	buffer_load_dwordx4 v237, s[76:79], s40 offen lds
	s_waitcnt vmcnt(8)
	s_waitcnt lgkmcnt(0)
	s_barrier
	s_setprio 1
	s_waitcnt lgkmcnt(7)
	s_waitcnt lgkmcnt(0)
	v_mfma_f32_16x16x32_bf16 v[130:133], v[134:137], v[166:169], v[130:133]
	v_mfma_f32_16x16x32_bf16 v[126:129], v[142:145], v[166:169], v[126:129]
	v_mfma_f32_16x16x32_bf16 v[118:121], v[142:145], v[184:187], v[118:121]
	v_mfma_f32_16x16x32_bf16 v[122:125], v[134:137], v[184:187], v[122:125]
	v_mfma_f32_16x16x32_bf16 v[114:117], v[134:137], v[192:195], v[114:117]
	v_mfma_f32_16x16x32_bf16 v[110:113], v[142:145], v[192:195], v[110:113]
	v_mfma_f32_16x16x32_bf16 v[102:105], v[142:145], v[200:203], v[102:105]
	v_mfma_f32_16x16x32_bf16 v[106:109], v[134:137], v[200:203], v[106:109]
	v_mfma_f32_16x16x32_bf16 v[130:133], v[138:141], v[170:173], v[130:133]
	v_mfma_f32_16x16x32_bf16 v[126:129], v[146:149], v[170:173], v[126:129]
	v_mfma_f32_16x16x32_bf16 v[118:121], v[146:149], v[188:191], v[118:121]
	v_mfma_f32_16x16x32_bf16 v[122:125], v[138:141], v[188:191], v[122:125]
	v_mfma_f32_16x16x32_bf16 v[114:117], v[138:141], v[196:199], v[114:117]
	v_mfma_f32_16x16x32_bf16 v[110:113], v[146:149], v[196:199], v[110:113]
	v_mfma_f32_16x16x32_bf16 v[102:105], v[146:149], v[204:207], v[102:105]
	v_mfma_f32_16x16x32_bf16 v[106:109], v[138:141], v[204:207], v[106:109]
	s_setprio 0
	s_setprio 1
	v_mfma_f32_16x16x32_bf16 v[62:65], v[150:153], v[166:169], v[62:65]
	v_mfma_f32_16x16x32_bf16 v[58:61], v[158:161], v[166:169], v[58:61]
	v_mfma_f32_16x16x32_bf16 v[50:53], v[158:161], v[184:187], v[50:53]
	v_mfma_f32_16x16x32_bf16 v[54:57], v[150:153], v[184:187], v[54:57]
	v_mfma_f32_16x16x32_bf16 v[46:49], v[150:153], v[192:195], v[46:49]
	v_mfma_f32_16x16x32_bf16 v[42:45], v[158:161], v[192:195], v[42:45]
	v_mfma_f32_16x16x32_bf16 v[34:37], v[158:161], v[200:203], v[34:37]
	v_mfma_f32_16x16x32_bf16 v[38:41], v[150:153], v[200:203], v[38:41]
	v_mfma_f32_16x16x32_bf16 v[62:65], v[154:157], v[170:173], v[62:65]
	v_mfma_f32_16x16x32_bf16 v[58:61], v[162:165], v[170:173], v[58:61]
	v_mfma_f32_16x16x32_bf16 v[50:53], v[162:165], v[188:191], v[50:53]
	v_mfma_f32_16x16x32_bf16 v[54:57], v[154:157], v[188:191], v[54:57]
	v_mfma_f32_16x16x32_bf16 v[46:49], v[154:157], v[196:199], v[46:49]
	v_mfma_f32_16x16x32_bf16 v[42:45], v[162:165], v[196:199], v[42:45]
	v_mfma_f32_16x16x32_bf16 v[34:37], v[162:165], v[204:207], v[34:37]
	v_mfma_f32_16x16x32_bf16 v[38:41], v[154:157], v[204:207], v[38:41]
	s_setprio 0
	s_barrier
	s_mov_b32 m0, s17
	s_mov_b32 s46, s78
	s_mov_b32 s47, s79
	ds_read_b128 v[166:169], v242 offset:16384
	ds_read_b128 v[170:173], v242 offset:17408
	ds_read_b128 v[184:187], v242 offset:18432
	ds_read_b128 v[188:191], v242 offset:19456
	ds_read_b128 v[192:195], v242 offset:20480
	ds_read_b128 v[196:199], v242 offset:21504
	ds_read_b128 v[200:203], v242 offset:22528
	ds_read_b128 v[204:207], v242 offset:23552
	buffer_load_dwordx4 v179, s[44:47], s62 offen lds
	s_mov_b32 m0, s18
	s_add_i32 s64, s62, 0x158000
	buffer_load_dwordx4 v238, s[44:47], s62 offen lds
	s_mov_b32 m0, s19
	s_nop 0
	buffer_load_dwordx4 v179, s[44:47], s64 offen lds
	s_mov_b32 m0, s20
	s_nop 0
	buffer_load_dwordx4 v238, s[44:47], s64 offen lds
	s_mov_b32 m0, s16
	s_nop 0
	buffer_load_dwordx4 v178, s[76:79], s63 offen lds
	s_mov_b32 m0, s21
	s_nop 0
	buffer_load_dwordx4 v237, s[76:79], s63 offen lds
	s_waitcnt vmcnt(8)
	s_waitcnt lgkmcnt(0)
	s_barrier
	s_setprio 1
	s_waitcnt lgkmcnt(7)
	v_mfma_f32_16x16x32_bf16 v[98:101], v[134:137], v[166:169], v[98:101]
	v_mfma_f32_16x16x32_bf16 v[94:97], v[142:145], v[166:169], v[94:97]
	s_waitcnt lgkmcnt(5)
	v_mfma_f32_16x16x32_bf16 v[90:93], v[134:137], v[184:187], v[90:93]
	v_mfma_f32_16x16x32_bf16 v[86:89], v[142:145], v[184:187], v[86:89]
	s_waitcnt lgkmcnt(3)
	v_mfma_f32_16x16x32_bf16 v[82:85], v[134:137], v[192:195], v[82:85]
	v_mfma_f32_16x16x32_bf16 v[76:79], v[142:145], v[192:195], v[78:81]
	s_waitcnt lgkmcnt(1)
	v_mfma_f32_16x16x32_bf16 v[70:73], v[134:137], v[200:203], v[72:75]
	v_mfma_f32_16x16x32_bf16 v[66:69], v[142:145], v[200:203], v[66:69]
	v_mfma_f32_16x16x32_bf16 v[98:101], v[138:141], v[170:173], v[98:101]
	v_mfma_f32_16x16x32_bf16 v[94:97], v[146:149], v[170:173], v[94:97]
	v_mfma_f32_16x16x32_bf16 v[90:93], v[138:141], v[188:191], v[90:93]
	v_mfma_f32_16x16x32_bf16 v[86:89], v[146:149], v[188:191], v[86:89]
	v_mfma_f32_16x16x32_bf16 v[82:85], v[138:141], v[196:199], v[82:85]
	v_mfma_f32_16x16x32_bf16 v[76:79], v[146:149], v[196:199], v[76:79]
	s_waitcnt lgkmcnt(0)
	v_mfma_f32_16x16x32_bf16 v[70:73], v[138:141], v[204:207], v[70:73]
	v_mfma_f32_16x16x32_bf16 v[66:69], v[146:149], v[204:207], v[66:69]
	s_setprio 0
	s_setprio 1
	v_mfma_f32_16x16x32_bf16 v[30:33], v[150:153], v[166:169], v[30:33]
	v_mfma_f32_16x16x32_bf16 v[26:29], v[158:161], v[166:169], v[26:29]
	v_mfma_f32_16x16x32_bf16 v[18:21], v[158:161], v[184:187], v[18:21]
	v_mfma_f32_16x16x32_bf16 v[22:25], v[150:153], v[184:187], v[22:25]
	v_mfma_f32_16x16x32_bf16 v[14:17], v[150:153], v[192:195], v[14:17]
	v_mfma_f32_16x16x32_bf16 v[10:13], v[158:161], v[192:195], v[10:13]
	v_mfma_f32_16x16x32_bf16 v[2:5], v[158:161], v[200:203], v[2:5]
	v_mfma_f32_16x16x32_bf16 v[6:9], v[150:153], v[200:203], v[6:9]
	v_mfma_f32_16x16x32_bf16 v[30:33], v[154:157], v[170:173], v[30:33]
	v_mfma_f32_16x16x32_bf16 v[26:29], v[162:165], v[170:173], v[26:29]
	v_mfma_f32_16x16x32_bf16 v[18:21], v[162:165], v[188:191], v[18:21]
	v_mfma_f32_16x16x32_bf16 v[22:25], v[154:157], v[188:191], v[22:25]
	v_mfma_f32_16x16x32_bf16 v[14:17], v[154:157], v[196:199], v[14:17]
	v_mfma_f32_16x16x32_bf16 v[10:13], v[162:165], v[196:199], v[10:13]
	v_mfma_f32_16x16x32_bf16 v[2:5], v[162:165], v[204:207], v[2:5]
	v_mfma_f32_16x16x32_bf16 v[6:9], v[154:157], v[204:207], v[6:9]
	s_setprio 0
	s_barrier
; #define PG8_STAGEX(rs, bufoff, soff, voff) do { _Pragma("unroll") for (int _i = 0; _i < 2; ++_i) \
;         __builtin_amdgcn_raw_ptr_buffer_load_lds(rs, (LAS unsigned*)(lds + (bufoff) + ldsw + _i * 8192), 16, (voff)[_i], (soff), 0, 0); } while (0)
; #define PG8_LDA(dst, b, h) do { _Pragma("unroll") for (int m = 0; m < 4; ++m) _Pragma("unroll") for (int k = 0; k < 2; ++k) dst[m][k] = *(const LAS bf16x8*)(lds + PG8_SA(b, h) + aoff + m * 2048 + k * 1024); } while (0)
; #define PG8_LDB(dst, b, h) do { _Pragma("unroll") for (int n = 0; n < 2; ++n) _Pragma("unroll") for (int k = 0; k < 2; ++k) dst[n][k] = *(const LAS bf16x8*)(lds + PG8_SB(b, h) + boff + n * 2048 + k * 1024); } while (0)
; #define PG8_WAIT_V(n) asm volatile("s_waitcnt vmcnt(" #n ")" ::: "memory")
; #define PG8_WAIT_L(n) asm volatile("s_waitcnt lgkmcnt(" #n ")" ::: "memory")
; #define PG8_BAR __builtin_amdgcn_s_barrier()
; #define PG8_SCHED __builtin_amdgcn_sched_barrier(0)
;     ...
;             PG8_LDB(B0, 1, 0); PG8_LDB(B1, 1, 1); PG8_SCHED; PG8_LDA(At, 1, 0); PG8_STAGEX(rsA, PG8_SA(0, 1), a2 + hstepA, voffA);
;             PG8_WAIT_V(8); PG8_WAIT_L(0); PG8_BAR; PG8_MMA(0, 0, At, B0); PG8_MMA(0, 1, At, B1); PG8_BAR; PG8_SCHED;
;             PG8_LDA(At, 1, 1); PG8_STAGEX(rsB, PG8_SB(1, 0), b3, voffB); PG8_STAGEX(rsB, PG8_SB(1, 1), b3 + hstepB, voffB); PG8_STAGEX(rsA, PG8_SA(1, 0), a3, voffA);
;             PG8_WAIT_V(8); PG8_WAIT_L(0); PG8_BAR; PG8_MMA(1, 0, At, B0); PG8_MMA(1, 1, At, B1); PG8_BAR; PG8_SCHED;
;         }
	v_add_u32_e32 v74, 0x18000, v241
	ds_read_b128 v[134:137], v74
	ds_read_b128 v[138:141], v74 offset:1024
	ds_read_b128 v[142:145], v74 offset:2048
	ds_read_b128 v[146:149], v74 offset:3072
	v_add_u32_e32 v74, 0x1c000, v241
	ds_read_b128 v[150:153], v74
	ds_read_b128 v[154:157], v74 offset:1024
	ds_read_b128 v[158:161], v74 offset:2048
	ds_read_b128 v[162:165], v74 offset:3072
	s_add_i32 s63, s63, 0x158000
	s_mov_b32 m0, s22
	ds_read_b128 v[166:169], v242 offset:32768
	ds_read_b128 v[170:173], v242 offset:33792
	ds_read_b128 v[184:187], v242 offset:34816
	ds_read_b128 v[188:191], v242 offset:35840
	ds_read_b128 v[192:195], v242 offset:36864
	ds_read_b128 v[196:199], v242 offset:37888
	ds_read_b128 v[200:203], v242 offset:38912
	ds_read_b128 v[204:207], v242 offset:39936
	buffer_load_dwordx4 v178, s[76:79], s63 offen lds
	s_mov_b32 m0, s23
	s_nop 0
	buffer_load_dwordx4 v237, s[76:79], s63 offen lds
	s_waitcnt vmcnt(8)
	s_waitcnt lgkmcnt(0)
	s_barrier
	s_setprio 1
	s_waitcnt lgkmcnt(7)
	s_waitcnt lgkmcnt(0)
	v_mfma_f32_16x16x32_bf16 v[130:133], v[134:137], v[166:169], v[130:133]
	v_mfma_f32_16x16x32_bf16 v[126:129], v[142:145], v[166:169], v[126:129]
	v_mfma_f32_16x16x32_bf16 v[118:121], v[142:145], v[184:187], v[118:121]
	v_mfma_f32_16x16x32_bf16 v[122:125], v[134:137], v[184:187], v[122:125]
	v_mfma_f32_16x16x32_bf16 v[114:117], v[134:137], v[192:195], v[114:117]
	v_mfma_f32_16x16x32_bf16 v[110:113], v[142:145], v[192:195], v[110:113]
	v_mfma_f32_16x16x32_bf16 v[102:105], v[142:145], v[200:203], v[102:105]
	v_mfma_f32_16x16x32_bf16 v[106:109], v[134:137], v[200:203], v[106:109]
	v_mfma_f32_16x16x32_bf16 v[130:133], v[138:141], v[170:173], v[130:133]
	v_mfma_f32_16x16x32_bf16 v[126:129], v[146:149], v[170:173], v[126:129]
	v_mfma_f32_16x16x32_bf16 v[118:121], v[146:149], v[188:191], v[118:121]
	v_mfma_f32_16x16x32_bf16 v[122:125], v[138:141], v[188:191], v[122:125]
	v_mfma_f32_16x16x32_bf16 v[114:117], v[138:141], v[196:199], v[114:117]
	v_mfma_f32_16x16x32_bf16 v[110:113], v[146:149], v[196:199], v[110:113]
	v_mfma_f32_16x16x32_bf16 v[102:105], v[146:149], v[204:207], v[102:105]
	v_mfma_f32_16x16x32_bf16 v[106:109], v[138:141], v[204:207], v[106:109]
	s_setprio 0
	s_setprio 1
	v_mfma_f32_16x16x32_bf16 v[62:65], v[150:153], v[166:169], v[62:65]
	v_mfma_f32_16x16x32_bf16 v[58:61], v[158:161], v[166:169], v[58:61]
	v_mfma_f32_16x16x32_bf16 v[50:53], v[158:161], v[184:187], v[50:53]
	v_mfma_f32_16x16x32_bf16 v[54:57], v[150:153], v[184:187], v[54:57]
	v_mfma_f32_16x16x32_bf16 v[46:49], v[150:153], v[192:195], v[46:49]
	v_mfma_f32_16x16x32_bf16 v[42:45], v[158:161], v[192:195], v[42:45]
	v_mfma_f32_16x16x32_bf16 v[34:37], v[158:161], v[200:203], v[34:37]
	v_mfma_f32_16x16x32_bf16 v[38:41], v[150:153], v[200:203], v[38:41]
	v_mfma_f32_16x16x32_bf16 v[62:65], v[154:157], v[170:173], v[62:65]
	v_mfma_f32_16x16x32_bf16 v[58:61], v[162:165], v[170:173], v[58:61]
	v_mfma_f32_16x16x32_bf16 v[50:53], v[162:165], v[188:191], v[50:53]
	v_mfma_f32_16x16x32_bf16 v[54:57], v[154:157], v[188:191], v[54:57]
	v_mfma_f32_16x16x32_bf16 v[46:49], v[154:157], v[196:199], v[46:49]
	v_mfma_f32_16x16x32_bf16 v[42:45], v[162:165], v[196:199], v[42:45]
	v_mfma_f32_16x16x32_bf16 v[34:37], v[162:165], v[204:207], v[34:37]
	v_mfma_f32_16x16x32_bf16 v[38:41], v[154:157], v[204:207], v[38:41]
	s_setprio 0
	s_barrier
	s_mov_b32 m0, s54
	s_or_b32 s63, s62, 0x80
	ds_read_b128 v[166:169], v242 offset:49152
	ds_read_b128 v[170:173], v242 offset:50176
	ds_read_b128 v[184:187], v242 offset:51200
	ds_read_b128 v[188:191], v242 offset:52224
	ds_read_b128 v[192:195], v242 offset:53248
	ds_read_b128 v[196:199], v242 offset:54272
	ds_read_b128 v[200:203], v242 offset:55296
	ds_read_b128 v[204:207], v242 offset:56320
	buffer_load_dwordx4 v179, s[44:47], s63 offen lds
	s_mov_b32 m0, s55
	s_add_i32 s62, s62, 0x158080
	buffer_load_dwordx4 v238, s[44:47], s63 offen lds
	s_mov_b32 m0, s70
	s_nop 0
	buffer_load_dwordx4 v179, s[44:47], s62 offen lds
	s_mov_b32 m0, s71
	s_nop 0
	buffer_load_dwordx4 v238, s[44:47], s62 offen lds
	s_mov_b32 m0, s68
	s_nop 0
	buffer_load_dwordx4 v178, s[76:79], s61 offen lds
	s_mov_b32 m0, s69
	s_nop 0
	buffer_load_dwordx4 v237, s[76:79], s61 offen lds
	s_waitcnt vmcnt(8)
	s_waitcnt lgkmcnt(0)
	s_barrier
	s_setprio 1
	s_waitcnt lgkmcnt(7)
	v_mfma_f32_16x16x32_bf16 v[98:101], v[134:137], v[166:169], v[98:101]
	v_mfma_f32_16x16x32_bf16 v[94:97], v[142:145], v[166:169], v[94:97]
	s_waitcnt lgkmcnt(5)
	v_mfma_f32_16x16x32_bf16 v[90:93], v[134:137], v[184:187], v[90:93]
	v_mfma_f32_16x16x32_bf16 v[86:89], v[142:145], v[184:187], v[86:89]
	s_waitcnt lgkmcnt(3)
	v_mfma_f32_16x16x32_bf16 v[80:83], v[134:137], v[192:195], v[82:85]
	v_mfma_f32_16x16x32_bf16 v[74:77], v[142:145], v[192:195], v[76:79]
	s_waitcnt lgkmcnt(1)
	v_mfma_f32_16x16x32_bf16 v[70:73], v[134:137], v[200:203], v[70:73]
	v_mfma_f32_16x16x32_bf16 v[66:69], v[142:145], v[200:203], v[66:69]
	v_mfma_f32_16x16x32_bf16 v[98:101], v[138:141], v[170:173], v[98:101]
	v_mfma_f32_16x16x32_bf16 v[94:97], v[146:149], v[170:173], v[94:97]
	v_mfma_f32_16x16x32_bf16 v[90:93], v[138:141], v[188:191], v[90:93]
	v_mfma_f32_16x16x32_bf16 v[86:89], v[146:149], v[188:191], v[86:89]
	v_mfma_f32_16x16x32_bf16 v[82:85], v[138:141], v[196:199], v[80:83]
	v_mfma_f32_16x16x32_bf16 v[78:81], v[146:149], v[196:199], v[74:77]
	s_waitcnt lgkmcnt(0)
	v_mfma_f32_16x16x32_bf16 v[72:75], v[138:141], v[204:207], v[70:73]
	v_mfma_f32_16x16x32_bf16 v[66:69], v[146:149], v[204:207], v[66:69]
	s_setprio 0
	s_setprio 1
	v_mfma_f32_16x16x32_bf16 v[30:33], v[150:153], v[166:169], v[30:33]
	v_mfma_f32_16x16x32_bf16 v[26:29], v[158:161], v[166:169], v[26:29]
	v_mfma_f32_16x16x32_bf16 v[18:21], v[158:161], v[184:187], v[18:21]
	v_mfma_f32_16x16x32_bf16 v[22:25], v[150:153], v[184:187], v[22:25]
	v_mfma_f32_16x16x32_bf16 v[14:17], v[150:153], v[192:195], v[14:17]
	v_mfma_f32_16x16x32_bf16 v[10:13], v[158:161], v[192:195], v[10:13]
	v_mfma_f32_16x16x32_bf16 v[2:5], v[158:161], v[200:203], v[2:5]
	v_mfma_f32_16x16x32_bf16 v[6:9], v[150:153], v[200:203], v[6:9]
	v_mfma_f32_16x16x32_bf16 v[30:33], v[154:157], v[170:173], v[30:33]
	v_mfma_f32_16x16x32_bf16 v[26:29], v[162:165], v[170:173], v[26:29]
	v_mfma_f32_16x16x32_bf16 v[18:21], v[162:165], v[188:191], v[18:21]
	v_mfma_f32_16x16x32_bf16 v[22:25], v[154:157], v[188:191], v[22:25]
	v_mfma_f32_16x16x32_bf16 v[14:17], v[154:157], v[196:199], v[14:17]
	v_mfma_f32_16x16x32_bf16 v[10:13], v[162:165], v[196:199], v[10:13]
	v_mfma_f32_16x16x32_bf16 v[2:5], v[162:165], v[204:207], v[2:5]
	v_mfma_f32_16x16x32_bf16 v[6:9], v[154:157], v[204:207], v[6:9]
	s_setprio 0
	s_barrier
	s_add_i32 s60, s60, 2
	s_addk_i32 s40, 0x100
	s_addk_i32 s41, 0x100
	s_cmpk_gt_u32 s60, 0x53
	s_cbranch_scc0 .LBB0_1750
	s_and_b64 vcc, exec, s[50:51]
	s_cbranch_vccz .LBB0_1753
	s_barrier
